# DIFF attention: running-max subtraction folded into the QK MFMA C operand (16-register -max block), 34 VALU fewer per 64-key iteration; plus dead address code removed in FFN-in epilogue and redundant
# speedup vs baseline: 1.0346x; 1.0038x over previous
.LBB0_74:
	s_add_i32 s7, s6, 2
	s_add_u32 s8, s10, 0x80
	s_addc_u32 s9, s11, 0
	s_add_i32 s14, 0, 0x10000
	s_cmp_eq_u32 s94, s6
	s_cselect_b32 s13, s75, s9
	s_cselect_b32 s12, s74, s8
	s_cselect_b32 s9, s79, s5
	s_cselect_b32 s8, s78, s1
	s_add_i32 s6, 0, 0x14000
	v_add_u32_e32 v142, s14, v211
	v_add_u32_e32 v170, s6, v211
	ds_read_b128 v[130:133], v142
	ds_read_b128 v[134:137], v142 offset:1024
	ds_read_b128 v[138:141], v142 offset:2048
	ds_read_b128 v[142:145], v142 offset:3072
	ds_read_b128 v[158:161], v170
	ds_read_b128 v[162:165], v170 offset:1024
	ds_read_b128 v[166:169], v170 offset:2048
	ds_read_b128 v[170:173], v170 offset:3072
	v_lshl_add_u64 v[208:209], s[10:11], 0, v[154:155]
	s_add_i32 m0, s27, 0xc000
	ds_read_b128 v[174:177], v230
	ds_read_b128 v[178:181], v230 offset:1024
	ds_read_b128 v[182:185], v230 offset:2048
	ds_read_b128 v[186:189], v230 offset:3072
	ds_read_b128 v[190:193], v230 offset:4096
	ds_read_b128 v[194:197], v230 offset:5120
	ds_read_b128 v[198:201], v230 offset:6144
	ds_read_b128 v[204:207], v230 offset:7168
	global_load_lds_dwordx4 v[208:209], off
	v_lshl_add_u64 v[208:209], s[10:11], 0, v[156:157]
	s_add_i32 m0, s27, 0xe000
	s_nop 0
	global_load_lds_dwordx4 v[208:209], off
	s_waitcnt vmcnt(8)
	s_waitcnt lgkmcnt(0)
	s_barrier
	s_setprio 1
	v_mfma_f32_16x16x32_bf16 v[126:129], v[130:133], v[174:177], v[126:129]
	v_mfma_f32_16x16x32_bf16 v[122:125], v[138:141], v[174:177], v[122:125]
	v_mfma_f32_16x16x32_bf16 v[110:113], v[130:133], v[182:185], v[110:113]
	v_mfma_f32_16x16x32_bf16 v[106:109], v[138:141], v[182:185], v[106:109]
	v_mfma_f32_16x16x32_bf16 v[94:97], v[130:133], v[190:193], v[94:97]
	v_mfma_f32_16x16x32_bf16 v[90:93], v[138:141], v[190:193], v[90:93]
	v_mfma_f32_16x16x32_bf16 v[78:81], v[130:133], v[198:201], v[78:81]
	v_mfma_f32_16x16x32_bf16 v[74:77], v[138:141], v[198:201], v[74:77]
	v_mfma_f32_16x16x32_bf16 v[126:129], v[134:137], v[178:181], v[126:129]
	v_mfma_f32_16x16x32_bf16 v[122:125], v[142:145], v[178:181], v[122:125]
	v_mfma_f32_16x16x32_bf16 v[110:113], v[134:137], v[186:189], v[110:113]
	v_mfma_f32_16x16x32_bf16 v[106:109], v[142:145], v[186:189], v[106:109]
	v_mfma_f32_16x16x32_bf16 v[94:97], v[134:137], v[194:197], v[94:97]
	v_mfma_f32_16x16x32_bf16 v[90:93], v[142:145], v[194:197], v[90:93]
	v_mfma_f32_16x16x32_bf16 v[78:81], v[134:137], v[204:207], v[78:81]
	v_mfma_f32_16x16x32_bf16 v[74:77], v[142:145], v[204:207], v[74:77]
	v_mfma_f32_16x16x32_bf16 v[118:121], v[158:161], v[174:177], v[118:121]
	v_mfma_f32_16x16x32_bf16 v[114:117], v[166:169], v[174:177], v[114:117]
	v_mfma_f32_16x16x32_bf16 v[102:105], v[158:161], v[182:185], v[102:105]
	v_mfma_f32_16x16x32_bf16 v[98:101], v[166:169], v[182:185], v[98:101]
	v_mfma_f32_16x16x32_bf16 v[86:89], v[158:161], v[190:193], v[86:89]
	v_mfma_f32_16x16x32_bf16 v[82:85], v[166:169], v[190:193], v[82:85]
	v_mfma_f32_16x16x32_bf16 v[70:73], v[158:161], v[198:201], v[70:73]
	v_mfma_f32_16x16x32_bf16 v[66:69], v[166:169], v[198:201], v[66:69]
	v_mfma_f32_16x16x32_bf16 v[118:121], v[162:165], v[178:181], v[118:121]
	v_mfma_f32_16x16x32_bf16 v[114:117], v[170:173], v[178:181], v[114:117]
	v_mfma_f32_16x16x32_bf16 v[102:105], v[162:165], v[186:189], v[102:105]
	v_mfma_f32_16x16x32_bf16 v[98:101], v[170:173], v[186:189], v[98:101]
	v_mfma_f32_16x16x32_bf16 v[86:89], v[162:165], v[194:197], v[86:89]
	v_mfma_f32_16x16x32_bf16 v[82:85], v[170:173], v[194:197], v[82:85]
	v_mfma_f32_16x16x32_bf16 v[70:73], v[162:165], v[204:207], v[70:73]
	v_mfma_f32_16x16x32_bf16 v[66:69], v[170:173], v[204:207], v[66:69]
	s_setprio 0
	s_barrier
	s_add_i32 s14, s14, s26
	v_lshl_add_u64 v[208:209], s[8:9], 0, v[146:147]
	s_mov_b32 m0, s14
	ds_read_b128 v[174:177], v230 offset:16384
	ds_read_b128 v[178:181], v230 offset:17408
	ds_read_b128 v[182:185], v230 offset:18432
	ds_read_b128 v[186:189], v230 offset:19456
	ds_read_b128 v[190:193], v230 offset:20480
	ds_read_b128 v[194:197], v230 offset:21504
	ds_read_b128 v[198:201], v230 offset:22528
	ds_read_b128 v[204:207], v230 offset:23552
	global_load_lds_dwordx4 v[208:209], off
	s_add_i32 m0, s14, 0x2000
	v_lshl_add_u64 v[212:213], s[8:9], 0, v[150:151]
	s_add_u32 s8, s8, s60
	s_addc_u32 s9, s9, s61
	s_add_i32 s6, s6, s26
	global_load_lds_dwordx4 v[212:213], off
	v_lshl_add_u64 v[214:215], s[8:9], 0, v[146:147]
	s_mov_b32 m0, s6
	v_lshl_add_u64 v[216:217], s[8:9], 0, v[150:151]
	global_load_lds_dwordx4 v[214:215], off
	s_add_i32 m0, s6, 0x2000
	v_lshl_add_u64 v[218:219], s[12:13], 0, v[148:149]
	global_load_lds_dwordx4 v[216:217], off
	s_mov_b32 m0, s27
	v_lshl_add_u64 v[220:221], s[12:13], 0, v[152:153]
	global_load_lds_dwordx4 v[218:219], off
	s_mov_b32 m0, s38
	s_nop 0
	global_load_lds_dwordx4 v[220:221], off
	s_waitcnt vmcnt(8)
	s_waitcnt lgkmcnt(0)
	s_barrier
	s_setprio 1
	v_mfma_f32_16x16x32_bf16 v[62:65], v[130:133], v[174:177], v[62:65]
	v_mfma_f32_16x16x32_bf16 v[58:61], v[138:141], v[174:177], v[58:61]
	v_mfma_f32_16x16x32_bf16 v[46:49], v[130:133], v[182:185], v[46:49]
	v_mfma_f32_16x16x32_bf16 v[42:45], v[138:141], v[182:185], v[42:45]
	v_mfma_f32_16x16x32_bf16 v[30:33], v[130:133], v[190:193], v[30:33]
	v_mfma_f32_16x16x32_bf16 v[26:29], v[138:141], v[190:193], v[26:29]
	v_mfma_f32_16x16x32_bf16 v[14:17], v[130:133], v[198:201], v[14:17]
	v_mfma_f32_16x16x32_bf16 v[10:13], v[138:141], v[198:201], v[10:13]
	v_mfma_f32_16x16x32_bf16 v[62:65], v[134:137], v[178:181], v[62:65]
	v_mfma_f32_16x16x32_bf16 v[58:61], v[142:145], v[178:181], v[58:61]
	v_mfma_f32_16x16x32_bf16 v[46:49], v[134:137], v[186:189], v[46:49]
	v_mfma_f32_16x16x32_bf16 v[42:45], v[142:145], v[186:189], v[42:45]
	v_mfma_f32_16x16x32_bf16 v[30:33], v[134:137], v[194:197], v[30:33]
	v_mfma_f32_16x16x32_bf16 v[26:29], v[142:145], v[194:197], v[26:29]
	v_mfma_f32_16x16x32_bf16 v[14:17], v[134:137], v[204:207], v[14:17]
	v_mfma_f32_16x16x32_bf16 v[10:13], v[142:145], v[204:207], v[10:13]
	v_mfma_f32_16x16x32_bf16 v[54:57], v[158:161], v[174:177], v[54:57]
	v_mfma_f32_16x16x32_bf16 v[50:53], v[166:169], v[174:177], v[50:53]
	v_mfma_f32_16x16x32_bf16 v[38:41], v[158:161], v[182:185], v[38:41]
	v_mfma_f32_16x16x32_bf16 v[34:37], v[166:169], v[182:185], v[34:37]
	v_mfma_f32_16x16x32_bf16 v[22:25], v[158:161], v[190:193], v[22:25]
	v_mfma_f32_16x16x32_bf16 v[18:21], v[166:169], v[190:193], v[18:21]
	v_mfma_f32_16x16x32_bf16 v[6:9], v[158:161], v[198:201], v[6:9]
	v_mfma_f32_16x16x32_bf16 v[2:5], v[166:169], v[198:201], v[2:5]
	v_mfma_f32_16x16x32_bf16 v[54:57], v[162:165], v[178:181], v[54:57]
	v_mfma_f32_16x16x32_bf16 v[50:53], v[170:173], v[178:181], v[50:53]
	v_mfma_f32_16x16x32_bf16 v[38:41], v[162:165], v[186:189], v[38:41]
	v_mfma_f32_16x16x32_bf16 v[34:37], v[170:173], v[186:189], v[34:37]
	v_mfma_f32_16x16x32_bf16 v[22:25], v[162:165], v[194:197], v[22:25]
	v_mfma_f32_16x16x32_bf16 v[18:21], v[170:173], v[194:197], v[18:21]
	v_mfma_f32_16x16x32_bf16 v[6:9], v[162:165], v[204:207], v[6:9]
	v_mfma_f32_16x16x32_bf16 v[2:5], v[170:173], v[204:207], v[2:5]
	s_setprio 0
	s_barrier
	s_add_i32 s6, 0, 0x18000
	s_add_i32 s14, 0, 0x1c000
	v_add_u32_e32 v142, s6, v211
	v_add_u32_e32 v170, s14, v211
	ds_read_b128 v[130:133], v142
	ds_read_b128 v[134:137], v142 offset:1024
	ds_read_b128 v[138:141], v142 offset:2048
	ds_read_b128 v[142:145], v142 offset:3072
	ds_read_b128 v[158:161], v170
	ds_read_b128 v[162:165], v170 offset:1024
	ds_read_b128 v[166:169], v170 offset:2048
	ds_read_b128 v[170:173], v170 offset:3072
	s_add_u32 s8, s12, s60
	s_addc_u32 s9, s13, s61
	s_mov_b32 m0, s39
	v_lshl_add_u64 v[222:223], s[8:9], 0, v[148:149]
	ds_read_b128 v[174:177], v230 offset:32768
	ds_read_b128 v[178:181], v230 offset:33792
	ds_read_b128 v[182:185], v230 offset:34816
	ds_read_b128 v[186:189], v230 offset:35840
	ds_read_b128 v[190:193], v230 offset:36864
	ds_read_b128 v[194:197], v230 offset:37888
	ds_read_b128 v[198:201], v230 offset:38912
	ds_read_b128 v[204:207], v230 offset:39936
	global_load_lds_dwordx4 v[222:223], off
	v_lshl_add_u64 v[222:223], s[8:9], 0, v[152:153]
	s_mov_b32 m0, s87
	s_nop 0
	global_load_lds_dwordx4 v[222:223], off
	s_waitcnt vmcnt(8)
	s_waitcnt lgkmcnt(0)
	s_barrier
	s_setprio 1
	v_mfma_f32_16x16x32_bf16 v[126:129], v[130:133], v[174:177], v[126:129]
	v_mfma_f32_16x16x32_bf16 v[122:125], v[138:141], v[174:177], v[122:125]
	v_mfma_f32_16x16x32_bf16 v[110:113], v[130:133], v[182:185], v[110:113]
	v_mfma_f32_16x16x32_bf16 v[106:109], v[138:141], v[182:185], v[106:109]
	v_mfma_f32_16x16x32_bf16 v[94:97], v[130:133], v[190:193], v[94:97]
	v_mfma_f32_16x16x32_bf16 v[90:93], v[138:141], v[190:193], v[90:93]
	v_mfma_f32_16x16x32_bf16 v[78:81], v[130:133], v[198:201], v[78:81]
	v_mfma_f32_16x16x32_bf16 v[74:77], v[138:141], v[198:201], v[74:77]
	v_mfma_f32_16x16x32_bf16 v[126:129], v[134:137], v[178:181], v[126:129]
	v_mfma_f32_16x16x32_bf16 v[122:125], v[142:145], v[178:181], v[122:125]
	v_mfma_f32_16x16x32_bf16 v[110:113], v[134:137], v[186:189], v[110:113]
	v_mfma_f32_16x16x32_bf16 v[106:109], v[142:145], v[186:189], v[106:109]
	v_mfma_f32_16x16x32_bf16 v[94:97], v[134:137], v[194:197], v[94:97]
	v_mfma_f32_16x16x32_bf16 v[90:93], v[142:145], v[194:197], v[90:93]
	v_mfma_f32_16x16x32_bf16 v[78:81], v[134:137], v[204:207], v[78:81]
	v_mfma_f32_16x16x32_bf16 v[74:77], v[142:145], v[204:207], v[74:77]
	v_mfma_f32_16x16x32_bf16 v[118:121], v[158:161], v[174:177], v[118:121]
	v_mfma_f32_16x16x32_bf16 v[114:117], v[166:169], v[174:177], v[114:117]
	v_mfma_f32_16x16x32_bf16 v[102:105], v[158:161], v[182:185], v[102:105]
	v_mfma_f32_16x16x32_bf16 v[98:101], v[166:169], v[182:185], v[98:101]
	v_mfma_f32_16x16x32_bf16 v[86:89], v[158:161], v[190:193], v[86:89]
	v_mfma_f32_16x16x32_bf16 v[82:85], v[166:169], v[190:193], v[82:85]
	v_mfma_f32_16x16x32_bf16 v[70:73], v[158:161], v[198:201], v[70:73]
	v_mfma_f32_16x16x32_bf16 v[66:69], v[166:169], v[198:201], v[66:69]
	v_mfma_f32_16x16x32_bf16 v[118:121], v[162:165], v[178:181], v[118:121]
	v_mfma_f32_16x16x32_bf16 v[114:117], v[170:173], v[178:181], v[114:117]
	v_mfma_f32_16x16x32_bf16 v[102:105], v[162:165], v[186:189], v[102:105]
	v_mfma_f32_16x16x32_bf16 v[98:101], v[170:173], v[186:189], v[98:101]
	v_mfma_f32_16x16x32_bf16 v[86:89], v[162:165], v[194:197], v[86:89]
	v_mfma_f32_16x16x32_bf16 v[82:85], v[170:173], v[194:197], v[82:85]
	v_mfma_f32_16x16x32_bf16 v[70:73], v[162:165], v[204:207], v[70:73]
	v_mfma_f32_16x16x32_bf16 v[66:69], v[170:173], v[204:207], v[66:69]
	s_setprio 0
	s_barrier
	s_add_i32 s6, s6, s26
	v_lshl_add_u64 v[208:209], v[208:209], 0, s[28:29]
	s_mov_b32 m0, s6
	ds_read_b128 v[174:177], v230 offset:49152
	ds_read_b128 v[178:181], v230 offset:50176
	ds_read_b128 v[182:185], v230 offset:51200
	ds_read_b128 v[186:189], v230 offset:52224
	ds_read_b128 v[190:193], v230 offset:53248
	ds_read_b128 v[194:197], v230 offset:54272
	ds_read_b128 v[198:201], v230 offset:55296
	ds_read_b128 v[204:207], v230 offset:56320
	global_load_lds_dwordx4 v[208:209], off
	v_lshl_add_u64 v[208:209], v[212:213], 0, s[28:29]
	s_add_i32 m0, s6, 0x2000
	s_add_i32 s6, s14, s26
	global_load_lds_dwordx4 v[208:209], off
	v_lshl_add_u64 v[208:209], v[214:215], 0, s[28:29]
	s_mov_b32 m0, s6
	s_nop 0
	global_load_lds_dwordx4 v[208:209], off
	v_lshl_add_u64 v[208:209], v[216:217], 0, s[28:29]
	s_add_i32 m0, s6, 0x2000
	s_nop 0
	global_load_lds_dwordx4 v[208:209], off
	v_lshl_add_u64 v[208:209], v[218:219], 0, s[28:29]
	s_mov_b32 m0, s88
	s_nop 0
	global_load_lds_dwordx4 v[208:209], off
	v_lshl_add_u64 v[208:209], v[220:221], 0, s[28:29]
	s_mov_b32 m0, s89
	s_nop 0
	global_load_lds_dwordx4 v[208:209], off
	s_waitcnt vmcnt(8)
	s_waitcnt lgkmcnt(0)
	s_barrier
	s_setprio 1
	v_mfma_f32_16x16x32_bf16 v[62:65], v[130:133], v[174:177], v[62:65]
	v_mfma_f32_16x16x32_bf16 v[58:61], v[138:141], v[174:177], v[58:61]
	v_mfma_f32_16x16x32_bf16 v[46:49], v[130:133], v[182:185], v[46:49]
	v_mfma_f32_16x16x32_bf16 v[42:45], v[138:141], v[182:185], v[42:45]
	v_mfma_f32_16x16x32_bf16 v[30:33], v[130:133], v[190:193], v[30:33]
	v_mfma_f32_16x16x32_bf16 v[26:29], v[138:141], v[190:193], v[26:29]
	v_mfma_f32_16x16x32_bf16 v[14:17], v[130:133], v[198:201], v[14:17]
	v_mfma_f32_16x16x32_bf16 v[10:13], v[138:141], v[198:201], v[10:13]
	v_mfma_f32_16x16x32_bf16 v[62:65], v[134:137], v[178:181], v[62:65]
	v_mfma_f32_16x16x32_bf16 v[58:61], v[142:145], v[178:181], v[58:61]
	v_mfma_f32_16x16x32_bf16 v[46:49], v[134:137], v[186:189], v[46:49]
	v_mfma_f32_16x16x32_bf16 v[42:45], v[142:145], v[186:189], v[42:45]
	v_mfma_f32_16x16x32_bf16 v[30:33], v[134:137], v[194:197], v[30:33]
	v_mfma_f32_16x16x32_bf16 v[26:29], v[142:145], v[194:197], v[26:29]
	v_mfma_f32_16x16x32_bf16 v[14:17], v[134:137], v[204:207], v[14:17]
	v_mfma_f32_16x16x32_bf16 v[10:13], v[142:145], v[204:207], v[10:13]
	v_mfma_f32_16x16x32_bf16 v[54:57], v[158:161], v[174:177], v[54:57]
	v_mfma_f32_16x16x32_bf16 v[50:53], v[166:169], v[174:177], v[50:53]
	v_mfma_f32_16x16x32_bf16 v[38:41], v[158:161], v[182:185], v[38:41]
	v_mfma_f32_16x16x32_bf16 v[34:37], v[166:169], v[182:185], v[34:37]
	v_mfma_f32_16x16x32_bf16 v[22:25], v[158:161], v[190:193], v[22:25]
	v_mfma_f32_16x16x32_bf16 v[18:21], v[166:169], v[190:193], v[18:21]
	v_mfma_f32_16x16x32_bf16 v[6:9], v[158:161], v[198:201], v[6:9]
	v_mfma_f32_16x16x32_bf16 v[2:5], v[166:169], v[198:201], v[2:5]
	v_mfma_f32_16x16x32_bf16 v[54:57], v[162:165], v[178:181], v[54:57]
	v_mfma_f32_16x16x32_bf16 v[50:53], v[170:173], v[178:181], v[50:53]
	v_mfma_f32_16x16x32_bf16 v[38:41], v[162:165], v[186:189], v[38:41]
	v_mfma_f32_16x16x32_bf16 v[34:37], v[170:173], v[186:189], v[34:37]
	v_mfma_f32_16x16x32_bf16 v[22:25], v[162:165], v[194:197], v[22:25]
	v_mfma_f32_16x16x32_bf16 v[18:21], v[170:173], v[194:197], v[18:21]
	v_mfma_f32_16x16x32_bf16 v[6:9], v[162:165], v[204:207], v[6:9]
	v_mfma_f32_16x16x32_bf16 v[2:5], v[170:173], v[204:207], v[2:5]
	s_setprio 0
	s_barrier
	s_add_u32 s1, s1, 0x100
	s_addc_u32 s5, s5, 0
	s_add_u32 s10, s10, 0x100
	s_addc_u32 s11, s11, 0
	s_cmp_ge_i32 s7, s91
	s_mov_b32 s6, s7
	s_cbranch_scc0 .LBB0_74

.LBB0_237:
	s_add_i32 s7, s6, 2
	s_add_u32 s8, s0, 0x80
	s_addc_u32 s9, s1, 0
	s_add_i32 s12, 0, 0x10000
	s_cmp_eq_u32 s74, s6
	s_cselect_b32 s11, s65, s9
	s_cselect_b32 s10, s64, s8
	s_cselect_b32 s9, s67, s5
	s_cselect_b32 s8, s66, s4
	s_add_i32 s6, 0, 0x14000
	v_add_u32_e32 v154, s12, v183
	v_add_u32_e32 v170, s6, v183
	ds_read_b128 v[130:133], v154
	ds_read_b128 v[134:137], v154 offset:1024
	ds_read_b128 v[150:153], v154 offset:2048
	ds_read_b128 v[154:157], v154 offset:3072
	ds_read_b128 v[158:161], v170
	ds_read_b128 v[162:165], v170 offset:1024
	ds_read_b128 v[166:169], v170 offset:2048
	ds_read_b128 v[170:173], v170 offset:3072
	v_lshl_add_u64 v[210:211], s[0:1], 0, v[146:147]
	s_add_i32 m0, s39, 0xc000
	ds_read_b128 v[174:177], v184
	ds_read_b128 v[178:181], v184 offset:1024
	ds_read_b128 v[186:189], v184 offset:2048
	ds_read_b128 v[190:193], v184 offset:3072
	ds_read_b128 v[194:197], v184 offset:4096
	ds_read_b128 v[198:201], v184 offset:5120
	ds_read_b128 v[202:205], v184 offset:6144
	ds_read_b128 v[206:209], v184 offset:7168
	global_load_lds_dwordx4 v[210:211], off
	v_lshl_add_u64 v[210:211], s[0:1], 0, v[148:149]
	s_add_i32 m0, s39, 0xe000
	s_nop 0
	global_load_lds_dwordx4 v[210:211], off
	s_waitcnt vmcnt(8)
	s_waitcnt lgkmcnt(0)
	s_barrier
	s_setprio 1
	v_mfma_f32_16x16x32_bf16 v[126:129], v[130:133], v[174:177], v[126:129]
	v_mfma_f32_16x16x32_bf16 v[122:125], v[150:153], v[174:177], v[122:125]
	v_mfma_f32_16x16x32_bf16 v[110:113], v[130:133], v[186:189], v[110:113]
	v_mfma_f32_16x16x32_bf16 v[106:109], v[150:153], v[186:189], v[106:109]
	v_mfma_f32_16x16x32_bf16 v[94:97], v[130:133], v[194:197], v[94:97]
	v_mfma_f32_16x16x32_bf16 v[90:93], v[150:153], v[194:197], v[90:93]
	v_mfma_f32_16x16x32_bf16 v[78:81], v[130:133], v[202:205], v[78:81]
	v_mfma_f32_16x16x32_bf16 v[74:77], v[150:153], v[202:205], v[74:77]
	v_mfma_f32_16x16x32_bf16 v[126:129], v[134:137], v[178:181], v[126:129]
	v_mfma_f32_16x16x32_bf16 v[122:125], v[154:157], v[178:181], v[122:125]
	v_mfma_f32_16x16x32_bf16 v[110:113], v[134:137], v[190:193], v[110:113]
	v_mfma_f32_16x16x32_bf16 v[106:109], v[154:157], v[190:193], v[106:109]
	v_mfma_f32_16x16x32_bf16 v[94:97], v[134:137], v[198:201], v[94:97]
	v_mfma_f32_16x16x32_bf16 v[90:93], v[154:157], v[198:201], v[90:93]
	v_mfma_f32_16x16x32_bf16 v[78:81], v[134:137], v[206:209], v[78:81]
	v_mfma_f32_16x16x32_bf16 v[74:77], v[154:157], v[206:209], v[74:77]
	v_mfma_f32_16x16x32_bf16 v[118:121], v[158:161], v[174:177], v[118:121]
	v_mfma_f32_16x16x32_bf16 v[114:117], v[166:169], v[174:177], v[114:117]
	v_mfma_f32_16x16x32_bf16 v[102:105], v[158:161], v[186:189], v[102:105]
	v_mfma_f32_16x16x32_bf16 v[98:101], v[166:169], v[186:189], v[98:101]
	v_mfma_f32_16x16x32_bf16 v[86:89], v[158:161], v[194:197], v[86:89]
	v_mfma_f32_16x16x32_bf16 v[82:85], v[166:169], v[194:197], v[82:85]
	v_mfma_f32_16x16x32_bf16 v[70:73], v[158:161], v[202:205], v[70:73]
	v_mfma_f32_16x16x32_bf16 v[66:69], v[166:169], v[202:205], v[66:69]
	v_mfma_f32_16x16x32_bf16 v[118:121], v[162:165], v[178:181], v[118:121]
	v_mfma_f32_16x16x32_bf16 v[114:117], v[170:173], v[178:181], v[114:117]
	v_mfma_f32_16x16x32_bf16 v[102:105], v[162:165], v[190:193], v[102:105]
	v_mfma_f32_16x16x32_bf16 v[98:101], v[170:173], v[190:193], v[98:101]
	v_mfma_f32_16x16x32_bf16 v[86:89], v[162:165], v[198:201], v[86:89]
	v_mfma_f32_16x16x32_bf16 v[82:85], v[170:173], v[198:201], v[82:85]
	v_mfma_f32_16x16x32_bf16 v[70:73], v[162:165], v[206:209], v[70:73]
	v_mfma_f32_16x16x32_bf16 v[66:69], v[170:173], v[206:209], v[66:69]
	s_setprio 0
	s_barrier
	s_add_i32 s12, s12, s38
	v_lshl_add_u64 v[210:211], s[8:9], 0, v[144:145]
	s_mov_b32 m0, s12
	ds_read_b128 v[174:177], v184 offset:16384
	ds_read_b128 v[178:181], v184 offset:17408
	ds_read_b128 v[186:189], v184 offset:18432
	ds_read_b128 v[190:193], v184 offset:19456
	ds_read_b128 v[194:197], v184 offset:20480
	ds_read_b128 v[198:201], v184 offset:21504
	ds_read_b128 v[202:205], v184 offset:22528
	ds_read_b128 v[206:209], v184 offset:23552
	global_load_lds_dwordx4 v[210:211], off
	s_add_i32 m0, s12, 0x2000
	v_lshl_add_u64 v[212:213], s[8:9], 0, v[140:141]
	s_add_u32 s8, s8, s46
	s_addc_u32 s9, s9, s47
	s_add_i32 s6, s6, s38
	global_load_lds_dwordx4 v[212:213], off
	v_lshl_add_u64 v[214:215], s[8:9], 0, v[144:145]
	s_mov_b32 m0, s6
	v_lshl_add_u64 v[216:217], s[8:9], 0, v[140:141]
	global_load_lds_dwordx4 v[214:215], off
	s_add_i32 m0, s6, 0x2000
	v_lshl_add_u64 v[218:219], s[10:11], 0, v[142:143]
	global_load_lds_dwordx4 v[216:217], off
	s_mov_b32 m0, s39
	v_lshl_add_u64 v[220:221], s[10:11], 0, v[138:139]
	global_load_lds_dwordx4 v[218:219], off
	s_mov_b32 m0, s70
	s_nop 0
	global_load_lds_dwordx4 v[220:221], off
	s_waitcnt vmcnt(8)
	s_waitcnt lgkmcnt(0)
	s_barrier
	s_setprio 1
	v_mfma_f32_16x16x32_bf16 v[62:65], v[130:133], v[174:177], v[62:65]
	v_mfma_f32_16x16x32_bf16 v[58:61], v[150:153], v[174:177], v[58:61]
	v_mfma_f32_16x16x32_bf16 v[46:49], v[130:133], v[186:189], v[46:49]
	v_mfma_f32_16x16x32_bf16 v[42:45], v[150:153], v[186:189], v[42:45]
	v_mfma_f32_16x16x32_bf16 v[30:33], v[130:133], v[194:197], v[30:33]
	v_mfma_f32_16x16x32_bf16 v[26:29], v[150:153], v[194:197], v[26:29]
	v_mfma_f32_16x16x32_bf16 v[14:17], v[130:133], v[202:205], v[14:17]
	v_mfma_f32_16x16x32_bf16 v[10:13], v[150:153], v[202:205], v[10:13]
	v_mfma_f32_16x16x32_bf16 v[62:65], v[134:137], v[178:181], v[62:65]
	v_mfma_f32_16x16x32_bf16 v[58:61], v[154:157], v[178:181], v[58:61]
	v_mfma_f32_16x16x32_bf16 v[46:49], v[134:137], v[190:193], v[46:49]
	v_mfma_f32_16x16x32_bf16 v[42:45], v[154:157], v[190:193], v[42:45]
	v_mfma_f32_16x16x32_bf16 v[30:33], v[134:137], v[198:201], v[30:33]
	v_mfma_f32_16x16x32_bf16 v[26:29], v[154:157], v[198:201], v[26:29]
	v_mfma_f32_16x16x32_bf16 v[14:17], v[134:137], v[206:209], v[14:17]
	v_mfma_f32_16x16x32_bf16 v[10:13], v[154:157], v[206:209], v[10:13]
	v_mfma_f32_16x16x32_bf16 v[54:57], v[158:161], v[174:177], v[54:57]
	v_mfma_f32_16x16x32_bf16 v[50:53], v[166:169], v[174:177], v[50:53]
	v_mfma_f32_16x16x32_bf16 v[38:41], v[158:161], v[186:189], v[38:41]
	v_mfma_f32_16x16x32_bf16 v[34:37], v[166:169], v[186:189], v[34:37]
	v_mfma_f32_16x16x32_bf16 v[22:25], v[158:161], v[194:197], v[22:25]
	v_mfma_f32_16x16x32_bf16 v[18:21], v[166:169], v[194:197], v[18:21]
	v_mfma_f32_16x16x32_bf16 v[6:9], v[158:161], v[202:205], v[6:9]
	v_mfma_f32_16x16x32_bf16 v[2:5], v[166:169], v[202:205], v[2:5]
	v_mfma_f32_16x16x32_bf16 v[54:57], v[162:165], v[178:181], v[54:57]
	v_mfma_f32_16x16x32_bf16 v[50:53], v[170:173], v[178:181], v[50:53]
	v_mfma_f32_16x16x32_bf16 v[38:41], v[162:165], v[190:193], v[38:41]
	v_mfma_f32_16x16x32_bf16 v[34:37], v[170:173], v[190:193], v[34:37]
	v_mfma_f32_16x16x32_bf16 v[22:25], v[162:165], v[198:201], v[22:25]
	v_mfma_f32_16x16x32_bf16 v[18:21], v[170:173], v[198:201], v[18:21]
	v_mfma_f32_16x16x32_bf16 v[6:9], v[162:165], v[206:209], v[6:9]
	v_mfma_f32_16x16x32_bf16 v[2:5], v[170:173], v[206:209], v[2:5]
	s_setprio 0
	s_barrier
	s_add_i32 s6, 0, 0x18000
	s_add_i32 s12, 0, 0x1c000
	v_add_u32_e32 v154, s6, v183
	v_add_u32_e32 v170, s12, v183
	ds_read_b128 v[130:133], v154
	ds_read_b128 v[134:137], v154 offset:1024
	ds_read_b128 v[150:153], v154 offset:2048
	ds_read_b128 v[154:157], v154 offset:3072
	ds_read_b128 v[158:161], v170
	ds_read_b128 v[162:165], v170 offset:1024
	ds_read_b128 v[166:169], v170 offset:2048
	ds_read_b128 v[170:173], v170 offset:3072
	s_add_u32 s8, s10, s46
	s_addc_u32 s9, s11, s47
	s_mov_b32 m0, s71
	v_lshl_add_u64 v[222:223], s[8:9], 0, v[142:143]
	ds_read_b128 v[174:177], v184 offset:32768
	ds_read_b128 v[178:181], v184 offset:33792
	ds_read_b128 v[186:189], v184 offset:34816
	ds_read_b128 v[190:193], v184 offset:35840
	ds_read_b128 v[194:197], v184 offset:36864
	ds_read_b128 v[198:201], v184 offset:37888
	ds_read_b128 v[202:205], v184 offset:38912
	ds_read_b128 v[206:209], v184 offset:39936
	global_load_lds_dwordx4 v[222:223], off
	v_lshl_add_u64 v[222:223], s[8:9], 0, v[138:139]
	s_mov_b32 m0, s72
	s_nop 0
	global_load_lds_dwordx4 v[222:223], off
	s_waitcnt vmcnt(8)
	s_waitcnt lgkmcnt(0)
	s_barrier
	s_setprio 1
	v_mfma_f32_16x16x32_bf16 v[126:129], v[130:133], v[174:177], v[126:129]
	v_mfma_f32_16x16x32_bf16 v[122:125], v[150:153], v[174:177], v[122:125]
	v_mfma_f32_16x16x32_bf16 v[110:113], v[130:133], v[186:189], v[110:113]
	v_mfma_f32_16x16x32_bf16 v[106:109], v[150:153], v[186:189], v[106:109]
	v_mfma_f32_16x16x32_bf16 v[94:97], v[130:133], v[194:197], v[94:97]
	v_mfma_f32_16x16x32_bf16 v[90:93], v[150:153], v[194:197], v[90:93]
	v_mfma_f32_16x16x32_bf16 v[78:81], v[130:133], v[202:205], v[78:81]
	v_mfma_f32_16x16x32_bf16 v[74:77], v[150:153], v[202:205], v[74:77]
	v_mfma_f32_16x16x32_bf16 v[126:129], v[134:137], v[178:181], v[126:129]
	v_mfma_f32_16x16x32_bf16 v[122:125], v[154:157], v[178:181], v[122:125]
	v_mfma_f32_16x16x32_bf16 v[110:113], v[134:137], v[190:193], v[110:113]
	v_mfma_f32_16x16x32_bf16 v[106:109], v[154:157], v[190:193], v[106:109]
	v_mfma_f32_16x16x32_bf16 v[94:97], v[134:137], v[198:201], v[94:97]
	v_mfma_f32_16x16x32_bf16 v[90:93], v[154:157], v[198:201], v[90:93]
	v_mfma_f32_16x16x32_bf16 v[78:81], v[134:137], v[206:209], v[78:81]
	v_mfma_f32_16x16x32_bf16 v[74:77], v[154:157], v[206:209], v[74:77]
	v_mfma_f32_16x16x32_bf16 v[118:121], v[158:161], v[174:177], v[118:121]
	v_mfma_f32_16x16x32_bf16 v[114:117], v[166:169], v[174:177], v[114:117]
	v_mfma_f32_16x16x32_bf16 v[102:105], v[158:161], v[186:189], v[102:105]
	v_mfma_f32_16x16x32_bf16 v[98:101], v[166:169], v[186:189], v[98:101]
	v_mfma_f32_16x16x32_bf16 v[86:89], v[158:161], v[194:197], v[86:89]
	v_mfma_f32_16x16x32_bf16 v[82:85], v[166:169], v[194:197], v[82:85]
	v_mfma_f32_16x16x32_bf16 v[70:73], v[158:161], v[202:205], v[70:73]
	v_mfma_f32_16x16x32_bf16 v[66:69], v[166:169], v[202:205], v[66:69]
	v_mfma_f32_16x16x32_bf16 v[118:121], v[162:165], v[178:181], v[118:121]
	v_mfma_f32_16x16x32_bf16 v[114:117], v[170:173], v[178:181], v[114:117]
	v_mfma_f32_16x16x32_bf16 v[102:105], v[162:165], v[190:193], v[102:105]
	v_mfma_f32_16x16x32_bf16 v[98:101], v[170:173], v[190:193], v[98:101]
	v_mfma_f32_16x16x32_bf16 v[86:89], v[162:165], v[198:201], v[86:89]
	v_mfma_f32_16x16x32_bf16 v[82:85], v[170:173], v[198:201], v[82:85]
	v_mfma_f32_16x16x32_bf16 v[70:73], v[162:165], v[206:209], v[70:73]
	v_mfma_f32_16x16x32_bf16 v[66:69], v[170:173], v[206:209], v[66:69]
	s_setprio 0
	s_barrier
	s_add_i32 s6, s6, s38
	v_lshl_add_u64 v[210:211], v[210:211], 0, s[28:29]
	s_mov_b32 m0, s6
	ds_read_b128 v[174:177], v184 offset:49152
	ds_read_b128 v[178:181], v184 offset:50176
	ds_read_b128 v[186:189], v184 offset:51200
	ds_read_b128 v[190:193], v184 offset:52224
	ds_read_b128 v[194:197], v184 offset:53248
	ds_read_b128 v[198:201], v184 offset:54272
	ds_read_b128 v[202:205], v184 offset:55296
	ds_read_b128 v[206:209], v184 offset:56320
	global_load_lds_dwordx4 v[210:211], off
	v_lshl_add_u64 v[210:211], v[212:213], 0, s[28:29]
	s_add_i32 m0, s6, 0x2000
	s_add_i32 s6, s12, s38
	global_load_lds_dwordx4 v[210:211], off
	v_lshl_add_u64 v[210:211], v[214:215], 0, s[28:29]
	s_mov_b32 m0, s6
	s_nop 0
	global_load_lds_dwordx4 v[210:211], off
	v_lshl_add_u64 v[210:211], v[216:217], 0, s[28:29]
	s_add_i32 m0, s6, 0x2000
	s_nop 0
	global_load_lds_dwordx4 v[210:211], off
	v_lshl_add_u64 v[210:211], v[218:219], 0, s[28:29]
	s_mov_b32 m0, s24
	s_nop 0
	global_load_lds_dwordx4 v[210:211], off
	v_lshl_add_u64 v[210:211], v[220:221], 0, s[28:29]
	s_mov_b32 m0, s25
	s_nop 0
	global_load_lds_dwordx4 v[210:211], off
	s_waitcnt vmcnt(8)
	s_waitcnt lgkmcnt(0)
	s_barrier
	s_setprio 1
	v_mfma_f32_16x16x32_bf16 v[62:65], v[130:133], v[174:177], v[62:65]
	v_mfma_f32_16x16x32_bf16 v[58:61], v[150:153], v[174:177], v[58:61]
	v_mfma_f32_16x16x32_bf16 v[46:49], v[130:133], v[186:189], v[46:49]
	v_mfma_f32_16x16x32_bf16 v[42:45], v[150:153], v[186:189], v[42:45]
	v_mfma_f32_16x16x32_bf16 v[30:33], v[130:133], v[194:197], v[30:33]
	v_mfma_f32_16x16x32_bf16 v[26:29], v[150:153], v[194:197], v[26:29]
	v_mfma_f32_16x16x32_bf16 v[14:17], v[130:133], v[202:205], v[14:17]
	v_mfma_f32_16x16x32_bf16 v[10:13], v[150:153], v[202:205], v[10:13]
	v_mfma_f32_16x16x32_bf16 v[62:65], v[134:137], v[178:181], v[62:65]
	v_mfma_f32_16x16x32_bf16 v[58:61], v[154:157], v[178:181], v[58:61]
	v_mfma_f32_16x16x32_bf16 v[46:49], v[134:137], v[190:193], v[46:49]
	v_mfma_f32_16x16x32_bf16 v[42:45], v[154:157], v[190:193], v[42:45]
	v_mfma_f32_16x16x32_bf16 v[30:33], v[134:137], v[198:201], v[30:33]
	v_mfma_f32_16x16x32_bf16 v[26:29], v[154:157], v[198:201], v[26:29]
	v_mfma_f32_16x16x32_bf16 v[14:17], v[134:137], v[206:209], v[14:17]
	v_mfma_f32_16x16x32_bf16 v[10:13], v[154:157], v[206:209], v[10:13]
	v_mfma_f32_16x16x32_bf16 v[54:57], v[158:161], v[174:177], v[54:57]
	v_mfma_f32_16x16x32_bf16 v[50:53], v[166:169], v[174:177], v[50:53]
	v_mfma_f32_16x16x32_bf16 v[38:41], v[158:161], v[186:189], v[38:41]
	v_mfma_f32_16x16x32_bf16 v[34:37], v[166:169], v[186:189], v[34:37]
	v_mfma_f32_16x16x32_bf16 v[22:25], v[158:161], v[194:197], v[22:25]
	v_mfma_f32_16x16x32_bf16 v[18:21], v[166:169], v[194:197], v[18:21]
	v_mfma_f32_16x16x32_bf16 v[6:9], v[158:161], v[202:205], v[6:9]
	v_mfma_f32_16x16x32_bf16 v[2:5], v[166:169], v[202:205], v[2:5]
	v_mfma_f32_16x16x32_bf16 v[54:57], v[162:165], v[178:181], v[54:57]
	v_mfma_f32_16x16x32_bf16 v[50:53], v[170:173], v[178:181], v[50:53]
	v_mfma_f32_16x16x32_bf16 v[38:41], v[162:165], v[190:193], v[38:41]
	v_mfma_f32_16x16x32_bf16 v[34:37], v[170:173], v[190:193], v[34:37]
	v_mfma_f32_16x16x32_bf16 v[22:25], v[162:165], v[198:201], v[22:25]
	v_mfma_f32_16x16x32_bf16 v[18:21], v[170:173], v[198:201], v[18:21]
	v_mfma_f32_16x16x32_bf16 v[6:9], v[162:165], v[206:209], v[6:9]
	v_mfma_f32_16x16x32_bf16 v[2:5], v[170:173], v[206:209], v[2:5]
	s_setprio 0
	s_barrier
	s_add_u32 s4, s4, 0x100
	s_addc_u32 s5, s5, 0
	s_add_u32 s0, s0, 0x100
	s_addc_u32 s1, s1, 0
	s_cmp_ge_i32 s7, s26
	s_mov_b32 s6, s7
	s_cbranch_scc0 .LBB0_237

.LBB0_299:
	s_add_i32 s8, s7, 2
	s_add_u32 s9, s0, 0x80
	s_addc_u32 s10, s1, 0
	s_add_i32 s14, 0, 0x10000
	s_cmp_eq_u32 s69, s7
	s_cselect_b32 s11, s61, s10
	s_cselect_b32 s10, s60, s9
	s_cselect_b32 s13, s63, s6
	s_cselect_b32 s12, s62, s5
	s_add_i32 s7, 0, 0x14000
	v_add_u32_e32 v154, s14, v181
	v_add_u32_e32 v170, s7, v181
	ds_read_b128 v[142:145], v154
	ds_read_b128 v[146:149], v154 offset:1024
	ds_read_b128 v[150:153], v154 offset:2048
	ds_read_b128 v[154:157], v154 offset:3072
	ds_read_b128 v[158:161], v170
	ds_read_b128 v[162:165], v170 offset:1024
	ds_read_b128 v[166:169], v170 offset:2048
	ds_read_b128 v[170:173], v170 offset:3072
	v_lshl_add_u64 v[178:179], s[0:1], 0, v[138:139]
	s_add_i32 m0, s25, 0xc000
	ds_read_b128 v[174:177], v182
	ds_read_b128 v[184:187], v182 offset:1024
	ds_read_b128 v[188:191], v182 offset:2048
	ds_read_b128 v[192:195], v182 offset:3072
	ds_read_b128 v[196:199], v182 offset:4096
	ds_read_b128 v[200:203], v182 offset:5120
	ds_read_b128 v[204:207], v182 offset:6144
	ds_read_b128 v[212:215], v182 offset:7168
	global_load_lds_dwordx4 v[178:179], off
	v_lshl_add_u64 v[178:179], s[0:1], 0, v[140:141]
	s_add_i32 m0, s25, 0xe000
	s_nop 0
	global_load_lds_dwordx4 v[178:179], off
	s_waitcnt vmcnt(8)
	s_waitcnt lgkmcnt(0)
	s_barrier
	s_setprio 1
	v_mfma_f32_16x16x32_bf16 v[126:129], v[142:145], v[174:177], v[126:129]
	v_mfma_f32_16x16x32_bf16 v[122:125], v[150:153], v[174:177], v[122:125]
	v_mfma_f32_16x16x32_bf16 v[118:121], v[142:145], v[188:191], v[118:121]
	v_mfma_f32_16x16x32_bf16 v[114:117], v[150:153], v[188:191], v[114:117]
	v_mfma_f32_16x16x32_bf16 v[110:113], v[142:145], v[196:199], v[110:113]
	v_mfma_f32_16x16x32_bf16 v[106:109], v[150:153], v[196:199], v[106:109]
	v_mfma_f32_16x16x32_bf16 v[102:105], v[142:145], v[204:207], v[102:105]
	v_mfma_f32_16x16x32_bf16 v[98:101], v[150:153], v[204:207], v[98:101]
	v_mfma_f32_16x16x32_bf16 v[126:129], v[146:149], v[184:187], v[126:129]
	v_mfma_f32_16x16x32_bf16 v[122:125], v[154:157], v[184:187], v[122:125]
	v_mfma_f32_16x16x32_bf16 v[118:121], v[146:149], v[192:195], v[118:121]
	v_mfma_f32_16x16x32_bf16 v[114:117], v[154:157], v[192:195], v[114:117]
	v_mfma_f32_16x16x32_bf16 v[110:113], v[146:149], v[200:203], v[110:113]
	v_mfma_f32_16x16x32_bf16 v[106:109], v[154:157], v[200:203], v[106:109]
	v_mfma_f32_16x16x32_bf16 v[102:105], v[146:149], v[212:215], v[102:105]
	v_mfma_f32_16x16x32_bf16 v[98:101], v[154:157], v[212:215], v[98:101]
	v_mfma_f32_16x16x32_bf16 v[6:9], v[158:161], v[174:177], v[6:9]
	v_mfma_f32_16x16x32_bf16 v[2:5], v[166:169], v[174:177], v[2:5]
	v_mfma_f32_16x16x32_bf16 v[14:17], v[158:161], v[188:191], v[14:17]
	v_mfma_f32_16x16x32_bf16 v[10:13], v[166:169], v[188:191], v[10:13]
	v_mfma_f32_16x16x32_bf16 v[22:25], v[158:161], v[196:199], v[22:25]
	v_mfma_f32_16x16x32_bf16 v[18:21], v[166:169], v[196:199], v[18:21]
	v_mfma_f32_16x16x32_bf16 v[34:37], v[158:161], v[204:207], v[34:37]
	v_mfma_f32_16x16x32_bf16 v[26:29], v[166:169], v[204:207], v[26:29]
	v_mfma_f32_16x16x32_bf16 v[6:9], v[162:165], v[184:187], v[6:9]
	v_mfma_f32_16x16x32_bf16 v[2:5], v[170:173], v[184:187], v[2:5]
	v_mfma_f32_16x16x32_bf16 v[14:17], v[162:165], v[192:195], v[14:17]
	v_mfma_f32_16x16x32_bf16 v[10:13], v[170:173], v[192:195], v[10:13]
	v_mfma_f32_16x16x32_bf16 v[22:25], v[162:165], v[200:203], v[22:25]
	v_mfma_f32_16x16x32_bf16 v[18:21], v[170:173], v[200:203], v[18:21]
	v_mfma_f32_16x16x32_bf16 v[34:37], v[162:165], v[212:215], v[34:37]
	v_mfma_f32_16x16x32_bf16 v[26:29], v[170:173], v[212:215], v[26:29]
	s_setprio 0
	s_barrier
	s_add_i32 s9, s14, s24
	v_lshl_add_u64 v[178:179], s[12:13], 0, v[136:137]
	s_mov_b32 m0, s9
	ds_read_b128 v[174:177], v182 offset:16384
	ds_read_b128 v[184:187], v182 offset:17408
	ds_read_b128 v[188:191], v182 offset:18432
	ds_read_b128 v[192:195], v182 offset:19456
	ds_read_b128 v[196:199], v182 offset:20480
	ds_read_b128 v[200:203], v182 offset:21504
	ds_read_b128 v[204:207], v182 offset:22528
	ds_read_b128 v[212:215], v182 offset:23552
	global_load_lds_dwordx4 v[178:179], off
	s_add_i32 m0, s9, 0x2000
	v_lshl_add_u64 v[208:209], s[12:13], 0, v[132:133]
	s_add_u32 s12, s12, s48
	s_addc_u32 s13, s13, s49
	s_add_i32 s7, s7, s24
	global_load_lds_dwordx4 v[208:209], off
	v_lshl_add_u64 v[210:211], s[12:13], 0, v[136:137]
	s_mov_b32 m0, s7
	v_lshl_add_u64 v[216:217], s[12:13], 0, v[132:133]
	global_load_lds_dwordx4 v[210:211], off
	s_add_i32 m0, s7, 0x2000
	v_lshl_add_u64 v[218:219], s[10:11], 0, v[134:135]
	global_load_lds_dwordx4 v[216:217], off
	s_mov_b32 m0, s25
	v_lshl_add_u64 v[220:221], s[10:11], 0, v[130:131]
	global_load_lds_dwordx4 v[218:219], off
	s_mov_b32 m0, s26
	s_nop 0
	global_load_lds_dwordx4 v[220:221], off
	s_waitcnt vmcnt(8)
	s_waitcnt lgkmcnt(0)
	s_barrier
	s_setprio 1
	v_mfma_f32_16x16x32_bf16 v[94:97], v[142:145], v[174:177], v[94:97]
	v_mfma_f32_16x16x32_bf16 v[90:93], v[150:153], v[174:177], v[90:93]
	v_mfma_f32_16x16x32_bf16 v[86:89], v[142:145], v[188:191], v[86:89]
	v_mfma_f32_16x16x32_bf16 v[82:85], v[150:153], v[188:191], v[82:85]
	v_mfma_f32_16x16x32_bf16 v[78:81], v[142:145], v[196:199], v[78:81]
	v_mfma_f32_16x16x32_bf16 v[74:77], v[150:153], v[196:199], v[74:77]
	v_mfma_f32_16x16x32_bf16 v[70:73], v[142:145], v[204:207], v[70:73]
	v_mfma_f32_16x16x32_bf16 v[66:69], v[150:153], v[204:207], v[66:69]
	v_mfma_f32_16x16x32_bf16 v[94:97], v[146:149], v[184:187], v[94:97]
	v_mfma_f32_16x16x32_bf16 v[90:93], v[154:157], v[184:187], v[90:93]
	v_mfma_f32_16x16x32_bf16 v[86:89], v[146:149], v[192:195], v[86:89]
	v_mfma_f32_16x16x32_bf16 v[82:85], v[154:157], v[192:195], v[82:85]
	v_mfma_f32_16x16x32_bf16 v[78:81], v[146:149], v[200:203], v[78:81]
	v_mfma_f32_16x16x32_bf16 v[74:77], v[154:157], v[200:203], v[74:77]
	v_mfma_f32_16x16x32_bf16 v[70:73], v[146:149], v[212:215], v[70:73]
	v_mfma_f32_16x16x32_bf16 v[66:69], v[154:157], v[212:215], v[66:69]
	v_mfma_f32_16x16x32_bf16 v[38:41], v[158:161], v[174:177], v[38:41]
	v_mfma_f32_16x16x32_bf16 v[30:33], v[166:169], v[174:177], v[30:33]
	v_mfma_f32_16x16x32_bf16 v[46:49], v[158:161], v[188:191], v[46:49]
	v_mfma_f32_16x16x32_bf16 v[42:45], v[166:169], v[188:191], v[42:45]
	v_mfma_f32_16x16x32_bf16 v[58:61], v[158:161], v[196:199], v[58:61]
	v_mfma_f32_16x16x32_bf16 v[50:53], v[166:169], v[196:199], v[50:53]
	v_mfma_f32_16x16x32_bf16 v[62:65], v[158:161], v[204:207], v[62:65]
	v_mfma_f32_16x16x32_bf16 v[54:57], v[166:169], v[204:207], v[54:57]
	v_mfma_f32_16x16x32_bf16 v[38:41], v[162:165], v[184:187], v[38:41]
	v_mfma_f32_16x16x32_bf16 v[30:33], v[170:173], v[184:187], v[30:33]
	v_mfma_f32_16x16x32_bf16 v[46:49], v[162:165], v[192:195], v[46:49]
	v_mfma_f32_16x16x32_bf16 v[42:45], v[170:173], v[192:195], v[42:45]
	v_mfma_f32_16x16x32_bf16 v[58:61], v[162:165], v[200:203], v[58:61]
	v_mfma_f32_16x16x32_bf16 v[50:53], v[170:173], v[200:203], v[50:53]
	v_mfma_f32_16x16x32_bf16 v[62:65], v[162:165], v[212:215], v[62:65]
	v_mfma_f32_16x16x32_bf16 v[54:57], v[170:173], v[212:215], v[54:57]
	s_setprio 0
	s_barrier
	s_add_i32 s7, 0, 0x18000
	s_add_i32 s9, 0, 0x1c000
	v_add_u32_e32 v154, s7, v181
	v_add_u32_e32 v170, s9, v181
	ds_read_b128 v[142:145], v154
	ds_read_b128 v[146:149], v154 offset:1024
	ds_read_b128 v[150:153], v154 offset:2048
	ds_read_b128 v[154:157], v154 offset:3072
	ds_read_b128 v[158:161], v170
	ds_read_b128 v[162:165], v170 offset:1024
	ds_read_b128 v[166:169], v170 offset:2048
	ds_read_b128 v[170:173], v170 offset:3072
	s_add_u32 s10, s10, s48
	s_addc_u32 s11, s11, s49
	s_mov_b32 m0, s27
	v_lshl_add_u64 v[222:223], s[10:11], 0, v[134:135]
	ds_read_b128 v[174:177], v182 offset:32768
	ds_read_b128 v[184:187], v182 offset:33792
	ds_read_b128 v[188:191], v182 offset:34816
	ds_read_b128 v[192:195], v182 offset:35840
	ds_read_b128 v[196:199], v182 offset:36864
	ds_read_b128 v[200:203], v182 offset:37888
	ds_read_b128 v[204:207], v182 offset:38912
	ds_read_b128 v[212:215], v182 offset:39936
	global_load_lds_dwordx4 v[222:223], off
	v_lshl_add_u64 v[222:223], s[10:11], 0, v[130:131]
	s_mov_b32 m0, s38
	s_nop 0
	global_load_lds_dwordx4 v[222:223], off
	s_waitcnt vmcnt(8)
	s_waitcnt lgkmcnt(0)
	s_barrier
	s_setprio 1
	v_mfma_f32_16x16x32_bf16 v[126:129], v[142:145], v[174:177], v[126:129]
	v_mfma_f32_16x16x32_bf16 v[122:125], v[150:153], v[174:177], v[122:125]
	v_mfma_f32_16x16x32_bf16 v[118:121], v[142:145], v[188:191], v[118:121]
	v_mfma_f32_16x16x32_bf16 v[114:117], v[150:153], v[188:191], v[114:117]
	v_mfma_f32_16x16x32_bf16 v[110:113], v[142:145], v[196:199], v[110:113]
	v_mfma_f32_16x16x32_bf16 v[106:109], v[150:153], v[196:199], v[106:109]
	v_mfma_f32_16x16x32_bf16 v[102:105], v[142:145], v[204:207], v[102:105]
	v_mfma_f32_16x16x32_bf16 v[98:101], v[150:153], v[204:207], v[98:101]
	v_mfma_f32_16x16x32_bf16 v[126:129], v[146:149], v[184:187], v[126:129]
	v_mfma_f32_16x16x32_bf16 v[122:125], v[154:157], v[184:187], v[122:125]
	v_mfma_f32_16x16x32_bf16 v[118:121], v[146:149], v[192:195], v[118:121]
	v_mfma_f32_16x16x32_bf16 v[114:117], v[154:157], v[192:195], v[114:117]
	v_mfma_f32_16x16x32_bf16 v[110:113], v[146:149], v[200:203], v[110:113]
	v_mfma_f32_16x16x32_bf16 v[106:109], v[154:157], v[200:203], v[106:109]
	v_mfma_f32_16x16x32_bf16 v[102:105], v[146:149], v[212:215], v[102:105]
	v_mfma_f32_16x16x32_bf16 v[98:101], v[154:157], v[212:215], v[98:101]
	v_mfma_f32_16x16x32_bf16 v[6:9], v[158:161], v[174:177], v[6:9]
	v_mfma_f32_16x16x32_bf16 v[2:5], v[166:169], v[174:177], v[2:5]
	v_mfma_f32_16x16x32_bf16 v[14:17], v[158:161], v[188:191], v[14:17]
	v_mfma_f32_16x16x32_bf16 v[10:13], v[166:169], v[188:191], v[10:13]
	v_mfma_f32_16x16x32_bf16 v[22:25], v[158:161], v[196:199], v[22:25]
	v_mfma_f32_16x16x32_bf16 v[18:21], v[166:169], v[196:199], v[18:21]
	v_mfma_f32_16x16x32_bf16 v[34:37], v[158:161], v[204:207], v[34:37]
	v_mfma_f32_16x16x32_bf16 v[26:29], v[166:169], v[204:207], v[26:29]
	v_mfma_f32_16x16x32_bf16 v[6:9], v[162:165], v[184:187], v[6:9]
	v_mfma_f32_16x16x32_bf16 v[2:5], v[170:173], v[184:187], v[2:5]
	v_mfma_f32_16x16x32_bf16 v[14:17], v[162:165], v[192:195], v[14:17]
	v_mfma_f32_16x16x32_bf16 v[10:13], v[170:173], v[192:195], v[10:13]
	v_mfma_f32_16x16x32_bf16 v[22:25], v[162:165], v[200:203], v[22:25]
	v_mfma_f32_16x16x32_bf16 v[18:21], v[170:173], v[200:203], v[18:21]
	v_mfma_f32_16x16x32_bf16 v[34:37], v[162:165], v[212:215], v[34:37]
	v_mfma_f32_16x16x32_bf16 v[26:29], v[170:173], v[212:215], v[26:29]
	s_setprio 0
	s_barrier
	s_add_i32 s7, s7, s24
	v_lshl_add_u64 v[178:179], v[178:179], 0, s[28:29]
	s_mov_b32 m0, s7
	ds_read_b128 v[174:177], v182 offset:49152
	ds_read_b128 v[184:187], v182 offset:50176
	ds_read_b128 v[188:191], v182 offset:51200
	ds_read_b128 v[192:195], v182 offset:52224
	ds_read_b128 v[196:199], v182 offset:53248
	ds_read_b128 v[200:203], v182 offset:54272
	ds_read_b128 v[204:207], v182 offset:55296
	ds_read_b128 v[212:215], v182 offset:56320
	global_load_lds_dwordx4 v[178:179], off
	v_lshl_add_u64 v[178:179], v[208:209], 0, s[28:29]
	s_add_i32 m0, s7, 0x2000
	s_add_i32 s7, s9, s24
	global_load_lds_dwordx4 v[178:179], off
	v_lshl_add_u64 v[178:179], v[210:211], 0, s[28:29]
	s_mov_b32 m0, s7
	s_nop 0
	global_load_lds_dwordx4 v[178:179], off
	v_lshl_add_u64 v[178:179], v[216:217], 0, s[28:29]
	s_add_i32 m0, s7, 0x2000
	s_nop 0
	global_load_lds_dwordx4 v[178:179], off
	v_lshl_add_u64 v[178:179], v[218:219], 0, s[28:29]
	s_mov_b32 m0, s39
	s_nop 0
	global_load_lds_dwordx4 v[178:179], off
	v_lshl_add_u64 v[178:179], v[220:221], 0, s[28:29]
	s_mov_b32 m0, s66
	s_nop 0
	global_load_lds_dwordx4 v[178:179], off
	s_waitcnt vmcnt(8)
	s_waitcnt lgkmcnt(0)
	s_barrier
	s_setprio 1
	v_mfma_f32_16x16x32_bf16 v[94:97], v[142:145], v[174:177], v[94:97]
	v_mfma_f32_16x16x32_bf16 v[90:93], v[150:153], v[174:177], v[90:93]
	v_mfma_f32_16x16x32_bf16 v[86:89], v[142:145], v[188:191], v[86:89]
	v_mfma_f32_16x16x32_bf16 v[82:85], v[150:153], v[188:191], v[82:85]
	v_mfma_f32_16x16x32_bf16 v[78:81], v[142:145], v[196:199], v[78:81]
	v_mfma_f32_16x16x32_bf16 v[74:77], v[150:153], v[196:199], v[74:77]
	v_mfma_f32_16x16x32_bf16 v[70:73], v[142:145], v[204:207], v[70:73]
	v_mfma_f32_16x16x32_bf16 v[66:69], v[150:153], v[204:207], v[66:69]
	v_mfma_f32_16x16x32_bf16 v[94:97], v[146:149], v[184:187], v[94:97]
	v_mfma_f32_16x16x32_bf16 v[90:93], v[154:157], v[184:187], v[90:93]
	v_mfma_f32_16x16x32_bf16 v[86:89], v[146:149], v[192:195], v[86:89]
	v_mfma_f32_16x16x32_bf16 v[82:85], v[154:157], v[192:195], v[82:85]
	v_mfma_f32_16x16x32_bf16 v[78:81], v[146:149], v[200:203], v[78:81]
	v_mfma_f32_16x16x32_bf16 v[74:77], v[154:157], v[200:203], v[74:77]
	v_mfma_f32_16x16x32_bf16 v[70:73], v[146:149], v[212:215], v[70:73]
	v_mfma_f32_16x16x32_bf16 v[66:69], v[154:157], v[212:215], v[66:69]
	v_mfma_f32_16x16x32_bf16 v[38:41], v[158:161], v[174:177], v[38:41]
	v_mfma_f32_16x16x32_bf16 v[30:33], v[166:169], v[174:177], v[30:33]
	v_mfma_f32_16x16x32_bf16 v[46:49], v[158:161], v[188:191], v[46:49]
	v_mfma_f32_16x16x32_bf16 v[42:45], v[166:169], v[188:191], v[42:45]
	v_mfma_f32_16x16x32_bf16 v[58:61], v[158:161], v[196:199], v[58:61]
	v_mfma_f32_16x16x32_bf16 v[50:53], v[166:169], v[196:199], v[50:53]
	v_mfma_f32_16x16x32_bf16 v[62:65], v[158:161], v[204:207], v[62:65]
	v_mfma_f32_16x16x32_bf16 v[54:57], v[166:169], v[204:207], v[54:57]
	v_mfma_f32_16x16x32_bf16 v[38:41], v[162:165], v[184:187], v[38:41]
	v_mfma_f32_16x16x32_bf16 v[30:33], v[170:173], v[184:187], v[30:33]
	v_mfma_f32_16x16x32_bf16 v[46:49], v[162:165], v[192:195], v[46:49]
	v_mfma_f32_16x16x32_bf16 v[42:45], v[170:173], v[192:195], v[42:45]
	v_mfma_f32_16x16x32_bf16 v[58:61], v[162:165], v[200:203], v[58:61]
	v_mfma_f32_16x16x32_bf16 v[50:53], v[170:173], v[200:203], v[50:53]
	v_mfma_f32_16x16x32_bf16 v[62:65], v[162:165], v[212:215], v[62:65]
	v_mfma_f32_16x16x32_bf16 v[54:57], v[170:173], v[212:215], v[54:57]
	s_setprio 0
	s_barrier
	s_add_u32 s5, s5, 0x100
	s_addc_u32 s6, s6, 0
	s_add_u32 s0, s0, 0x100
	s_addc_u32 s1, s1, 0
	s_cmp_ge_i32 s8, s67
	s_mov_b32 s7, s8
	s_cbranch_scc0 .LBB0_299

.LBB0_522:
	s_add_i32 s7, s6, 2
	s_add_u32 s8, s10, 0x80
	s_addc_u32 s9, s11, 0
	s_add_i32 s14, 0, 0x10000
	s_cmp_eq_u32 s75, s6
	s_cselect_b32 s13, s61, s9
	s_cselect_b32 s12, s60, s8
	s_cselect_b32 s9, s63, s5
	s_cselect_b32 s8, s62, s1
	s_add_i32 s6, 0, 0x14000
	v_add_u32_e32 v154, s14, v182
	v_add_u32_e32 v170, s6, v182
	ds_read_b128 v[142:145], v154
	ds_read_b128 v[146:149], v154 offset:1024
	ds_read_b128 v[150:153], v154 offset:2048
	ds_read_b128 v[154:157], v154 offset:3072
	ds_read_b128 v[158:161], v170
	ds_read_b128 v[162:165], v170 offset:1024
	ds_read_b128 v[166:169], v170 offset:2048
	ds_read_b128 v[172:175], v170 offset:3072
	v_lshl_add_u64 v[180:181], s[10:11], 0, v[138:139]
	s_add_i32 m0, s67, 0xc000
	ds_read_b128 v[176:179], v183
	ds_read_b128 v[184:187], v183 offset:1024
	ds_read_b128 v[188:191], v183 offset:2048
	ds_read_b128 v[192:195], v183 offset:3072
	ds_read_b128 v[196:199], v183 offset:4096
	ds_read_b128 v[200:203], v183 offset:5120
	ds_read_b128 v[204:207], v183 offset:6144
	ds_read_b128 v[212:215], v183 offset:7168
	global_load_lds_dwordx4 v[180:181], off
	v_lshl_add_u64 v[180:181], s[10:11], 0, v[140:141]
	s_add_i32 m0, s67, 0xe000
	s_nop 0
	global_load_lds_dwordx4 v[180:181], off
	s_waitcnt vmcnt(8)
	s_waitcnt lgkmcnt(0)
	s_barrier
	s_setprio 1
	v_mfma_f32_16x16x32_bf16 v[126:129], v[142:145], v[176:179], v[126:129]
	v_mfma_f32_16x16x32_bf16 v[122:125], v[150:153], v[176:179], v[122:125]
	v_mfma_f32_16x16x32_bf16 v[110:113], v[142:145], v[188:191], v[110:113]
	v_mfma_f32_16x16x32_bf16 v[106:109], v[150:153], v[188:191], v[106:109]
	v_mfma_f32_16x16x32_bf16 v[94:97], v[142:145], v[196:199], v[94:97]
	v_mfma_f32_16x16x32_bf16 v[90:93], v[150:153], v[196:199], v[90:93]
	v_mfma_f32_16x16x32_bf16 v[78:81], v[142:145], v[204:207], v[78:81]
	v_mfma_f32_16x16x32_bf16 v[74:77], v[150:153], v[204:207], v[74:77]
	v_mfma_f32_16x16x32_bf16 v[126:129], v[146:149], v[184:187], v[126:129]
	v_mfma_f32_16x16x32_bf16 v[122:125], v[154:157], v[184:187], v[122:125]
	v_mfma_f32_16x16x32_bf16 v[110:113], v[146:149], v[192:195], v[110:113]
	v_mfma_f32_16x16x32_bf16 v[106:109], v[154:157], v[192:195], v[106:109]
	v_mfma_f32_16x16x32_bf16 v[94:97], v[146:149], v[200:203], v[94:97]
	v_mfma_f32_16x16x32_bf16 v[90:93], v[154:157], v[200:203], v[90:93]
	v_mfma_f32_16x16x32_bf16 v[78:81], v[146:149], v[212:215], v[78:81]
	v_mfma_f32_16x16x32_bf16 v[74:77], v[154:157], v[212:215], v[74:77]
	v_mfma_f32_16x16x32_bf16 v[118:121], v[158:161], v[176:179], v[118:121]
	v_mfma_f32_16x16x32_bf16 v[114:117], v[166:169], v[176:179], v[114:117]
	v_mfma_f32_16x16x32_bf16 v[102:105], v[158:161], v[188:191], v[102:105]
	v_mfma_f32_16x16x32_bf16 v[98:101], v[166:169], v[188:191], v[98:101]
	v_mfma_f32_16x16x32_bf16 v[86:89], v[158:161], v[196:199], v[86:89]
	v_mfma_f32_16x16x32_bf16 v[82:85], v[166:169], v[196:199], v[82:85]
	v_mfma_f32_16x16x32_bf16 v[70:73], v[158:161], v[204:207], v[70:73]
	v_mfma_f32_16x16x32_bf16 v[66:69], v[166:169], v[204:207], v[66:69]
	v_mfma_f32_16x16x32_bf16 v[118:121], v[162:165], v[184:187], v[118:121]
	v_mfma_f32_16x16x32_bf16 v[114:117], v[172:175], v[184:187], v[114:117]
	v_mfma_f32_16x16x32_bf16 v[102:105], v[162:165], v[192:195], v[102:105]
	v_mfma_f32_16x16x32_bf16 v[98:101], v[172:175], v[192:195], v[98:101]
	v_mfma_f32_16x16x32_bf16 v[86:89], v[162:165], v[200:203], v[86:89]
	v_mfma_f32_16x16x32_bf16 v[82:85], v[172:175], v[200:203], v[82:85]
	v_mfma_f32_16x16x32_bf16 v[70:73], v[162:165], v[212:215], v[70:73]
	v_mfma_f32_16x16x32_bf16 v[66:69], v[172:175], v[212:215], v[66:69]
	s_setprio 0
	s_barrier
	s_add_i32 s14, s14, s66
	v_lshl_add_u64 v[180:181], s[8:9], 0, v[136:137]
	s_mov_b32 m0, s14
	ds_read_b128 v[176:179], v183 offset:16384
	ds_read_b128 v[184:187], v183 offset:17408
	ds_read_b128 v[188:191], v183 offset:18432
	ds_read_b128 v[192:195], v183 offset:19456
	ds_read_b128 v[196:199], v183 offset:20480
	ds_read_b128 v[200:203], v183 offset:21504
	ds_read_b128 v[204:207], v183 offset:22528
	ds_read_b128 v[212:215], v183 offset:23552
	global_load_lds_dwordx4 v[180:181], off
	s_add_i32 m0, s14, 0x2000
	v_lshl_add_u64 v[208:209], s[8:9], 0, v[132:133]
	s_add_u32 s8, s8, s50
	s_addc_u32 s9, s9, s51
	s_add_i32 s6, s6, s66
	global_load_lds_dwordx4 v[208:209], off
	v_lshl_add_u64 v[216:217], s[8:9], 0, v[136:137]
	s_mov_b32 m0, s6
	v_lshl_add_u64 v[218:219], s[8:9], 0, v[132:133]
	global_load_lds_dwordx4 v[216:217], off
	s_add_i32 m0, s6, 0x2000
	v_lshl_add_u64 v[220:221], s[12:13], 0, v[134:135]
	global_load_lds_dwordx4 v[218:219], off
	s_mov_b32 m0, s67
	v_lshl_add_u64 v[222:223], s[12:13], 0, v[130:131]
	global_load_lds_dwordx4 v[220:221], off
	s_mov_b32 m0, s68
	s_nop 0
	global_load_lds_dwordx4 v[222:223], off
	s_waitcnt vmcnt(8)
	s_waitcnt lgkmcnt(0)
	s_barrier
	s_setprio 1
	v_mfma_f32_16x16x32_bf16 v[62:65], v[142:145], v[176:179], v[62:65]
	v_mfma_f32_16x16x32_bf16 v[58:61], v[150:153], v[176:179], v[58:61]
	v_mfma_f32_16x16x32_bf16 v[46:49], v[142:145], v[188:191], v[46:49]
	v_mfma_f32_16x16x32_bf16 v[42:45], v[150:153], v[188:191], v[42:45]
	v_mfma_f32_16x16x32_bf16 v[30:33], v[142:145], v[196:199], v[30:33]
	v_mfma_f32_16x16x32_bf16 v[26:29], v[150:153], v[196:199], v[26:29]
	v_mfma_f32_16x16x32_bf16 v[14:17], v[142:145], v[204:207], v[14:17]
	v_mfma_f32_16x16x32_bf16 v[10:13], v[150:153], v[204:207], v[10:13]
	v_mfma_f32_16x16x32_bf16 v[62:65], v[146:149], v[184:187], v[62:65]
	v_mfma_f32_16x16x32_bf16 v[58:61], v[154:157], v[184:187], v[58:61]
	v_mfma_f32_16x16x32_bf16 v[46:49], v[146:149], v[192:195], v[46:49]
	v_mfma_f32_16x16x32_bf16 v[42:45], v[154:157], v[192:195], v[42:45]
	v_mfma_f32_16x16x32_bf16 v[30:33], v[146:149], v[200:203], v[30:33]
	v_mfma_f32_16x16x32_bf16 v[26:29], v[154:157], v[200:203], v[26:29]
	v_mfma_f32_16x16x32_bf16 v[14:17], v[146:149], v[212:215], v[14:17]
	v_mfma_f32_16x16x32_bf16 v[10:13], v[154:157], v[212:215], v[10:13]
	v_mfma_f32_16x16x32_bf16 v[54:57], v[158:161], v[176:179], v[54:57]
	v_mfma_f32_16x16x32_bf16 v[50:53], v[166:169], v[176:179], v[50:53]
	v_mfma_f32_16x16x32_bf16 v[38:41], v[158:161], v[188:191], v[38:41]
	v_mfma_f32_16x16x32_bf16 v[34:37], v[166:169], v[188:191], v[34:37]
	v_mfma_f32_16x16x32_bf16 v[22:25], v[158:161], v[196:199], v[22:25]
	v_mfma_f32_16x16x32_bf16 v[18:21], v[166:169], v[196:199], v[18:21]
	v_mfma_f32_16x16x32_bf16 v[6:9], v[158:161], v[204:207], v[6:9]
	v_mfma_f32_16x16x32_bf16 v[2:5], v[166:169], v[204:207], v[2:5]
	v_mfma_f32_16x16x32_bf16 v[54:57], v[162:165], v[184:187], v[54:57]
	v_mfma_f32_16x16x32_bf16 v[50:53], v[172:175], v[184:187], v[50:53]
	v_mfma_f32_16x16x32_bf16 v[38:41], v[162:165], v[192:195], v[38:41]
	v_mfma_f32_16x16x32_bf16 v[34:37], v[172:175], v[192:195], v[34:37]
	v_mfma_f32_16x16x32_bf16 v[22:25], v[162:165], v[200:203], v[22:25]
	v_mfma_f32_16x16x32_bf16 v[18:21], v[172:175], v[200:203], v[18:21]
	v_mfma_f32_16x16x32_bf16 v[6:9], v[162:165], v[212:215], v[6:9]
	v_mfma_f32_16x16x32_bf16 v[2:5], v[172:175], v[212:215], v[2:5]
	s_setprio 0
	s_barrier
	s_add_i32 s6, 0, 0x18000
	s_add_i32 s14, 0, 0x1c000
	v_add_u32_e32 v154, s6, v182
	v_add_u32_e32 v170, s14, v182
	ds_read_b128 v[142:145], v154
	ds_read_b128 v[146:149], v154 offset:1024
	ds_read_b128 v[150:153], v154 offset:2048
	ds_read_b128 v[154:157], v154 offset:3072
	ds_read_b128 v[158:161], v170
	ds_read_b128 v[162:165], v170 offset:1024
	ds_read_b128 v[166:169], v170 offset:2048
	ds_read_b128 v[172:175], v170 offset:3072
	s_add_u32 s8, s12, s50
	s_addc_u32 s9, s13, s51
	s_mov_b32 m0, s69
	v_lshl_add_u64 v[224:225], s[8:9], 0, v[134:135]
	ds_read_b128 v[176:179], v183 offset:32768
	ds_read_b128 v[184:187], v183 offset:33792
	ds_read_b128 v[188:191], v183 offset:34816
	ds_read_b128 v[192:195], v183 offset:35840
	ds_read_b128 v[196:199], v183 offset:36864
	ds_read_b128 v[200:203], v183 offset:37888
	ds_read_b128 v[204:207], v183 offset:38912
	ds_read_b128 v[212:215], v183 offset:39936
	global_load_lds_dwordx4 v[224:225], off
	v_lshl_add_u64 v[224:225], s[8:9], 0, v[130:131]
	s_mov_b32 m0, s70
	s_nop 0
	global_load_lds_dwordx4 v[224:225], off
	s_waitcnt vmcnt(8)
	s_waitcnt lgkmcnt(0)
	s_barrier
	s_setprio 1
	v_mfma_f32_16x16x32_bf16 v[126:129], v[142:145], v[176:179], v[126:129]
	v_mfma_f32_16x16x32_bf16 v[122:125], v[150:153], v[176:179], v[122:125]
	v_mfma_f32_16x16x32_bf16 v[110:113], v[142:145], v[188:191], v[110:113]
	v_mfma_f32_16x16x32_bf16 v[106:109], v[150:153], v[188:191], v[106:109]
	v_mfma_f32_16x16x32_bf16 v[94:97], v[142:145], v[196:199], v[94:97]
	v_mfma_f32_16x16x32_bf16 v[90:93], v[150:153], v[196:199], v[90:93]
	v_mfma_f32_16x16x32_bf16 v[78:81], v[142:145], v[204:207], v[78:81]
	v_mfma_f32_16x16x32_bf16 v[74:77], v[150:153], v[204:207], v[74:77]
	v_mfma_f32_16x16x32_bf16 v[126:129], v[146:149], v[184:187], v[126:129]
	v_mfma_f32_16x16x32_bf16 v[122:125], v[154:157], v[184:187], v[122:125]
	v_mfma_f32_16x16x32_bf16 v[110:113], v[146:149], v[192:195], v[110:113]
	v_mfma_f32_16x16x32_bf16 v[106:109], v[154:157], v[192:195], v[106:109]
	v_mfma_f32_16x16x32_bf16 v[94:97], v[146:149], v[200:203], v[94:97]
	v_mfma_f32_16x16x32_bf16 v[90:93], v[154:157], v[200:203], v[90:93]
	v_mfma_f32_16x16x32_bf16 v[78:81], v[146:149], v[212:215], v[78:81]
	v_mfma_f32_16x16x32_bf16 v[74:77], v[154:157], v[212:215], v[74:77]
	v_mfma_f32_16x16x32_bf16 v[118:121], v[158:161], v[176:179], v[118:121]
	v_mfma_f32_16x16x32_bf16 v[114:117], v[166:169], v[176:179], v[114:117]
	v_mfma_f32_16x16x32_bf16 v[102:105], v[158:161], v[188:191], v[102:105]
	v_mfma_f32_16x16x32_bf16 v[98:101], v[166:169], v[188:191], v[98:101]
	v_mfma_f32_16x16x32_bf16 v[86:89], v[158:161], v[196:199], v[86:89]
	v_mfma_f32_16x16x32_bf16 v[82:85], v[166:169], v[196:199], v[82:85]
	v_mfma_f32_16x16x32_bf16 v[70:73], v[158:161], v[204:207], v[70:73]
	v_mfma_f32_16x16x32_bf16 v[66:69], v[166:169], v[204:207], v[66:69]
	v_mfma_f32_16x16x32_bf16 v[118:121], v[162:165], v[184:187], v[118:121]
	v_mfma_f32_16x16x32_bf16 v[114:117], v[172:175], v[184:187], v[114:117]
	v_mfma_f32_16x16x32_bf16 v[102:105], v[162:165], v[192:195], v[102:105]
	v_mfma_f32_16x16x32_bf16 v[98:101], v[172:175], v[192:195], v[98:101]
	v_mfma_f32_16x16x32_bf16 v[86:89], v[162:165], v[200:203], v[86:89]
	v_mfma_f32_16x16x32_bf16 v[82:85], v[172:175], v[200:203], v[82:85]
	v_mfma_f32_16x16x32_bf16 v[70:73], v[162:165], v[212:215], v[70:73]
	v_mfma_f32_16x16x32_bf16 v[66:69], v[172:175], v[212:215], v[66:69]
	s_setprio 0
	s_barrier
	s_add_i32 s6, s6, s66
	v_lshl_add_u64 v[180:181], v[180:181], 0, s[28:29]
	s_mov_b32 m0, s6
	ds_read_b128 v[176:179], v183 offset:49152
	ds_read_b128 v[184:187], v183 offset:50176
	ds_read_b128 v[188:191], v183 offset:51200
	ds_read_b128 v[192:195], v183 offset:52224
	ds_read_b128 v[196:199], v183 offset:53248
	ds_read_b128 v[200:203], v183 offset:54272
	ds_read_b128 v[204:207], v183 offset:55296
	ds_read_b128 v[212:215], v183 offset:56320
	global_load_lds_dwordx4 v[180:181], off
	v_lshl_add_u64 v[180:181], v[208:209], 0, s[28:29]
	s_add_i32 m0, s6, 0x2000
	s_add_i32 s6, s14, s66
	global_load_lds_dwordx4 v[180:181], off
	v_lshl_add_u64 v[180:181], v[216:217], 0, s[28:29]
	s_mov_b32 m0, s6
	s_nop 0
	global_load_lds_dwordx4 v[180:181], off
	v_lshl_add_u64 v[180:181], v[218:219], 0, s[28:29]
	s_add_i32 m0, s6, 0x2000
	s_nop 0
	global_load_lds_dwordx4 v[180:181], off
	v_lshl_add_u64 v[180:181], v[220:221], 0, s[28:29]
	s_mov_b32 m0, s71
	s_nop 0
	global_load_lds_dwordx4 v[180:181], off
	v_lshl_add_u64 v[180:181], v[222:223], 0, s[28:29]
	s_mov_b32 m0, s72
	s_nop 0
	global_load_lds_dwordx4 v[180:181], off
	s_waitcnt vmcnt(8)
	s_waitcnt lgkmcnt(0)
	s_barrier
	s_setprio 1
	v_mfma_f32_16x16x32_bf16 v[62:65], v[142:145], v[176:179], v[62:65]
	v_mfma_f32_16x16x32_bf16 v[58:61], v[150:153], v[176:179], v[58:61]
	v_mfma_f32_16x16x32_bf16 v[46:49], v[142:145], v[188:191], v[46:49]
	v_mfma_f32_16x16x32_bf16 v[42:45], v[150:153], v[188:191], v[42:45]
	v_mfma_f32_16x16x32_bf16 v[30:33], v[142:145], v[196:199], v[30:33]
	v_mfma_f32_16x16x32_bf16 v[26:29], v[150:153], v[196:199], v[26:29]
	v_mfma_f32_16x16x32_bf16 v[14:17], v[142:145], v[204:207], v[14:17]
	v_mfma_f32_16x16x32_bf16 v[10:13], v[150:153], v[204:207], v[10:13]
	v_mfma_f32_16x16x32_bf16 v[62:65], v[146:149], v[184:187], v[62:65]
	v_mfma_f32_16x16x32_bf16 v[58:61], v[154:157], v[184:187], v[58:61]
	v_mfma_f32_16x16x32_bf16 v[46:49], v[146:149], v[192:195], v[46:49]
	v_mfma_f32_16x16x32_bf16 v[42:45], v[154:157], v[192:195], v[42:45]
	v_mfma_f32_16x16x32_bf16 v[30:33], v[146:149], v[200:203], v[30:33]
	v_mfma_f32_16x16x32_bf16 v[26:29], v[154:157], v[200:203], v[26:29]
	v_mfma_f32_16x16x32_bf16 v[14:17], v[146:149], v[212:215], v[14:17]
	v_mfma_f32_16x16x32_bf16 v[10:13], v[154:157], v[212:215], v[10:13]
	v_mfma_f32_16x16x32_bf16 v[54:57], v[158:161], v[176:179], v[54:57]
	v_mfma_f32_16x16x32_bf16 v[50:53], v[166:169], v[176:179], v[50:53]
	v_mfma_f32_16x16x32_bf16 v[38:41], v[158:161], v[188:191], v[38:41]
	v_mfma_f32_16x16x32_bf16 v[34:37], v[166:169], v[188:191], v[34:37]
	v_mfma_f32_16x16x32_bf16 v[22:25], v[158:161], v[196:199], v[22:25]
	v_mfma_f32_16x16x32_bf16 v[18:21], v[166:169], v[196:199], v[18:21]
	v_mfma_f32_16x16x32_bf16 v[6:9], v[158:161], v[204:207], v[6:9]
	v_mfma_f32_16x16x32_bf16 v[2:5], v[166:169], v[204:207], v[2:5]
	v_mfma_f32_16x16x32_bf16 v[54:57], v[162:165], v[184:187], v[54:57]
	v_mfma_f32_16x16x32_bf16 v[50:53], v[172:175], v[184:187], v[50:53]
	v_mfma_f32_16x16x32_bf16 v[38:41], v[162:165], v[192:195], v[38:41]
	v_mfma_f32_16x16x32_bf16 v[34:37], v[172:175], v[192:195], v[34:37]
	v_mfma_f32_16x16x32_bf16 v[22:25], v[162:165], v[200:203], v[22:25]
	v_mfma_f32_16x16x32_bf16 v[18:21], v[172:175], v[200:203], v[18:21]
	v_mfma_f32_16x16x32_bf16 v[6:9], v[162:165], v[212:215], v[6:9]
	v_mfma_f32_16x16x32_bf16 v[2:5], v[172:175], v[212:215], v[2:5]
	s_setprio 0
	s_barrier
	s_add_u32 s1, s1, 0x100
	s_addc_u32 s5, s5, 0
	s_add_u32 s10, s10, 0x100
	s_addc_u32 s11, s11, 0
	s_cmp_ge_i32 s7, s73
	s_mov_b32 s6, s7
	s_cbranch_scc0 .LBB0_522
	v_mov_b64_e32 v[224:225], v[210:211]

.LBB0_664:
	s_xor_b64 s[10:11], s[50:51], -1
	s_andn2_b64 vcc, exec, s[24:25]
	s_cbranch_vccnz .LBB0_704
	v_mov_b32_e32 v160, 0
	v_mov_b32_e32 v161, 0
	v_mov_b32_e32 v162, 0
	v_mov_b32_e32 v163, 0
	v_mov_b32_e32 v164, 0
	v_mov_b32_e32 v165, 0
	v_mov_b32_e32 v166, 0
	v_mov_b32_e32 v167, 0
	v_mov_b32_e32 v168, 0
	v_mov_b32_e32 v169, 0
	v_mov_b32_e32 v170, 0
	v_mov_b32_e32 v171, 0
	v_mov_b32_e32 v172, 0
	v_mov_b32_e32 v173, 0
	v_mov_b32_e32 v174, 0
	v_mov_b32_e32 v175, 0
	v_mov_b32_e32 v14, v0
	v_mov_b32_e32 v15, v0
	v_mov_b32_e32 v1, v0
	v_mov_b32_e32 v2, v0
	v_mov_b32_e32 v3, v0
	v_mov_b32_e32 v4, v0
	v_mov_b32_e32 v5, v0
	v_mov_b32_e32 v6, v0
	v_mov_b32_e32 v7, v0
	v_mov_b32_e32 v8, v0
	v_mov_b32_e32 v9, v0
	v_mov_b32_e32 v10, v0
	v_mov_b32_e32 v11, v0
	v_mov_b32_e32 v12, v0
	v_mov_b32_e32 v13, v0
	v_mov_b64_e32 v[46:47], v[14:15]
	v_mov_b64_e32 v[62:63], v[14:15]
	v_mov_b64_e32 v[78:79], v[14:15]
	v_mov_b64_e32 v[94:95], v[14:15]
	s_mov_b32 s18, 1
	v_lshl_add_u64 v[240:241], s[48:49], 1, v[238:239]
	s_mov_b32 s15, 0
	v_mov_b32_e32 v217, 0
	s_mov_b32 s31, 2
	s_movk_i32 s76, 0x80
	v_mov_b64_e32 v[44:45], v[12:13]
	v_mov_b64_e32 v[42:43], v[10:11]
	v_mov_b64_e32 v[40:41], v[8:9]
	v_mov_b64_e32 v[38:39], v[6:7]
	v_mov_b64_e32 v[36:37], v[4:5]
	v_mov_b64_e32 v[34:35], v[2:3]
	v_mov_b64_e32 v[32:33], v[0:1]
	v_mov_b64_e32 v[60:61], v[12:13]
	v_mov_b64_e32 v[58:59], v[10:11]
	v_mov_b64_e32 v[56:57], v[8:9]
	v_mov_b64_e32 v[54:55], v[6:7]
	v_mov_b64_e32 v[52:53], v[4:5]
	v_mov_b64_e32 v[50:51], v[2:3]
	v_mov_b64_e32 v[48:49], v[0:1]
	v_mov_b64_e32 v[76:77], v[12:13]
	v_mov_b64_e32 v[74:75], v[10:11]
	v_mov_b64_e32 v[72:73], v[8:9]
	v_mov_b64_e32 v[70:71], v[6:7]
	v_mov_b64_e32 v[68:69], v[4:5]
	v_mov_b64_e32 v[66:67], v[2:3]
	v_mov_b64_e32 v[64:65], v[0:1]
	v_mov_b64_e32 v[92:93], v[12:13]
	v_mov_b64_e32 v[90:91], v[10:11]
	v_mov_b64_e32 v[88:89], v[8:9]
	v_mov_b64_e32 v[86:87], v[6:7]
	v_mov_b64_e32 v[84:85], v[4:5]
	v_mov_b64_e32 v[82:83], v[2:3]
	v_mov_b64_e32 v[80:81], v[0:1]
	s_mov_b32 s21, 0
	s_mov_b32 s30, 0
	v_mov_b32_e32 v216, 0
	s_add_i32 s20, s30, 1
	s_mov_b32 s19, s21
	s_cmp_ge_i32 s20, s6
	s_cbranch_scc1 .LBB0_669

.LBB0_681:
	v_add3_u32 v1, s21, v209, v213
	ds_read_b128 v[6:9], v1
	ds_read_b128 v[10:13], v1 offset:32
	ds_read_b128 v[112:115], v1 offset:64
	ds_read_b128 v[2:5], v1 offset:96
	s_mulk_i32 s31, 0x4800
	v_add_u32_e32 v132, s31, v223
	ds_read_b128 v[124:127], v132 offset:18496
	ds_read_b128 v[128:131], v132 offset:18528
	ds_read_b128 v[134:137], v132 offset:23104
	ds_read_b128 v[138:141], v132 offset:23136
	ds_read_b128 v[142:145], v132 offset:27712
	ds_read_b128 v[146:149], v132 offset:27744
	ds_read_b128 v[150:153], v132 offset:32320
	ds_read_b128 v[154:157], v132 offset:32352
	s_waitcnt lgkmcnt(11)
	v_mfma_f32_32x32x16_bf16 v[96:111], v[6:9], v[176:179], v[160:175]
	v_exp_f32_e32 v7, v16
	v_exp_f32_e32 v9, v17
	v_max_f32_e32 v1, v16, v17
	s_waitcnt lgkmcnt(10)
	v_mfma_f32_32x32x16_bf16 v[96:111], v[10:13], v[180:183], v[96:111]
	v_exp_f32_e32 v11, v18
	v_exp_f32_e32 v12, v19
	v_exp_f32_e32 v13, v20
	v_add_f32_e32 v8, v9, v7
	v_exp_f32_e32 v14, v21
	v_add_f32_e32 v8, v11, v8
	v_exp_f32_e32 v15, v22
	v_max3_f32 v1, v1, v18, v19
	v_add_f32_e32 v8, v12, v8
	v_exp_f32_e32 v16, v23
	v_max3_f32 v1, v1, v20, v21
	v_add_f32_e32 v8, v13, v8
	v_exp_f32_e32 v17, v24
	v_max3_f32 v1, v1, v22, v23
	v_add_f32_e32 v8, v14, v8
	v_exp_f32_e32 v18, v25
	v_max3_f32 v1, v1, v24, v25
	v_add_f32_e32 v8, v15, v8
	v_exp_f32_e32 v19, v26
	v_max3_f32 v1, v1, v26, v27
	v_add_f32_e32 v8, v16, v8
	v_exp_f32_e32 v20, v27
	v_max3_f32 v1, v1, v28, v29
	v_add_f32_e32 v8, v17, v8
	v_exp_f32_e32 v21, v28
	v_max3_f32 v1, v1, v30, v31
	v_add_f32_e32 v8, v18, v8
	v_exp_f32_e32 v22, v29
	ds_bpermute_b32 v6, v247, v1
	v_add_f32_e32 v8, v19, v8
	v_exp_f32_e32 v23, v30
	v_add_f32_e32 v8, v20, v8
	v_exp_f32_e32 v24, v31
	v_add_f32_e32 v8, v21, v8
	v_add_f32_e32 v8, v22, v8
	v_add_f32_e32 v8, v23, v8
	v_add_f32_e32 v8, v24, v8
	s_waitcnt lgkmcnt(0)
	v_max_f32_e32 v210, v1, v6
	v_add_f32_e32 v1, v216, v8
	v_cvt_pk_bf16_f32 v8, v21, v22
	v_cvt_pk_bf16_f32 v10, v7, v9
	v_cvt_pk_bf16_f32 v11, v11, v12
	v_cvt_pk_bf16_f32 v12, v13, v14
	v_cvt_pk_bf16_f32 v13, v15, v16
	v_cvt_pk_bf16_f32 v6, v17, v18
	v_cvt_pk_bf16_f32 v7, v19, v20
	v_mfma_f32_32x32x16_bf16 v[96:111], v[112:115], v[184:187], v[96:111]
	v_cvt_pk_bf16_f32 v9, v23, v24
	v_mfma_f32_32x32x16_bf16 v[32:47], v[124:127], v[10:13], v[32:47]
	v_mfma_f32_32x32x16_bf16 v[48:63], v[134:137], v[10:13], v[48:63]
	v_mfma_f32_32x32x16_bf16 v[48:63], v[138:141], v[6:9], v[48:63]
	v_mfma_f32_32x32x16_bf16 v[64:79], v[142:145], v[10:13], v[64:79]
	v_mfma_f32_32x32x16_bf16 v[64:79], v[146:149], v[6:9], v[64:79]
	v_mfma_f32_32x32x16_bf16 v[80:95], v[150:153], v[10:13], v[80:95]
	v_mfma_f32_32x32x16_bf16 v[32:47], v[128:131], v[6:9], v[32:47]
	v_mfma_f32_32x32x16_bf16 v[80:95], v[154:157], v[6:9], v[80:95]
	v_mfma_f32_32x32x16_bf16 v[16:31], v[2:5], v[188:191], v[96:111]
	v_mov_b32_e32 v2, v210
	v_cmp_lt_f32_e32 vcc, s2, v2
	s_cbranch_vccz .LBB0_698
	v_max_f32_e32 v2, v2, v2
	v_max_f32_e32 v3, 0, v2
	v_exp_f32_e64 v2, -v3
	v_add_f32_e32 v6, v217, v3
	v_mul_f32_e32 v1, v2, v1
	s_nop 3
	v_pk_mul_f32 v[46:47], v[46:47], v[2:3] op_sel_hi:[1,0]
	v_pk_mul_f32 v[44:45], v[44:45], v[2:3] op_sel_hi:[1,0]
	v_pk_mul_f32 v[42:43], v[42:43], v[2:3] op_sel_hi:[1,0]
	v_pk_mul_f32 v[40:41], v[40:41], v[2:3] op_sel_hi:[1,0]
	v_pk_mul_f32 v[38:39], v[38:39], v[2:3] op_sel_hi:[1,0]
	v_pk_mul_f32 v[36:37], v[36:37], v[2:3] op_sel_hi:[1,0]
	v_pk_mul_f32 v[34:35], v[34:35], v[2:3] op_sel_hi:[1,0]
	v_pk_mul_f32 v[32:33], v[32:33], v[2:3] op_sel_hi:[1,0]
	v_pk_mul_f32 v[62:63], v[62:63], v[2:3] op_sel_hi:[1,0]
	v_pk_mul_f32 v[60:61], v[60:61], v[2:3] op_sel_hi:[1,0]
	v_pk_mul_f32 v[58:59], v[58:59], v[2:3] op_sel_hi:[1,0]
	v_pk_mul_f32 v[56:57], v[56:57], v[2:3] op_sel_hi:[1,0]
	v_pk_mul_f32 v[54:55], v[54:55], v[2:3] op_sel_hi:[1,0]
	v_pk_mul_f32 v[52:53], v[52:53], v[2:3] op_sel_hi:[1,0]
	v_pk_mul_f32 v[50:51], v[50:51], v[2:3] op_sel_hi:[1,0]
	v_pk_mul_f32 v[48:49], v[48:49], v[2:3] op_sel_hi:[1,0]
	v_pk_mul_f32 v[78:79], v[2:3], v[78:79] op_sel_hi:[0,1]
	v_pk_mul_f32 v[76:77], v[2:3], v[76:77] op_sel_hi:[0,1]
	v_pk_mul_f32 v[74:75], v[2:3], v[74:75] op_sel_hi:[0,1]
	v_pk_mul_f32 v[72:73], v[2:3], v[72:73] op_sel_hi:[0,1]
	v_pk_mul_f32 v[70:71], v[2:3], v[70:71] op_sel_hi:[0,1]
	v_pk_mul_f32 v[68:69], v[2:3], v[68:69] op_sel_hi:[0,1]
	v_pk_mul_f32 v[66:67], v[2:3], v[66:67] op_sel_hi:[0,1]
	v_pk_mul_f32 v[64:65], v[2:3], v[64:65] op_sel_hi:[0,1]
	v_pk_mul_f32 v[94:95], v[2:3], v[94:95] op_sel_hi:[0,1]
	v_pk_mul_f32 v[92:93], v[2:3], v[92:93] op_sel_hi:[0,1]
	v_pk_mul_f32 v[90:91], v[2:3], v[90:91] op_sel_hi:[0,1]
	v_pk_mul_f32 v[88:89], v[2:3], v[88:89] op_sel_hi:[0,1]
	v_pk_mul_f32 v[86:87], v[2:3], v[86:87] op_sel_hi:[0,1]
	v_pk_mul_f32 v[84:85], v[2:3], v[84:85] op_sel_hi:[0,1]
	v_pk_mul_f32 v[82:83], v[2:3], v[82:83] op_sel_hi:[0,1]
	v_pk_mul_f32 v[80:81], v[2:3], v[80:81] op_sel_hi:[0,1]
	v_sub_f32_e32 v16, v16, v3
	v_sub_f32_e32 v17, v17, v3
	v_sub_f32_e32 v18, v18, v3
	v_sub_f32_e32 v19, v19, v3
	v_sub_f32_e32 v20, v20, v3
	v_sub_f32_e32 v21, v21, v3
	v_sub_f32_e32 v22, v22, v3
	v_sub_f32_e32 v23, v23, v3
	v_sub_f32_e32 v24, v24, v3
	v_sub_f32_e32 v25, v25, v3
	v_sub_f32_e32 v26, v26, v3
	v_sub_f32_e32 v27, v27, v3
	v_sub_f32_e32 v28, v28, v3
	v_sub_f32_e32 v29, v29, v3
	v_sub_f32_e32 v30, v30, v3
	v_sub_f32_e32 v31, v31, v3
	v_sub_f32_e32 v160, v160, v3
	v_sub_f32_e32 v161, v161, v3
	v_sub_f32_e32 v162, v162, v3
	v_sub_f32_e32 v163, v163, v3
	v_sub_f32_e32 v164, v164, v3
	v_sub_f32_e32 v165, v165, v3
	v_sub_f32_e32 v166, v166, v3
	v_sub_f32_e32 v167, v167, v3
	v_sub_f32_e32 v168, v168, v3
	v_sub_f32_e32 v169, v169, v3
	v_sub_f32_e32 v170, v170, v3
	v_sub_f32_e32 v171, v171, v3
	v_sub_f32_e32 v172, v172, v3
	v_sub_f32_e32 v173, v173, v3
	v_sub_f32_e32 v174, v174, v3
	v_sub_f32_e32 v175, v175, v3
	s_cbranch_execz .LBB0_685
	s_branch .LBB0_686

.LBB0_694:
	v_add3_u32 v119, s21, v209, v213
	ds_read_b128 v[2:5], v119 offset:4608
	ds_read_b128 v[10:13], v119 offset:4640
	s_mul_i32 s21, s19, 0x4800
	v_add_u32_e32 v132, s21, v223
	ds_read_b128 v[124:127], v132 offset:18432
	ds_read_b128 v[128:131], v132 offset:18464
	ds_read_b128 v[134:137], v132 offset:23040
	ds_read_b128 v[138:141], v132 offset:23072
	ds_read_b128 v[142:145], v132 offset:27648
	ds_read_b128 v[146:149], v132 offset:27680
	ds_read_b128 v[150:153], v132 offset:32256
	ds_read_b128 v[154:157], v132 offset:32288
	s_waitcnt lgkmcnt(9)
	v_mfma_f32_32x32x16_bf16 v[96:111], v[2:5], v[176:179], v[160:175]
	ds_read_b128 v[2:5], v119 offset:4672
	v_exp_f32_e32 v7, v16
	s_waitcnt lgkmcnt(9)
	v_mfma_f32_32x32x16_bf16 v[96:111], v[10:13], v[180:183], v[96:111]
	v_exp_f32_e32 v13, v22
	v_exp_f32_e32 v10, v19
	v_exp_f32_e32 v14, v23
	v_exp_f32_e32 v11, v20
	v_exp_f32_e32 v15, v24
	v_exp_f32_e32 v8, v17
	v_exp_f32_e32 v9, v18
	s_waitcnt lgkmcnt(0)
	v_mfma_f32_32x32x16_bf16 v[96:111], v[2:5], v[184:187], v[96:111]
	v_exp_f32_e32 v113, v26
	v_exp_f32_e32 v114, v27
	v_exp_f32_e32 v115, v28
	v_exp_f32_e32 v12, v21
	v_cvt_pk_bf16_f32 v120, v7, v8
	v_cvt_pk_bf16_f32 v121, v9, v10
	v_cvt_pk_bf16_f32 v123, v13, v14
	v_cvt_pk_bf16_f32 v122, v11, v12
	v_exp_f32_e32 v112, v25
	v_exp_f32_e32 v116, v29
	v_mfma_f32_32x32x16_bf16 v[32:47], v[124:127], v[120:123], v[32:47]
	ds_read_b128 v[124:127], v119 offset:4704
	v_exp_f32_e32 v117, v30
	v_exp_f32_e32 v118, v31
	v_cvt_pk_bf16_f32 v2, v15, v112
	v_cvt_pk_bf16_f32 v3, v113, v114
	v_cvt_pk_bf16_f32 v4, v115, v116
	v_cvt_pk_bf16_f32 v5, v117, v118
	v_max_f32_e32 v16, v16, v17
	v_max3_f32 v16, v16, v18, v19
	v_mfma_f32_32x32x16_bf16 v[32:47], v[128:131], v[2:5], v[32:47]
	v_max3_f32 v16, v16, v20, v21
	v_max3_f32 v16, v16, v22, v23
	v_max3_f32 v20, v16, v24, v25
	v_mfma_f32_32x32x16_bf16 v[48:63], v[134:137], v[120:123], v[48:63]
	v_max3_f32 v20, v20, v26, v27
	v_max3_f32 v20, v20, v28, v29
	v_max3_f32 v20, v20, v30, v31
	ds_bpermute_b32 v21, v247, v20
	s_andn2_b64 vcc, exec, s[92:93]
	v_mfma_f32_32x32x16_bf16 v[48:63], v[138:141], v[2:5], v[48:63]
	v_mfma_f32_32x32x16_bf16 v[64:79], v[142:145], v[120:123], v[64:79]
	v_mfma_f32_32x32x16_bf16 v[80:95], v[150:153], v[120:123], v[80:95]
	v_mfma_f32_32x32x16_bf16 v[64:79], v[146:149], v[2:5], v[64:79]
	v_mfma_f32_32x32x16_bf16 v[80:95], v[154:157], v[2:5], v[80:95]
	s_waitcnt lgkmcnt(0)
	v_max_f32_e32 v2, v20, v21
	v_mfma_f32_32x32x16_bf16 v[16:31], v[124:127], v[188:191], v[96:111]
	s_cbranch_vccnz .LBB0_697
	v_cmp_lt_f32_e32 vcc, s2, v2
	s_cbranch_vccz .LBB0_699
	v_max_f32_e32 v2, v2, v2
	v_max_f32_e32 v2, 0, v2

.LBB0_700:
	v_add_f32_e32 v3, v8, v7
	v_add_f32_e32 v3, v9, v3
	v_add_f32_e32 v3, v10, v3
	v_add_f32_e32 v3, v11, v3
	v_add_f32_e32 v3, v12, v3
	v_add_f32_e32 v3, v13, v3
	v_add_f32_e32 v3, v14, v3
	v_add_f32_e32 v3, v15, v3
	v_add_f32_e32 v3, v112, v3
	v_add_f32_e32 v3, v113, v3
	v_add_f32_e32 v3, v114, v3
	v_add_f32_e32 v3, v115, v3
	v_add_f32_e32 v3, v116, v3
	v_add_f32_e32 v3, v117, v3
	v_add_f32_e32 v3, v118, v3
	v_add_f32_e32 v1, v1, v3
	s_and_b64 vcc, exec, s[48:49]
	s_cbranch_vccz .LBB0_702
	v_exp_f32_e64 v4, -v2
	v_add_f32_e32 v6, v6, v2
	v_mul_f32_e32 v1, v1, v4
	v_pk_mul_f32 v[46:47], v[46:47], v[4:5] op_sel_hi:[1,0]
	v_pk_mul_f32 v[44:45], v[44:45], v[4:5] op_sel_hi:[1,0]
	v_pk_mul_f32 v[42:43], v[42:43], v[4:5] op_sel_hi:[1,0]
	v_pk_mul_f32 v[40:41], v[40:41], v[4:5] op_sel_hi:[1,0]
	v_pk_mul_f32 v[38:39], v[38:39], v[4:5] op_sel_hi:[1,0]
	v_pk_mul_f32 v[36:37], v[36:37], v[4:5] op_sel_hi:[1,0]
	v_pk_mul_f32 v[34:35], v[34:35], v[4:5] op_sel_hi:[1,0]
	v_pk_mul_f32 v[32:33], v[32:33], v[4:5] op_sel_hi:[1,0]
	v_pk_mul_f32 v[62:63], v[62:63], v[4:5] op_sel_hi:[1,0]
	v_pk_mul_f32 v[60:61], v[60:61], v[4:5] op_sel_hi:[1,0]
	v_pk_mul_f32 v[58:59], v[58:59], v[4:5] op_sel_hi:[1,0]
	v_pk_mul_f32 v[56:57], v[56:57], v[4:5] op_sel_hi:[1,0]
	v_pk_mul_f32 v[54:55], v[54:55], v[4:5] op_sel_hi:[1,0]
	v_pk_mul_f32 v[52:53], v[52:53], v[4:5] op_sel_hi:[1,0]
	v_pk_mul_f32 v[50:51], v[50:51], v[4:5] op_sel_hi:[1,0]
	v_pk_mul_f32 v[48:49], v[48:49], v[4:5] op_sel_hi:[1,0]
	v_pk_mul_f32 v[78:79], v[78:79], v[4:5] op_sel_hi:[1,0]
	v_pk_mul_f32 v[76:77], v[76:77], v[4:5] op_sel_hi:[1,0]
	v_pk_mul_f32 v[74:75], v[74:75], v[4:5] op_sel_hi:[1,0]
	v_pk_mul_f32 v[72:73], v[72:73], v[4:5] op_sel_hi:[1,0]
	v_pk_mul_f32 v[70:71], v[70:71], v[4:5] op_sel_hi:[1,0]
	v_pk_mul_f32 v[68:69], v[68:69], v[4:5] op_sel_hi:[1,0]
	v_pk_mul_f32 v[66:67], v[66:67], v[4:5] op_sel_hi:[1,0]
	v_pk_mul_f32 v[64:65], v[64:65], v[4:5] op_sel_hi:[1,0]
	v_pk_mul_f32 v[94:95], v[94:95], v[4:5] op_sel_hi:[1,0]
	v_pk_mul_f32 v[92:93], v[92:93], v[4:5] op_sel_hi:[1,0]
	v_pk_mul_f32 v[90:91], v[90:91], v[4:5] op_sel_hi:[1,0]
	v_pk_mul_f32 v[88:89], v[88:89], v[4:5] op_sel_hi:[1,0]
	v_pk_mul_f32 v[86:87], v[86:87], v[4:5] op_sel_hi:[1,0]
	v_pk_mul_f32 v[84:85], v[84:85], v[4:5] op_sel_hi:[1,0]
	v_pk_mul_f32 v[82:83], v[82:83], v[4:5] op_sel_hi:[1,0]
	v_pk_mul_f32 v[80:81], v[80:81], v[4:5] op_sel_hi:[1,0]
	v_sub_f32_e32 v16, v16, v2
	v_sub_f32_e32 v17, v17, v2
	v_sub_f32_e32 v18, v18, v2
	v_sub_f32_e32 v19, v19, v2
	v_sub_f32_e32 v20, v20, v2
	v_sub_f32_e32 v21, v21, v2
	v_sub_f32_e32 v22, v22, v2
	v_sub_f32_e32 v23, v23, v2
	v_sub_f32_e32 v24, v24, v2
	v_sub_f32_e32 v25, v25, v2
	v_sub_f32_e32 v26, v26, v2
	v_sub_f32_e32 v27, v27, v2
	v_sub_f32_e32 v28, v28, v2
	v_sub_f32_e32 v29, v29, v2
	v_sub_f32_e32 v30, v30, v2
	v_sub_f32_e32 v31, v31, v2
	v_sub_f32_e32 v160, v160, v2
	v_sub_f32_e32 v161, v161, v2
	v_sub_f32_e32 v162, v162, v2
	v_sub_f32_e32 v163, v163, v2
	v_sub_f32_e32 v164, v164, v2
	v_sub_f32_e32 v165, v165, v2
	v_sub_f32_e32 v166, v166, v2
	v_sub_f32_e32 v167, v167, v2
	v_sub_f32_e32 v168, v168, v2
	v_sub_f32_e32 v169, v169, v2
	v_sub_f32_e32 v170, v170, v2
	v_sub_f32_e32 v171, v171, v2
	v_sub_f32_e32 v172, v172, v2
	v_sub_f32_e32 v173, v173, v2
	v_sub_f32_e32 v174, v174, v2
	v_sub_f32_e32 v175, v175, v2

.LBB0_787:
	s_add_i32 s25, s12, 2
	s_add_u32 s33, s10, 0x80
	s_addc_u32 s13, s11, 0
	s_add_i32 s36, 0, 0x10000
	s_cmp_eq_u32 s20, s12
	s_cselect_b32 s13, s45, s13
	s_cselect_b32 s12, s44, s33
	v_add_u32_e32 v146, s36, v149
	s_cselect_b32 s35, s61, s24
	s_cselect_b32 s34, s60, s1
	s_add_i32 s33, 0, 0x14000
	ds_read_b128 v[142:145], v146
	ds_read_b128 v[152:155], v146 offset:1024
	ds_read_b128 v[156:159], v146 offset:2048
	ds_read_b128 v[160:163], v146 offset:3072
	v_add_u32_e32 v146, s33, v149
	ds_read_b128 v[164:167], v146
	ds_read_b128 v[168:171], v146 offset:1024
	ds_read_b128 v[172:175], v146 offset:2048
	ds_read_b128 v[176:179], v146 offset:3072
	v_lshl_add_u64 v[146:147], s[10:11], 0, v[138:139]
	s_add_i32 m0, s5, 0xc000
	ds_read_b128 v[180:183], v150
	ds_read_b128 v[184:187], v150 offset:1024
	ds_read_b128 v[188:191], v150 offset:2048
	ds_read_b128 v[192:195], v150 offset:3072
	ds_read_b128 v[196:199], v150 offset:4096
	ds_read_b128 v[200:203], v150 offset:5120
	ds_read_b128 v[204:207], v150 offset:6144
	ds_read_b128 v[212:215], v150 offset:7168
	global_load_lds_dwordx4 v[146:147], off
	v_lshl_add_u64 v[146:147], s[10:11], 0, v[140:141]
	s_add_i32 m0, s5, 0xe000
	s_nop 0
	global_load_lds_dwordx4 v[146:147], off
	s_waitcnt vmcnt(8)
	s_waitcnt lgkmcnt(0)
	s_barrier
	s_setprio 1
	v_mfma_f32_16x16x32_bf16 v[126:129], v[142:145], v[180:183], v[126:129]
	v_mfma_f32_16x16x32_bf16 v[122:125], v[156:159], v[180:183], v[122:125]
	v_mfma_f32_16x16x32_bf16 v[110:113], v[142:145], v[188:191], v[110:113]
	v_mfma_f32_16x16x32_bf16 v[106:109], v[156:159], v[188:191], v[106:109]
	v_mfma_f32_16x16x32_bf16 v[94:97], v[142:145], v[196:199], v[94:97]
	v_mfma_f32_16x16x32_bf16 v[90:93], v[156:159], v[196:199], v[90:93]
	v_mfma_f32_16x16x32_bf16 v[78:81], v[142:145], v[204:207], v[78:81]
	v_mfma_f32_16x16x32_bf16 v[74:77], v[156:159], v[204:207], v[74:77]
	v_mfma_f32_16x16x32_bf16 v[126:129], v[152:155], v[184:187], v[126:129]
	v_mfma_f32_16x16x32_bf16 v[122:125], v[160:163], v[184:187], v[122:125]
	v_mfma_f32_16x16x32_bf16 v[110:113], v[152:155], v[192:195], v[110:113]
	v_mfma_f32_16x16x32_bf16 v[106:109], v[160:163], v[192:195], v[106:109]
	v_mfma_f32_16x16x32_bf16 v[94:97], v[152:155], v[200:203], v[94:97]
	v_mfma_f32_16x16x32_bf16 v[90:93], v[160:163], v[200:203], v[90:93]
	v_mfma_f32_16x16x32_bf16 v[78:81], v[152:155], v[212:215], v[78:81]
	v_mfma_f32_16x16x32_bf16 v[74:77], v[160:163], v[212:215], v[74:77]
	v_mfma_f32_16x16x32_bf16 v[118:121], v[164:167], v[180:183], v[118:121]
	v_mfma_f32_16x16x32_bf16 v[114:117], v[172:175], v[180:183], v[114:117]
	v_mfma_f32_16x16x32_bf16 v[102:105], v[164:167], v[188:191], v[102:105]
	v_mfma_f32_16x16x32_bf16 v[98:101], v[172:175], v[188:191], v[98:101]
	v_mfma_f32_16x16x32_bf16 v[86:89], v[164:167], v[196:199], v[86:89]
	v_mfma_f32_16x16x32_bf16 v[82:85], v[172:175], v[196:199], v[82:85]
	v_mfma_f32_16x16x32_bf16 v[70:73], v[164:167], v[204:207], v[70:73]
	v_mfma_f32_16x16x32_bf16 v[66:69], v[172:175], v[204:207], v[66:69]
	v_mfma_f32_16x16x32_bf16 v[118:121], v[168:171], v[184:187], v[118:121]
	v_mfma_f32_16x16x32_bf16 v[114:117], v[176:179], v[184:187], v[114:117]
	v_mfma_f32_16x16x32_bf16 v[102:105], v[168:171], v[192:195], v[102:105]
	v_mfma_f32_16x16x32_bf16 v[98:101], v[176:179], v[192:195], v[98:101]
	v_mfma_f32_16x16x32_bf16 v[86:89], v[168:171], v[200:203], v[86:89]
	v_mfma_f32_16x16x32_bf16 v[82:85], v[176:179], v[200:203], v[82:85]
	v_mfma_f32_16x16x32_bf16 v[70:73], v[168:171], v[212:215], v[70:73]
	v_mfma_f32_16x16x32_bf16 v[66:69], v[176:179], v[212:215], v[66:69]
	s_setprio 0
	s_barrier
	s_add_i32 s36, s36, s4
	v_lshl_add_u64 v[146:147], s[34:35], 0, v[136:137]
	s_mov_b32 m0, s36
	ds_read_b128 v[180:183], v150 offset:16384
	ds_read_b128 v[184:187], v150 offset:17408
	ds_read_b128 v[188:191], v150 offset:18432
	ds_read_b128 v[192:195], v150 offset:19456
	ds_read_b128 v[196:199], v150 offset:20480
	ds_read_b128 v[200:203], v150 offset:21504
	ds_read_b128 v[204:207], v150 offset:22528
	ds_read_b128 v[212:215], v150 offset:23552
	global_load_lds_dwordx4 v[146:147], off
	s_add_i32 m0, s36, 0x2000
	v_lshl_add_u64 v[208:209], s[34:35], 0, v[132:133]
	s_add_u32 s34, s34, s50
	s_addc_u32 s35, s35, s51
	s_add_i32 s33, s33, s4
	global_load_lds_dwordx4 v[208:209], off
	v_lshl_add_u64 v[210:211], s[34:35], 0, v[136:137]
	s_mov_b32 m0, s33
	v_lshl_add_u64 v[216:217], s[34:35], 0, v[132:133]
	global_load_lds_dwordx4 v[210:211], off
	s_add_i32 m0, s33, 0x2000
	v_lshl_add_u64 v[218:219], s[12:13], 0, v[134:135]
	global_load_lds_dwordx4 v[216:217], off
	s_mov_b32 m0, s5
	v_lshl_add_u64 v[220:221], s[12:13], 0, v[130:131]
	global_load_lds_dwordx4 v[218:219], off
	s_mov_b32 m0, s6
	s_nop 0
	global_load_lds_dwordx4 v[220:221], off
	s_waitcnt vmcnt(8)
	s_waitcnt lgkmcnt(0)
	s_barrier
	s_setprio 1
	v_mfma_f32_16x16x32_bf16 v[62:65], v[142:145], v[180:183], v[62:65]
	v_mfma_f32_16x16x32_bf16 v[58:61], v[156:159], v[180:183], v[58:61]
	v_mfma_f32_16x16x32_bf16 v[46:49], v[142:145], v[188:191], v[46:49]
	v_mfma_f32_16x16x32_bf16 v[42:45], v[156:159], v[188:191], v[42:45]
	v_mfma_f32_16x16x32_bf16 v[30:33], v[142:145], v[196:199], v[30:33]
	v_mfma_f32_16x16x32_bf16 v[26:29], v[156:159], v[196:199], v[26:29]
	v_mfma_f32_16x16x32_bf16 v[14:17], v[142:145], v[204:207], v[14:17]
	v_mfma_f32_16x16x32_bf16 v[10:13], v[156:159], v[204:207], v[10:13]
	v_mfma_f32_16x16x32_bf16 v[62:65], v[152:155], v[184:187], v[62:65]
	v_mfma_f32_16x16x32_bf16 v[58:61], v[160:163], v[184:187], v[58:61]
	v_mfma_f32_16x16x32_bf16 v[46:49], v[152:155], v[192:195], v[46:49]
	v_mfma_f32_16x16x32_bf16 v[42:45], v[160:163], v[192:195], v[42:45]
	v_mfma_f32_16x16x32_bf16 v[30:33], v[152:155], v[200:203], v[30:33]
	v_mfma_f32_16x16x32_bf16 v[26:29], v[160:163], v[200:203], v[26:29]
	v_mfma_f32_16x16x32_bf16 v[14:17], v[152:155], v[212:215], v[14:17]
	v_mfma_f32_16x16x32_bf16 v[10:13], v[160:163], v[212:215], v[10:13]
	v_mfma_f32_16x16x32_bf16 v[54:57], v[164:167], v[180:183], v[54:57]
	v_mfma_f32_16x16x32_bf16 v[50:53], v[172:175], v[180:183], v[50:53]
	v_mfma_f32_16x16x32_bf16 v[38:41], v[164:167], v[188:191], v[38:41]
	v_mfma_f32_16x16x32_bf16 v[34:37], v[172:175], v[188:191], v[34:37]
	v_mfma_f32_16x16x32_bf16 v[22:25], v[164:167], v[196:199], v[22:25]
	v_mfma_f32_16x16x32_bf16 v[18:21], v[172:175], v[196:199], v[18:21]
	v_mfma_f32_16x16x32_bf16 v[6:9], v[164:167], v[204:207], v[6:9]
	v_mfma_f32_16x16x32_bf16 v[2:5], v[172:175], v[204:207], v[2:5]
	v_mfma_f32_16x16x32_bf16 v[54:57], v[168:171], v[184:187], v[54:57]
	v_mfma_f32_16x16x32_bf16 v[50:53], v[176:179], v[184:187], v[50:53]
	v_mfma_f32_16x16x32_bf16 v[38:41], v[168:171], v[192:195], v[38:41]
	v_mfma_f32_16x16x32_bf16 v[34:37], v[176:179], v[192:195], v[34:37]
	v_mfma_f32_16x16x32_bf16 v[22:25], v[168:171], v[200:203], v[22:25]
	v_mfma_f32_16x16x32_bf16 v[18:21], v[176:179], v[200:203], v[18:21]
	v_mfma_f32_16x16x32_bf16 v[6:9], v[168:171], v[212:215], v[6:9]
	v_mfma_f32_16x16x32_bf16 v[2:5], v[176:179], v[212:215], v[2:5]
	s_setprio 0
	s_barrier
	s_add_i32 s33, 0, 0x18000
	v_add_u32_e32 v151, s33, v149
	s_add_i32 s34, 0, 0x1c000
	ds_read_b128 v[142:145], v151
	ds_read_b128 v[152:155], v151 offset:1024
	ds_read_b128 v[156:159], v151 offset:2048
	ds_read_b128 v[160:163], v151 offset:3072
	v_add_u32_e32 v151, s34, v149
	ds_read_b128 v[164:167], v151
	ds_read_b128 v[168:171], v151 offset:1024
	ds_read_b128 v[172:175], v151 offset:2048
	ds_read_b128 v[176:179], v151 offset:3072
	s_add_u32 s12, s12, s50
	s_addc_u32 s13, s13, s51
	s_mov_b32 m0, s7
	v_lshl_add_u64 v[222:223], s[12:13], 0, v[134:135]
	ds_read_b128 v[180:183], v150 offset:32768
	ds_read_b128 v[184:187], v150 offset:33792
	ds_read_b128 v[188:191], v150 offset:34816
	ds_read_b128 v[192:195], v150 offset:35840
	ds_read_b128 v[196:199], v150 offset:36864
	ds_read_b128 v[200:203], v150 offset:37888
	ds_read_b128 v[204:207], v150 offset:38912
	ds_read_b128 v[212:215], v150 offset:39936
	global_load_lds_dwordx4 v[222:223], off
	v_lshl_add_u64 v[222:223], s[12:13], 0, v[130:131]
	s_mov_b32 m0, s8
	s_nop 0
	global_load_lds_dwordx4 v[222:223], off
	s_waitcnt vmcnt(8)
	s_waitcnt lgkmcnt(0)
	s_barrier
	s_setprio 1
	v_mfma_f32_16x16x32_bf16 v[126:129], v[142:145], v[180:183], v[126:129]
	v_mfma_f32_16x16x32_bf16 v[122:125], v[156:159], v[180:183], v[122:125]
	v_mfma_f32_16x16x32_bf16 v[110:113], v[142:145], v[188:191], v[110:113]
	v_mfma_f32_16x16x32_bf16 v[106:109], v[156:159], v[188:191], v[106:109]
	v_mfma_f32_16x16x32_bf16 v[94:97], v[142:145], v[196:199], v[94:97]
	v_mfma_f32_16x16x32_bf16 v[90:93], v[156:159], v[196:199], v[90:93]
	v_mfma_f32_16x16x32_bf16 v[78:81], v[142:145], v[204:207], v[78:81]
	v_mfma_f32_16x16x32_bf16 v[74:77], v[156:159], v[204:207], v[74:77]
	v_mfma_f32_16x16x32_bf16 v[126:129], v[152:155], v[184:187], v[126:129]
	v_mfma_f32_16x16x32_bf16 v[122:125], v[160:163], v[184:187], v[122:125]
	v_mfma_f32_16x16x32_bf16 v[110:113], v[152:155], v[192:195], v[110:113]
	v_mfma_f32_16x16x32_bf16 v[106:109], v[160:163], v[192:195], v[106:109]
	v_mfma_f32_16x16x32_bf16 v[94:97], v[152:155], v[200:203], v[94:97]
	v_mfma_f32_16x16x32_bf16 v[90:93], v[160:163], v[200:203], v[90:93]
	v_mfma_f32_16x16x32_bf16 v[78:81], v[152:155], v[212:215], v[78:81]
	v_mfma_f32_16x16x32_bf16 v[74:77], v[160:163], v[212:215], v[74:77]
	v_mfma_f32_16x16x32_bf16 v[118:121], v[164:167], v[180:183], v[118:121]
	v_mfma_f32_16x16x32_bf16 v[114:117], v[172:175], v[180:183], v[114:117]
	v_mfma_f32_16x16x32_bf16 v[102:105], v[164:167], v[188:191], v[102:105]
	v_mfma_f32_16x16x32_bf16 v[98:101], v[172:175], v[188:191], v[98:101]
	v_mfma_f32_16x16x32_bf16 v[86:89], v[164:167], v[196:199], v[86:89]
	v_mfma_f32_16x16x32_bf16 v[82:85], v[172:175], v[196:199], v[82:85]
	v_mfma_f32_16x16x32_bf16 v[70:73], v[164:167], v[204:207], v[70:73]
	v_mfma_f32_16x16x32_bf16 v[66:69], v[172:175], v[204:207], v[66:69]
	v_mfma_f32_16x16x32_bf16 v[118:121], v[168:171], v[184:187], v[118:121]
	v_mfma_f32_16x16x32_bf16 v[114:117], v[176:179], v[184:187], v[114:117]
	v_mfma_f32_16x16x32_bf16 v[102:105], v[168:171], v[192:195], v[102:105]
	v_mfma_f32_16x16x32_bf16 v[98:101], v[176:179], v[192:195], v[98:101]
	v_mfma_f32_16x16x32_bf16 v[86:89], v[168:171], v[200:203], v[86:89]
	v_mfma_f32_16x16x32_bf16 v[82:85], v[176:179], v[200:203], v[82:85]
	v_mfma_f32_16x16x32_bf16 v[70:73], v[168:171], v[212:215], v[70:73]
	v_mfma_f32_16x16x32_bf16 v[66:69], v[176:179], v[212:215], v[66:69]
	s_setprio 0
	s_barrier
	s_add_i32 s12, s33, s4
	v_lshl_add_u64 v[146:147], v[146:147], 0, s[28:29]
	s_mov_b32 m0, s12
	ds_read_b128 v[180:183], v150 offset:49152
	ds_read_b128 v[184:187], v150 offset:50176
	ds_read_b128 v[188:191], v150 offset:51200
	ds_read_b128 v[192:195], v150 offset:52224
	ds_read_b128 v[196:199], v150 offset:53248
	ds_read_b128 v[200:203], v150 offset:54272
	ds_read_b128 v[204:207], v150 offset:55296
	ds_read_b128 v[212:215], v150 offset:56320
	global_load_lds_dwordx4 v[146:147], off
	v_lshl_add_u64 v[146:147], v[208:209], 0, s[28:29]
	s_add_i32 m0, s12, 0x2000
	s_add_i32 s12, s34, s4
	global_load_lds_dwordx4 v[146:147], off
	v_lshl_add_u64 v[146:147], v[210:211], 0, s[28:29]
	s_mov_b32 m0, s12
	s_nop 0
	global_load_lds_dwordx4 v[146:147], off
	v_lshl_add_u64 v[146:147], v[216:217], 0, s[28:29]
	s_add_i32 m0, s12, 0x2000
	s_nop 0
	global_load_lds_dwordx4 v[146:147], off
	v_lshl_add_u64 v[146:147], v[218:219], 0, s[28:29]
	s_mov_b32 m0, s9
	s_nop 0
	global_load_lds_dwordx4 v[146:147], off
	v_lshl_add_u64 v[146:147], v[220:221], 0, s[28:29]
	s_mov_b32 m0, s14
	s_nop 0
	global_load_lds_dwordx4 v[146:147], off
	s_waitcnt vmcnt(8)
	s_waitcnt lgkmcnt(0)
	s_barrier
	s_setprio 1
	v_mfma_f32_16x16x32_bf16 v[62:65], v[142:145], v[180:183], v[62:65]
	v_mfma_f32_16x16x32_bf16 v[58:61], v[156:159], v[180:183], v[58:61]
	v_mfma_f32_16x16x32_bf16 v[46:49], v[142:145], v[188:191], v[46:49]
	v_mfma_f32_16x16x32_bf16 v[42:45], v[156:159], v[188:191], v[42:45]
	v_mfma_f32_16x16x32_bf16 v[30:33], v[142:145], v[196:199], v[30:33]
	v_mfma_f32_16x16x32_bf16 v[26:29], v[156:159], v[196:199], v[26:29]
	v_mfma_f32_16x16x32_bf16 v[14:17], v[142:145], v[204:207], v[14:17]
	v_mfma_f32_16x16x32_bf16 v[10:13], v[156:159], v[204:207], v[10:13]
	v_mfma_f32_16x16x32_bf16 v[62:65], v[152:155], v[184:187], v[62:65]
	v_mfma_f32_16x16x32_bf16 v[58:61], v[160:163], v[184:187], v[58:61]
	v_mfma_f32_16x16x32_bf16 v[46:49], v[152:155], v[192:195], v[46:49]
	v_mfma_f32_16x16x32_bf16 v[42:45], v[160:163], v[192:195], v[42:45]
	v_mfma_f32_16x16x32_bf16 v[30:33], v[152:155], v[200:203], v[30:33]
	v_mfma_f32_16x16x32_bf16 v[26:29], v[160:163], v[200:203], v[26:29]
	v_mfma_f32_16x16x32_bf16 v[14:17], v[152:155], v[212:215], v[14:17]
	v_mfma_f32_16x16x32_bf16 v[10:13], v[160:163], v[212:215], v[10:13]
	v_mfma_f32_16x16x32_bf16 v[54:57], v[164:167], v[180:183], v[54:57]
	v_mfma_f32_16x16x32_bf16 v[50:53], v[172:175], v[180:183], v[50:53]
	v_mfma_f32_16x16x32_bf16 v[38:41], v[164:167], v[188:191], v[38:41]
	v_mfma_f32_16x16x32_bf16 v[34:37], v[172:175], v[188:191], v[34:37]
	v_mfma_f32_16x16x32_bf16 v[22:25], v[164:167], v[196:199], v[22:25]
	v_mfma_f32_16x16x32_bf16 v[18:21], v[172:175], v[196:199], v[18:21]
	v_mfma_f32_16x16x32_bf16 v[6:9], v[164:167], v[204:207], v[6:9]
	v_mfma_f32_16x16x32_bf16 v[2:5], v[172:175], v[204:207], v[2:5]
	v_mfma_f32_16x16x32_bf16 v[54:57], v[168:171], v[184:187], v[54:57]
	v_mfma_f32_16x16x32_bf16 v[50:53], v[176:179], v[184:187], v[50:53]
	v_mfma_f32_16x16x32_bf16 v[38:41], v[168:171], v[192:195], v[38:41]
	v_mfma_f32_16x16x32_bf16 v[34:37], v[176:179], v[192:195], v[34:37]
	v_mfma_f32_16x16x32_bf16 v[22:25], v[168:171], v[200:203], v[22:25]
	v_mfma_f32_16x16x32_bf16 v[18:21], v[176:179], v[200:203], v[18:21]
	v_mfma_f32_16x16x32_bf16 v[6:9], v[168:171], v[212:215], v[6:9]
	v_mfma_f32_16x16x32_bf16 v[2:5], v[176:179], v[212:215], v[2:5]
	s_setprio 0
	s_barrier
	s_add_u32 s1, s1, 0x100
	s_addc_u32 s24, s24, 0
	s_add_u32 s10, s10, 0x100
	s_addc_u32 s11, s11, 0
	s_cmp_ge_i32 s25, s18
	s_mov_b32 s12, s25
	s_cbranch_scc0 .LBB0_787

.LBB0_931:
	s_add_i32 s24, s10, 2
	s_add_u32 s25, s0, 0x80
	s_addc_u32 s11, s1, 0
	s_add_i32 s38, 0, 0x10000
	s_cmp_eq_u32 s30, s10
	s_cselect_b32 s11, s91, s11
	s_cselect_b32 s10, s90, s25
	s_cselect_b32 s27, s51, s13
	s_cselect_b32 s26, s50, s12
	s_add_i32 s25, 0, 0x14000
	v_add_u32_e32 v142, s38, v201
	v_add_u32_e32 v158, s25, v201
	ds_read_b128 v[130:133], v142
	ds_read_b128 v[134:137], v142 offset:1024
	ds_read_b128 v[138:141], v142 offset:2048
	ds_read_b128 v[142:145], v142 offset:3072
	ds_read_b128 v[146:149], v158
	ds_read_b128 v[150:153], v158 offset:1024
	ds_read_b128 v[154:157], v158 offset:2048
	ds_read_b128 v[158:161], v158 offset:3072
	v_lshl_add_u64 v[198:199], s[0:1], 0, v[186:187]
	s_add_i32 m0, s7, 0xc000
	ds_read_b128 v[162:165], v202
	ds_read_b128 v[166:169], v202 offset:1024
	ds_read_b128 v[170:173], v202 offset:2048
	ds_read_b128 v[174:177], v202 offset:3072
	ds_read_b128 v[190:193], v202 offset:4096
	ds_read_b128 v[194:197], v202 offset:5120
	ds_read_b128 v[204:207], v202 offset:6144
	ds_read_b128 v[212:215], v202 offset:7168
	global_load_lds_dwordx4 v[198:199], off
	v_lshl_add_u64 v[198:199], s[0:1], 0, v[188:189]
	s_add_i32 m0, s7, 0xe000
	s_nop 0
	global_load_lds_dwordx4 v[198:199], off
	s_waitcnt vmcnt(8)
	s_waitcnt lgkmcnt(0)
	s_barrier
	s_setprio 1
	v_mfma_f32_16x16x32_bf16 v[94:97], v[130:133], v[162:165], v[94:97]
	v_mfma_f32_16x16x32_bf16 v[30:33], v[138:141], v[162:165], v[30:33]
	v_mfma_f32_16x16x32_bf16 v[82:85], v[130:133], v[170:173], v[82:85]
	v_mfma_f32_16x16x32_bf16 v[22:25], v[138:141], v[170:173], v[22:25]
	v_mfma_f32_16x16x32_bf16 v[114:117], v[130:133], v[190:193], v[114:117]
	v_mfma_f32_16x16x32_bf16 v[42:45], v[138:141], v[190:193], v[42:45]
	v_mfma_f32_16x16x32_bf16 v[122:125], v[130:133], v[204:207], v[122:125]
	v_mfma_f32_16x16x32_bf16 v[58:61], v[138:141], v[204:207], v[58:61]
	v_mfma_f32_16x16x32_bf16 v[94:97], v[134:137], v[166:169], v[94:97]
	v_mfma_f32_16x16x32_bf16 v[30:33], v[142:145], v[166:169], v[30:33]
	v_mfma_f32_16x16x32_bf16 v[82:85], v[134:137], v[174:177], v[82:85]
	v_mfma_f32_16x16x32_bf16 v[22:25], v[142:145], v[174:177], v[22:25]
	v_mfma_f32_16x16x32_bf16 v[114:117], v[134:137], v[194:197], v[114:117]
	v_mfma_f32_16x16x32_bf16 v[42:45], v[142:145], v[194:197], v[42:45]
	v_mfma_f32_16x16x32_bf16 v[122:125], v[134:137], v[212:215], v[122:125]
	v_mfma_f32_16x16x32_bf16 v[58:61], v[142:145], v[212:215], v[58:61]
	v_mfma_f32_16x16x32_bf16 v[90:93], v[146:149], v[162:165], v[90:93]
	v_mfma_f32_16x16x32_bf16 v[26:29], v[154:157], v[162:165], v[26:29]
	v_mfma_f32_16x16x32_bf16 v[78:81], v[146:149], v[170:173], v[78:81]
	v_mfma_f32_16x16x32_bf16 v[18:21], v[154:157], v[170:173], v[18:21]
	v_mfma_f32_16x16x32_bf16 v[118:121], v[146:149], v[190:193], v[118:121]
	v_mfma_f32_16x16x32_bf16 v[54:57], v[154:157], v[190:193], v[54:57]
	v_mfma_f32_16x16x32_bf16 v[126:129], v[146:149], v[204:207], v[126:129]
	v_mfma_f32_16x16x32_bf16 v[62:65], v[154:157], v[204:207], v[62:65]
	v_mfma_f32_16x16x32_bf16 v[90:93], v[150:153], v[166:169], v[90:93]
	v_mfma_f32_16x16x32_bf16 v[26:29], v[158:161], v[166:169], v[26:29]
	v_mfma_f32_16x16x32_bf16 v[78:81], v[150:153], v[174:177], v[78:81]
	v_mfma_f32_16x16x32_bf16 v[18:21], v[158:161], v[174:177], v[18:21]
	v_mfma_f32_16x16x32_bf16 v[118:121], v[150:153], v[194:197], v[118:121]
	v_mfma_f32_16x16x32_bf16 v[54:57], v[158:161], v[194:197], v[54:57]
	v_mfma_f32_16x16x32_bf16 v[126:129], v[150:153], v[212:215], v[126:129]
	v_mfma_f32_16x16x32_bf16 v[62:65], v[158:161], v[212:215], v[62:65]
	s_setprio 0
	s_barrier
	s_add_i32 s38, s38, s6
	v_lshl_add_u64 v[198:199], s[26:27], 0, v[178:179]
	s_mov_b32 m0, s38
	ds_read_b128 v[162:165], v202 offset:16384
	ds_read_b128 v[166:169], v202 offset:17408
	ds_read_b128 v[170:173], v202 offset:18432
	ds_read_b128 v[174:177], v202 offset:19456
	ds_read_b128 v[190:193], v202 offset:20480
	ds_read_b128 v[194:197], v202 offset:21504
	ds_read_b128 v[204:207], v202 offset:22528
	ds_read_b128 v[212:215], v202 offset:23552
	global_load_lds_dwordx4 v[198:199], off
	s_add_i32 m0, s38, 0x2000
	v_lshl_add_u64 v[208:209], s[26:27], 0, v[182:183]
	s_add_u32 s26, s26, s56
	s_addc_u32 s27, s27, s57
	s_add_i32 s25, s25, s6
	global_load_lds_dwordx4 v[208:209], off
	v_lshl_add_u64 v[210:211], s[26:27], 0, v[178:179]
	s_mov_b32 m0, s25
	v_lshl_add_u64 v[216:217], s[26:27], 0, v[182:183]
	global_load_lds_dwordx4 v[210:211], off
	s_add_i32 m0, s25, 0x2000
	v_lshl_add_u64 v[218:219], s[10:11], 0, v[180:181]
	global_load_lds_dwordx4 v[216:217], off
	s_mov_b32 m0, s7
	v_lshl_add_u64 v[220:221], s[10:11], 0, v[184:185]
	global_load_lds_dwordx4 v[218:219], off
	s_mov_b32 m0, s36
	s_nop 0
	global_load_lds_dwordx4 v[220:221], off
	s_waitcnt vmcnt(8)
	s_waitcnt lgkmcnt(0)
	s_barrier
	s_setprio 1
	v_mfma_f32_16x16x32_bf16 v[70:73], v[130:133], v[162:165], v[70:73]
	v_mfma_f32_16x16x32_bf16 v[14:17], v[138:141], v[162:165], v[14:17]
	v_mfma_f32_16x16x32_bf16 v[50:53], v[130:133], v[170:173], v[50:53]
	v_mfma_f32_16x16x32_bf16 v[6:9], v[138:141], v[170:173], v[6:9]
	v_mfma_f32_16x16x32_bf16 v[106:109], v[130:133], v[190:193], v[106:109]
	v_mfma_f32_16x16x32_bf16 v[34:37], v[138:141], v[190:193], v[34:37]
	v_mfma_f32_16x16x32_bf16 v[102:105], v[130:133], v[204:207], v[102:105]
	v_mfma_f32_16x16x32_bf16 v[74:77], v[138:141], v[204:207], v[74:77]
	v_mfma_f32_16x16x32_bf16 v[70:73], v[134:137], v[166:169], v[70:73]
	v_mfma_f32_16x16x32_bf16 v[14:17], v[142:145], v[166:169], v[14:17]
	v_mfma_f32_16x16x32_bf16 v[50:53], v[134:137], v[174:177], v[50:53]
	v_mfma_f32_16x16x32_bf16 v[6:9], v[142:145], v[174:177], v[6:9]
	v_mfma_f32_16x16x32_bf16 v[106:109], v[134:137], v[194:197], v[106:109]
	v_mfma_f32_16x16x32_bf16 v[34:37], v[142:145], v[194:197], v[34:37]
	v_mfma_f32_16x16x32_bf16 v[102:105], v[134:137], v[212:215], v[102:105]
	v_mfma_f32_16x16x32_bf16 v[74:77], v[142:145], v[212:215], v[74:77]
	v_mfma_f32_16x16x32_bf16 v[66:69], v[146:149], v[162:165], v[66:69]
	v_mfma_f32_16x16x32_bf16 v[10:13], v[154:157], v[162:165], v[10:13]
	v_mfma_f32_16x16x32_bf16 v[46:49], v[146:149], v[170:173], v[46:49]
	v_mfma_f32_16x16x32_bf16 v[2:5], v[154:157], v[170:173], v[2:5]
	v_mfma_f32_16x16x32_bf16 v[110:113], v[146:149], v[190:193], v[110:113]
	v_mfma_f32_16x16x32_bf16 v[38:41], v[154:157], v[190:193], v[38:41]
	v_mfma_f32_16x16x32_bf16 v[98:101], v[146:149], v[204:207], v[98:101]
	v_mfma_f32_16x16x32_bf16 v[86:89], v[154:157], v[204:207], v[86:89]
	v_mfma_f32_16x16x32_bf16 v[66:69], v[150:153], v[166:169], v[66:69]
	v_mfma_f32_16x16x32_bf16 v[10:13], v[158:161], v[166:169], v[10:13]
	v_mfma_f32_16x16x32_bf16 v[46:49], v[150:153], v[174:177], v[46:49]
	v_mfma_f32_16x16x32_bf16 v[2:5], v[158:161], v[174:177], v[2:5]
	v_mfma_f32_16x16x32_bf16 v[110:113], v[150:153], v[194:197], v[110:113]
	v_mfma_f32_16x16x32_bf16 v[38:41], v[158:161], v[194:197], v[38:41]
	v_mfma_f32_16x16x32_bf16 v[98:101], v[150:153], v[212:215], v[98:101]
	v_mfma_f32_16x16x32_bf16 v[86:89], v[158:161], v[212:215], v[86:89]
	s_setprio 0
	s_barrier
	s_add_i32 s25, 0, 0x18000
	s_add_i32 s26, 0, 0x1c000
	v_add_u32_e32 v142, s25, v201
	v_add_u32_e32 v158, s26, v201
	ds_read_b128 v[130:133], v142
	ds_read_b128 v[134:137], v142 offset:1024
	ds_read_b128 v[138:141], v142 offset:2048
	ds_read_b128 v[142:145], v142 offset:3072
	ds_read_b128 v[146:149], v158
	ds_read_b128 v[150:153], v158 offset:1024
	ds_read_b128 v[154:157], v158 offset:2048
	ds_read_b128 v[158:161], v158 offset:3072
	s_add_u32 s10, s10, s56
	s_addc_u32 s11, s11, s57
	s_mov_b32 m0, s96
	v_lshl_add_u64 v[222:223], s[10:11], 0, v[180:181]
	ds_read_b128 v[162:165], v202 offset:32768
	ds_read_b128 v[166:169], v202 offset:33792
	ds_read_b128 v[170:173], v202 offset:34816
	ds_read_b128 v[174:177], v202 offset:35840
	ds_read_b128 v[190:193], v202 offset:36864
	ds_read_b128 v[194:197], v202 offset:37888
	ds_read_b128 v[204:207], v202 offset:38912
	ds_read_b128 v[212:215], v202 offset:39936
	global_load_lds_dwordx4 v[222:223], off
	v_lshl_add_u64 v[222:223], s[10:11], 0, v[184:185]
	s_mov_b32 m0, s97
	s_nop 0
	global_load_lds_dwordx4 v[222:223], off
	s_waitcnt vmcnt(8)
	s_waitcnt lgkmcnt(0)
	s_barrier
	s_setprio 1
	v_mfma_f32_16x16x32_bf16 v[94:97], v[130:133], v[162:165], v[94:97]
	v_mfma_f32_16x16x32_bf16 v[30:33], v[138:141], v[162:165], v[30:33]
	v_mfma_f32_16x16x32_bf16 v[82:85], v[130:133], v[170:173], v[82:85]
	v_mfma_f32_16x16x32_bf16 v[22:25], v[138:141], v[170:173], v[22:25]
	v_mfma_f32_16x16x32_bf16 v[114:117], v[130:133], v[190:193], v[114:117]
	v_mfma_f32_16x16x32_bf16 v[42:45], v[138:141], v[190:193], v[42:45]
	v_mfma_f32_16x16x32_bf16 v[122:125], v[130:133], v[204:207], v[122:125]
	v_mfma_f32_16x16x32_bf16 v[58:61], v[138:141], v[204:207], v[58:61]
	v_mfma_f32_16x16x32_bf16 v[94:97], v[134:137], v[166:169], v[94:97]
	v_mfma_f32_16x16x32_bf16 v[30:33], v[142:145], v[166:169], v[30:33]
	v_mfma_f32_16x16x32_bf16 v[82:85], v[134:137], v[174:177], v[82:85]
	v_mfma_f32_16x16x32_bf16 v[22:25], v[142:145], v[174:177], v[22:25]
	v_mfma_f32_16x16x32_bf16 v[114:117], v[134:137], v[194:197], v[114:117]
	v_mfma_f32_16x16x32_bf16 v[42:45], v[142:145], v[194:197], v[42:45]
	v_mfma_f32_16x16x32_bf16 v[122:125], v[134:137], v[212:215], v[122:125]
	v_mfma_f32_16x16x32_bf16 v[58:61], v[142:145], v[212:215], v[58:61]
	v_mfma_f32_16x16x32_bf16 v[90:93], v[146:149], v[162:165], v[90:93]
	v_mfma_f32_16x16x32_bf16 v[26:29], v[154:157], v[162:165], v[26:29]
	v_mfma_f32_16x16x32_bf16 v[78:81], v[146:149], v[170:173], v[78:81]
	v_mfma_f32_16x16x32_bf16 v[18:21], v[154:157], v[170:173], v[18:21]
	v_mfma_f32_16x16x32_bf16 v[118:121], v[146:149], v[190:193], v[118:121]
	v_mfma_f32_16x16x32_bf16 v[54:57], v[154:157], v[190:193], v[54:57]
	v_mfma_f32_16x16x32_bf16 v[126:129], v[146:149], v[204:207], v[126:129]
	v_mfma_f32_16x16x32_bf16 v[62:65], v[154:157], v[204:207], v[62:65]
	v_mfma_f32_16x16x32_bf16 v[90:93], v[150:153], v[166:169], v[90:93]
	v_mfma_f32_16x16x32_bf16 v[26:29], v[158:161], v[166:169], v[26:29]
	v_mfma_f32_16x16x32_bf16 v[78:81], v[150:153], v[174:177], v[78:81]
	v_mfma_f32_16x16x32_bf16 v[18:21], v[158:161], v[174:177], v[18:21]
	v_mfma_f32_16x16x32_bf16 v[118:121], v[150:153], v[194:197], v[118:121]
	v_mfma_f32_16x16x32_bf16 v[54:57], v[158:161], v[194:197], v[54:57]
	v_mfma_f32_16x16x32_bf16 v[126:129], v[150:153], v[212:215], v[126:129]
	v_mfma_f32_16x16x32_bf16 v[62:65], v[158:161], v[212:215], v[62:65]
	s_setprio 0
	s_barrier
	s_add_i32 s10, s25, s6
	v_lshl_add_u64 v[198:199], v[198:199], 0, s[28:29]
	s_mov_b32 m0, s10
	ds_read_b128 v[162:165], v202 offset:49152
	ds_read_b128 v[166:169], v202 offset:50176
	ds_read_b128 v[170:173], v202 offset:51200
	ds_read_b128 v[174:177], v202 offset:52224
	ds_read_b128 v[190:193], v202 offset:53248
	ds_read_b128 v[194:197], v202 offset:54272
	ds_read_b128 v[204:207], v202 offset:55296
	ds_read_b128 v[212:215], v202 offset:56320
	global_load_lds_dwordx4 v[198:199], off
	v_lshl_add_u64 v[198:199], v[208:209], 0, s[28:29]
	s_add_i32 m0, s10, 0x2000
	s_add_i32 s10, s26, s6
	global_load_lds_dwordx4 v[198:199], off
	v_lshl_add_u64 v[198:199], v[210:211], 0, s[28:29]
	s_mov_b32 m0, s10
	s_nop 0
	global_load_lds_dwordx4 v[198:199], off
	v_lshl_add_u64 v[198:199], v[216:217], 0, s[28:29]
	s_add_i32 m0, s10, 0x2000
	s_nop 0
	global_load_lds_dwordx4 v[198:199], off
	v_lshl_add_u64 v[198:199], v[218:219], 0, s[28:29]
	s_mov_b32 m0, s18
	s_nop 0
	global_load_lds_dwordx4 v[198:199], off
	v_lshl_add_u64 v[198:199], v[220:221], 0, s[28:29]
	s_mov_b32 m0, s19
	s_nop 0
	global_load_lds_dwordx4 v[198:199], off
	s_waitcnt vmcnt(8)
	s_waitcnt lgkmcnt(0)
	s_barrier
	s_setprio 1
	v_mfma_f32_16x16x32_bf16 v[70:73], v[130:133], v[162:165], v[70:73]
	v_mfma_f32_16x16x32_bf16 v[14:17], v[138:141], v[162:165], v[14:17]
	v_mfma_f32_16x16x32_bf16 v[50:53], v[130:133], v[170:173], v[50:53]
	v_mfma_f32_16x16x32_bf16 v[6:9], v[138:141], v[170:173], v[6:9]
	v_mfma_f32_16x16x32_bf16 v[106:109], v[130:133], v[190:193], v[106:109]
	v_mfma_f32_16x16x32_bf16 v[34:37], v[138:141], v[190:193], v[34:37]
	v_mfma_f32_16x16x32_bf16 v[102:105], v[130:133], v[204:207], v[102:105]
	v_mfma_f32_16x16x32_bf16 v[74:77], v[138:141], v[204:207], v[74:77]
	v_mfma_f32_16x16x32_bf16 v[70:73], v[134:137], v[166:169], v[70:73]
	v_mfma_f32_16x16x32_bf16 v[14:17], v[142:145], v[166:169], v[14:17]
	v_mfma_f32_16x16x32_bf16 v[50:53], v[134:137], v[174:177], v[50:53]
	v_mfma_f32_16x16x32_bf16 v[6:9], v[142:145], v[174:177], v[6:9]
	v_mfma_f32_16x16x32_bf16 v[106:109], v[134:137], v[194:197], v[106:109]
	v_mfma_f32_16x16x32_bf16 v[34:37], v[142:145], v[194:197], v[34:37]
	v_mfma_f32_16x16x32_bf16 v[102:105], v[134:137], v[212:215], v[102:105]
	v_mfma_f32_16x16x32_bf16 v[74:77], v[142:145], v[212:215], v[74:77]
	v_mfma_f32_16x16x32_bf16 v[66:69], v[146:149], v[162:165], v[66:69]
	v_mfma_f32_16x16x32_bf16 v[10:13], v[154:157], v[162:165], v[10:13]
	v_mfma_f32_16x16x32_bf16 v[46:49], v[146:149], v[170:173], v[46:49]
	v_mfma_f32_16x16x32_bf16 v[2:5], v[154:157], v[170:173], v[2:5]
	v_mfma_f32_16x16x32_bf16 v[110:113], v[146:149], v[190:193], v[110:113]
	v_mfma_f32_16x16x32_bf16 v[38:41], v[154:157], v[190:193], v[38:41]
	v_mfma_f32_16x16x32_bf16 v[98:101], v[146:149], v[204:207], v[98:101]
	v_mfma_f32_16x16x32_bf16 v[86:89], v[154:157], v[204:207], v[86:89]
	v_mfma_f32_16x16x32_bf16 v[66:69], v[150:153], v[166:169], v[66:69]
	v_mfma_f32_16x16x32_bf16 v[10:13], v[158:161], v[166:169], v[10:13]
	v_mfma_f32_16x16x32_bf16 v[46:49], v[150:153], v[174:177], v[46:49]
	v_mfma_f32_16x16x32_bf16 v[2:5], v[158:161], v[174:177], v[2:5]
	v_mfma_f32_16x16x32_bf16 v[110:113], v[150:153], v[194:197], v[110:113]
	v_mfma_f32_16x16x32_bf16 v[38:41], v[158:161], v[194:197], v[38:41]
	v_mfma_f32_16x16x32_bf16 v[98:101], v[150:153], v[212:215], v[98:101]
	v_mfma_f32_16x16x32_bf16 v[86:89], v[158:161], v[212:215], v[86:89]
	s_setprio 0
	s_barrier
	s_add_u32 s12, s12, 0x100
	s_addc_u32 s13, s13, 0
	s_add_u32 s0, s0, 0x100
	s_addc_u32 s1, s1, 0
	s_cmp_ge_i32 s24, s8
	s_mov_b32 s10, s24
	s_cbranch_scc0 .LBB0_931

.LBB0_934:
	s_mul_hi_i32 s0, s31, 0x78787879
	s_lshr_b32 s1, s0, 31
	s_ashr_i32 s0, s0, 3
	s_add_i32 s0, s0, s1
	s_mul_i32 s1, s0, 17
	v_mov_b32_e32 v136, v200
	v_mov_b32_e32 v203, v1
	s_sub_i32 s12, s31, s1
	s_mul_i32 s31, s12, 0xfe
	v_lshlrev_b32_e32 v130, 2, v203
	v_readlane_b32 s1, v254, 58
	s_add_i32 s31, s31, -2
	v_mov_b32_e32 v144, 0xfff
	v_add_u32_e32 v199, s1, v130
	v_add_u32_e32 v190, s31, v199
	v_lshl_add_u32 v130, v136, 6, v130
	s_lshl_b32 s1, s0, 12
	v_xor_b32_e32 v138, 64, v130
	v_xor_b32_e32 v137, 0x80, v130
	v_med3_i32 v130, v190, 0, v144
	v_or_b32_e32 v130, s1, v130
	v_lshlrev_b32_e32 v134, 2, v136
	v_ashrrev_i32_e32 v131, 31, v130
	v_readlane_b32 s24, v254, 45
	v_ashrrev_i32_e32 v135, 31, v134
	v_lshlrev_b64 v[130:131], 6, v[130:131]
	v_readlane_b32 s25, v254, 46
	s_nop 1
	v_lshl_add_u64 v[132:133], s[24:25], 0, v[130:131]
	v_lshlrev_b64 v[130:131], 2, v[134:135]
	v_lshl_add_u64 v[132:133], v[132:133], 0, v[130:131]
	global_load_dwordx4 v[146:149], v[132:133], off
	v_or_b32_e32 v192, 1, v190
	v_med3_i32 v192, v192, 0, v144
	v_or_b32_e32 v192, s1, v192
	v_ashrrev_i32_e32 v193, 31, v192
	v_lshlrev_b64 v[192:193], 6, v[192:193]
	v_lshl_add_u64 v[192:193], s[24:25], 0, v[192:193]
	v_lshl_add_u64 v[192:193], v[192:193], 0, v[130:131]
	global_load_dwordx4 v[150:153], v[192:193], off
	v_max_i32_e32 v192, -2, v190
	v_add_u32_e32 v192, 2, v192
	v_min_u32_e32 v192, 0xfff, v192
	v_or_b32_e32 v192, s1, v192
	v_ashrrev_i32_e32 v193, 31, v192
	v_lshlrev_b64 v[192:193], 6, v[192:193]
	v_lshl_add_u64 v[192:193], s[24:25], 0, v[192:193]
	v_lshl_add_u64 v[192:193], v[192:193], 0, v[130:131]
	global_load_dwordx4 v[154:157], v[192:193], off
	v_max_i32_e32 v192, -3, v190
	v_add_u32_e32 v192, 3, v192
	v_min_u32_e32 v192, 0xfff, v192
	v_or_b32_e32 v192, s1, v192
	v_ashrrev_i32_e32 v193, 31, v192
	v_lshlrev_b64 v[192:193], 6, v[192:193]
	v_lshl_add_u64 v[192:193], s[24:25], 0, v[192:193]
	v_lshl_add_u64 v[192:193], v[192:193], 0, v[130:131]
	global_load_dwordx4 v[158:161], v[192:193], off
	v_add_u32_e32 v192, 0x80, v190
	v_med3_i32 v192, v192, 0, v144
	v_or_b32_e32 v192, s1, v192
	v_ashrrev_i32_e32 v193, 31, v192
	v_lshlrev_b64 v[192:193], 6, v[192:193]
	v_lshl_add_u64 v[192:193], s[24:25], 0, v[192:193]
	v_lshl_add_u64 v[192:193], v[192:193], 0, v[130:131]
	global_load_dwordx4 v[162:165], v[192:193], off
	v_add_u32_e32 v192, 0x81, v190
	v_med3_i32 v192, v192, 0, v144
	v_or_b32_e32 v192, s1, v192
	v_ashrrev_i32_e32 v193, 31, v192
	v_lshlrev_b64 v[192:193], 6, v[192:193]
	v_lshl_add_u64 v[192:193], s[24:25], 0, v[192:193]
	v_lshl_add_u64 v[192:193], v[192:193], 0, v[130:131]
	global_load_dwordx4 v[166:169], v[192:193], off
	v_add_u32_e32 v192, 0x82, v190
	v_med3_i32 v192, v192, 0, v144
	v_or_b32_e32 v192, s1, v192
	v_ashrrev_i32_e32 v193, 31, v192
	v_lshlrev_b64 v[192:193], 6, v[192:193]
	v_lshl_add_u64 v[192:193], s[24:25], 0, v[192:193]
	v_lshl_add_u64 v[192:193], v[192:193], 0, v[130:131]
	global_load_dwordx4 v[170:173], v[192:193], off
	v_add_u32_e32 v192, 0x83, v190
	v_med3_i32 v192, v192, 0, v144
	v_or_b32_e32 v192, s1, v192
	v_ashrrev_i32_e32 v193, 31, v192
	v_lshlrev_b64 v[192:193], 6, v[192:193]
	v_lshl_add_u64 v[192:193], s[24:25], 0, v[192:193]
	v_lshl_add_u64 v[192:193], v[192:193], 0, v[130:131]
	global_load_dwordx4 v[174:177], v[192:193], off
	s_waitcnt vmcnt(7)
	v_mov_b64_e32 v[140:141], v[146:147]
	v_mov_b64_e32 v[142:143], v[148:149]
	v_mov_b32_e32 v132, v141
	v_mov_b32_e32 v133, v142
	v_mov_b32_e32 v141, v143
	v_pk_add_f32 v[132:133], v[132:133], v[140:141]
	s_nop 0
	v_add_f32_e32 v132, v132, v133
	ds_bpermute_b32 v133, v138, v132
	s_waitcnt lgkmcnt(0)
	v_add_f32_e32 v191, v132, v133
	ds_bpermute_b32 v198, v137, v191
	s_waitcnt vmcnt(6)
	v_mov_b64_e32 v[140:141], v[150:151]
	v_mov_b64_e32 v[142:143], v[152:153]
	v_mov_b32_e32 v132, v141
	v_mov_b32_e32 v133, v142
	v_mov_b32_e32 v141, v143
	v_pk_add_f32 v[132:133], v[132:133], v[140:141]
	s_nop 0
	v_add_f32_e32 v132, v132, v133
	ds_bpermute_b32 v133, v138, v132
	s_waitcnt lgkmcnt(0)
	v_add_f32_e32 v208, v132, v133
	ds_bpermute_b32 v209, v137, v208
	s_waitcnt vmcnt(5)
	v_mov_b64_e32 v[140:141], v[154:155]
	v_mov_b64_e32 v[142:143], v[156:157]
	v_mov_b32_e32 v132, v141
	v_mov_b32_e32 v133, v142
	v_mov_b32_e32 v141, v143
	v_pk_add_f32 v[132:133], v[132:133], v[140:141]
	s_nop 0
	v_add_f32_e32 v132, v132, v133
	ds_bpermute_b32 v133, v138, v132
	s_waitcnt lgkmcnt(0)
	v_add_f32_e32 v132, v132, v133
	ds_bpermute_b32 v133, v137, v132
	s_waitcnt lgkmcnt(0)
	v_add_f32_e32 v132, v132, v133
	v_fmamk_f32 v132, v132, 0x3a800000, v243
	v_rsq_f32_e32 v132, v132
	s_nop 0
	v_pk_mul_f32 v[116:117], v[116:117], v[132:133] op_sel_hi:[1,0]
	v_pk_mul_f32 v[114:115], v[114:115], v[132:133] op_sel_hi:[1,0]
	v_pk_mul_f32 v[44:45], v[44:45], v[132:133] op_sel_hi:[1,0]
	v_pk_mul_f32 v[42:43], v[42:43], v[132:133] op_sel_hi:[1,0]
	v_pk_mul_f32 v[120:121], v[120:121], v[132:133] op_sel_hi:[1,0]
	v_pk_mul_f32 v[118:119], v[118:119], v[132:133] op_sel_hi:[1,0]
	v_pk_mul_f32 v[56:57], v[56:57], v[132:133] op_sel_hi:[1,0]
	v_pk_mul_f32 v[54:55], v[54:55], v[132:133] op_sel_hi:[1,0]
	s_waitcnt vmcnt(4)
	v_mov_b64_e32 v[140:141], v[158:159]
	v_mov_b64_e32 v[142:143], v[160:161]
	v_mov_b32_e32 v132, v141
	v_mov_b32_e32 v133, v142
	v_mov_b32_e32 v141, v143
	v_pk_add_f32 v[132:133], v[132:133], v[140:141]
	s_nop 0
	v_add_f32_e32 v132, v132, v133
	ds_bpermute_b32 v133, v138, v132
	s_waitcnt lgkmcnt(0)
	v_add_f32_e32 v132, v132, v133
	ds_bpermute_b32 v133, v137, v132
	s_waitcnt lgkmcnt(0)
	v_add_f32_e32 v132, v132, v133
	v_fmamk_f32 v132, v132, 0x3a800000, v243
	v_rsq_f32_e32 v132, v132
	s_nop 0
	v_pk_mul_f32 v[124:125], v[124:125], v[132:133] op_sel_hi:[1,0]
	v_pk_mul_f32 v[122:123], v[122:123], v[132:133] op_sel_hi:[1,0]
	v_pk_mul_f32 v[60:61], v[60:61], v[132:133] op_sel_hi:[1,0]
	v_pk_mul_f32 v[58:59], v[58:59], v[132:133] op_sel_hi:[1,0]
	v_pk_mul_f32 v[128:129], v[128:129], v[132:133] op_sel_hi:[1,0]
	v_pk_mul_f32 v[126:127], v[126:127], v[132:133] op_sel_hi:[1,0]
	v_pk_mul_f32 v[64:65], v[64:65], v[132:133] op_sel_hi:[1,0]
	v_pk_mul_f32 v[62:63], v[62:63], v[132:133] op_sel_hi:[1,0]
	s_waitcnt vmcnt(3)
	v_mov_b64_e32 v[140:141], v[162:163]
	v_mov_b64_e32 v[142:143], v[164:165]
	v_mov_b32_e32 v132, v141
	v_mov_b32_e32 v133, v142
	v_mov_b32_e32 v141, v143
	v_pk_add_f32 v[132:133], v[132:133], v[140:141]
	s_nop 0
	v_add_f32_e32 v132, v132, v133
	ds_bpermute_b32 v133, v138, v132
	s_waitcnt lgkmcnt(0)
	v_add_f32_e32 v206, v132, v133
	ds_bpermute_b32 v207, v137, v206
	s_waitcnt vmcnt(2)
	v_mov_b64_e32 v[140:141], v[166:167]
	v_mov_b64_e32 v[142:143], v[168:169]
	v_mov_b32_e32 v132, v141
	v_mov_b32_e32 v133, v142
	v_mov_b32_e32 v141, v143
	v_pk_add_f32 v[132:133], v[132:133], v[140:141]
	s_nop 0
	v_add_f32_e32 v132, v132, v133
	ds_bpermute_b32 v133, v138, v132
	s_waitcnt lgkmcnt(0)
	v_add_f32_e32 v204, v132, v133
	ds_bpermute_b32 v205, v137, v204
	s_waitcnt vmcnt(1)
	v_mov_b64_e32 v[140:141], v[170:171]
	v_mov_b64_e32 v[142:143], v[172:173]
	v_mov_b32_e32 v132, v141
	v_mov_b32_e32 v133, v142
	v_mov_b32_e32 v141, v143
	v_pk_add_f32 v[132:133], v[132:133], v[140:141]
	s_nop 0
	v_add_f32_e32 v132, v132, v133
	ds_bpermute_b32 v133, v138, v132
	s_waitcnt lgkmcnt(0)
	v_add_f32_e32 v132, v132, v133
	ds_bpermute_b32 v133, v137, v132
	s_waitcnt lgkmcnt(0)
	v_add_f32_e32 v132, v132, v133
	v_fmamk_f32 v132, v132, 0x3a800000, v243
	v_rsq_f32_e32 v132, v132
	s_nop 0
	v_pk_mul_f32 v[108:109], v[108:109], v[132:133] op_sel_hi:[1,0]
	v_pk_mul_f32 v[106:107], v[106:107], v[132:133] op_sel_hi:[1,0]
	v_pk_mul_f32 v[36:37], v[36:37], v[132:133] op_sel_hi:[1,0]
	v_pk_mul_f32 v[34:35], v[34:35], v[132:133] op_sel_hi:[1,0]
	v_pk_mul_f32 v[112:113], v[112:113], v[132:133] op_sel_hi:[1,0]
	v_pk_mul_f32 v[110:111], v[110:111], v[132:133] op_sel_hi:[1,0]
	v_pk_mul_f32 v[40:41], v[40:41], v[132:133] op_sel_hi:[1,0]
	v_pk_mul_f32 v[38:39], v[38:39], v[132:133] op_sel_hi:[1,0]
	s_waitcnt vmcnt(0)
	v_mov_b64_e32 v[130:131], v[174:175]
	v_mov_b64_e32 v[132:133], v[176:177]
	v_mov_b32_e32 v140, v131
	v_mov_b32_e32 v141, v132
	v_mov_b32_e32 v131, v133
	v_pk_add_f32 v[130:131], v[140:141], v[130:131]
	s_nop 0
	v_add_f32_e32 v130, v130, v131
	ds_bpermute_b32 v131, v138, v130
	s_waitcnt lgkmcnt(0)
	v_add_f32_e32 v130, v130, v131
	ds_bpermute_b32 v131, v137, v130
	s_waitcnt lgkmcnt(0)
	v_add_f32_e32 v130, v130, v131
	v_fmamk_f32 v130, v130, 0x3a800000, v243
	v_rsq_f32_e32 v130, v130
	s_nop 0
	v_pk_mul_f32 v[104:105], v[104:105], v[130:131] op_sel_hi:[1,0]
	v_pk_mul_f32 v[102:103], v[102:103], v[130:131] op_sel_hi:[1,0]
	v_pk_mul_f32 v[76:77], v[76:77], v[130:131] op_sel_hi:[1,0]
	v_pk_mul_f32 v[74:75], v[74:75], v[130:131] op_sel_hi:[1,0]
	v_pk_mul_f32 v[100:101], v[100:101], v[130:131] op_sel_hi:[1,0]
	v_pk_mul_f32 v[98:99], v[98:99], v[130:131] op_sel_hi:[1,0]
	v_pk_mul_f32 v[88:89], v[88:89], v[130:131] op_sel_hi:[1,0]
	v_pk_mul_f32 v[86:87], v[86:87], v[130:131] op_sel_hi:[1,0]
	v_cmp_eq_u32_e32 vcc, 15, v203
	s_and_saveexec_b64 s[10:11], vcc
	s_cbranch_execz .LBB0_936
	v_lshlrev_b32_e32 v130, 4, v136
	v_readlane_b32 s1, v255, 5
	s_nop 1
	v_add_u32_e32 v131, s1, v130
	v_readlane_b32 s1, v255, 6
	ds_write_b128 v131, v[114:117]
	ds_write_b128 v131, v[122:125] offset:1024
	ds_write_b128 v131, v[42:45] offset:64
	ds_write_b128 v131, v[58:61] offset:1088
	ds_write_b128 v131, v[118:121] offset:512
	ds_write_b128 v131, v[126:129] offset:1536
	ds_write_b128 v131, v[54:57] offset:576
	ds_write_b128 v131, v[62:65] offset:1600
	v_add_u32_e32 v130, s1, v130
	ds_write_b128 v130, v[106:109]
	ds_write_b128 v130, v[102:105] offset:1024
	ds_write_b128 v131, v[34:37] offset:4160
	ds_write_b128 v131, v[74:77] offset:5184
	ds_write_b128 v131, v[110:113] offset:4608
	ds_write_b128 v131, v[98:101] offset:5632
	ds_write_b128 v131, v[38:41] offset:4672
	ds_write_b128 v131, v[86:89] offset:5696

.LBB0_1062:
	s_add_i32 s25, s12, 2
	s_add_u32 s33, s10, 0x80
	s_addc_u32 s13, s11, 0
	s_add_i32 s36, 0, 0x10000
	s_cmp_eq_u32 s20, s12
	s_cselect_b32 s13, s45, s13
	s_cselect_b32 s12, s44, s33
	v_add_u32_e32 v146, s36, v149
	s_cselect_b32 s35, s61, s24
	s_cselect_b32 s34, s60, s1
	s_add_i32 s33, 0, 0x14000
	ds_read_b128 v[142:145], v146
	ds_read_b128 v[152:155], v146 offset:1024
	ds_read_b128 v[156:159], v146 offset:2048
	ds_read_b128 v[160:163], v146 offset:3072
	v_add_u32_e32 v146, s33, v149
	ds_read_b128 v[164:167], v146
	ds_read_b128 v[168:171], v146 offset:1024
	ds_read_b128 v[172:175], v146 offset:2048
	ds_read_b128 v[176:179], v146 offset:3072
	v_lshl_add_u64 v[146:147], s[10:11], 0, v[138:139]
	s_add_i32 m0, s5, 0xc000
	ds_read_b128 v[180:183], v150
	ds_read_b128 v[184:187], v150 offset:1024
	ds_read_b128 v[188:191], v150 offset:2048
	ds_read_b128 v[192:195], v150 offset:3072
	ds_read_b128 v[196:199], v150 offset:4096
	ds_read_b128 v[200:203], v150 offset:5120
	ds_read_b128 v[204:207], v150 offset:6144
	ds_read_b128 v[212:215], v150 offset:7168
	global_load_lds_dwordx4 v[146:147], off
	v_lshl_add_u64 v[146:147], s[10:11], 0, v[140:141]
	s_add_i32 m0, s5, 0xe000
	s_nop 0
	global_load_lds_dwordx4 v[146:147], off
	s_waitcnt vmcnt(8)
	s_waitcnt lgkmcnt(0)
	s_barrier
	s_setprio 1
	v_mfma_f32_16x16x32_bf16 v[126:129], v[142:145], v[180:183], v[126:129]
	v_mfma_f32_16x16x32_bf16 v[122:125], v[156:159], v[180:183], v[122:125]
	v_mfma_f32_16x16x32_bf16 v[110:113], v[142:145], v[188:191], v[110:113]
	v_mfma_f32_16x16x32_bf16 v[106:109], v[156:159], v[188:191], v[106:109]
	v_mfma_f32_16x16x32_bf16 v[94:97], v[142:145], v[196:199], v[94:97]
	v_mfma_f32_16x16x32_bf16 v[90:93], v[156:159], v[196:199], v[90:93]
	v_mfma_f32_16x16x32_bf16 v[78:81], v[142:145], v[204:207], v[78:81]
	v_mfma_f32_16x16x32_bf16 v[74:77], v[156:159], v[204:207], v[74:77]
	v_mfma_f32_16x16x32_bf16 v[126:129], v[152:155], v[184:187], v[126:129]
	v_mfma_f32_16x16x32_bf16 v[122:125], v[160:163], v[184:187], v[122:125]
	v_mfma_f32_16x16x32_bf16 v[110:113], v[152:155], v[192:195], v[110:113]
	v_mfma_f32_16x16x32_bf16 v[106:109], v[160:163], v[192:195], v[106:109]
	v_mfma_f32_16x16x32_bf16 v[94:97], v[152:155], v[200:203], v[94:97]
	v_mfma_f32_16x16x32_bf16 v[90:93], v[160:163], v[200:203], v[90:93]
	v_mfma_f32_16x16x32_bf16 v[78:81], v[152:155], v[212:215], v[78:81]
	v_mfma_f32_16x16x32_bf16 v[74:77], v[160:163], v[212:215], v[74:77]
	v_mfma_f32_16x16x32_bf16 v[118:121], v[164:167], v[180:183], v[118:121]
	v_mfma_f32_16x16x32_bf16 v[114:117], v[172:175], v[180:183], v[114:117]
	v_mfma_f32_16x16x32_bf16 v[102:105], v[164:167], v[188:191], v[102:105]
	v_mfma_f32_16x16x32_bf16 v[98:101], v[172:175], v[188:191], v[98:101]
	v_mfma_f32_16x16x32_bf16 v[86:89], v[164:167], v[196:199], v[86:89]
	v_mfma_f32_16x16x32_bf16 v[82:85], v[172:175], v[196:199], v[82:85]
	v_mfma_f32_16x16x32_bf16 v[70:73], v[164:167], v[204:207], v[70:73]
	v_mfma_f32_16x16x32_bf16 v[66:69], v[172:175], v[204:207], v[66:69]
	v_mfma_f32_16x16x32_bf16 v[118:121], v[168:171], v[184:187], v[118:121]
	v_mfma_f32_16x16x32_bf16 v[114:117], v[176:179], v[184:187], v[114:117]
	v_mfma_f32_16x16x32_bf16 v[102:105], v[168:171], v[192:195], v[102:105]
	v_mfma_f32_16x16x32_bf16 v[98:101], v[176:179], v[192:195], v[98:101]
	v_mfma_f32_16x16x32_bf16 v[86:89], v[168:171], v[200:203], v[86:89]
	v_mfma_f32_16x16x32_bf16 v[82:85], v[176:179], v[200:203], v[82:85]
	v_mfma_f32_16x16x32_bf16 v[70:73], v[168:171], v[212:215], v[70:73]
	v_mfma_f32_16x16x32_bf16 v[66:69], v[176:179], v[212:215], v[66:69]
	s_setprio 0
	s_barrier
	s_add_i32 s36, s36, s4
	v_lshl_add_u64 v[146:147], s[34:35], 0, v[136:137]
	s_mov_b32 m0, s36
	ds_read_b128 v[180:183], v150 offset:16384
	ds_read_b128 v[184:187], v150 offset:17408
	ds_read_b128 v[188:191], v150 offset:18432
	ds_read_b128 v[192:195], v150 offset:19456
	ds_read_b128 v[196:199], v150 offset:20480
	ds_read_b128 v[200:203], v150 offset:21504
	ds_read_b128 v[204:207], v150 offset:22528
	ds_read_b128 v[212:215], v150 offset:23552
	global_load_lds_dwordx4 v[146:147], off
	s_add_i32 m0, s36, 0x2000
	v_lshl_add_u64 v[208:209], s[34:35], 0, v[132:133]
	s_add_u32 s34, s34, s46
	s_addc_u32 s35, s35, s47
	s_add_i32 s33, s33, s4
	global_load_lds_dwordx4 v[208:209], off
	v_lshl_add_u64 v[210:211], s[34:35], 0, v[136:137]
	s_mov_b32 m0, s33
	v_lshl_add_u64 v[216:217], s[34:35], 0, v[132:133]
	global_load_lds_dwordx4 v[210:211], off
	s_add_i32 m0, s33, 0x2000
	v_lshl_add_u64 v[218:219], s[12:13], 0, v[134:135]
	global_load_lds_dwordx4 v[216:217], off
	s_mov_b32 m0, s5
	v_lshl_add_u64 v[220:221], s[12:13], 0, v[130:131]
	global_load_lds_dwordx4 v[218:219], off
	s_mov_b32 m0, s6
	s_nop 0
	global_load_lds_dwordx4 v[220:221], off
	s_waitcnt vmcnt(8)
	s_waitcnt lgkmcnt(0)
	s_barrier
	s_setprio 1
	v_mfma_f32_16x16x32_bf16 v[62:65], v[142:145], v[180:183], v[62:65]
	v_mfma_f32_16x16x32_bf16 v[58:61], v[156:159], v[180:183], v[58:61]
	v_mfma_f32_16x16x32_bf16 v[46:49], v[142:145], v[188:191], v[46:49]
	v_mfma_f32_16x16x32_bf16 v[42:45], v[156:159], v[188:191], v[42:45]
	v_mfma_f32_16x16x32_bf16 v[30:33], v[142:145], v[196:199], v[30:33]
	v_mfma_f32_16x16x32_bf16 v[26:29], v[156:159], v[196:199], v[26:29]
	v_mfma_f32_16x16x32_bf16 v[14:17], v[142:145], v[204:207], v[14:17]
	v_mfma_f32_16x16x32_bf16 v[10:13], v[156:159], v[204:207], v[10:13]
	v_mfma_f32_16x16x32_bf16 v[62:65], v[152:155], v[184:187], v[62:65]
	v_mfma_f32_16x16x32_bf16 v[58:61], v[160:163], v[184:187], v[58:61]
	v_mfma_f32_16x16x32_bf16 v[46:49], v[152:155], v[192:195], v[46:49]
	v_mfma_f32_16x16x32_bf16 v[42:45], v[160:163], v[192:195], v[42:45]
	v_mfma_f32_16x16x32_bf16 v[30:33], v[152:155], v[200:203], v[30:33]
	v_mfma_f32_16x16x32_bf16 v[26:29], v[160:163], v[200:203], v[26:29]
	v_mfma_f32_16x16x32_bf16 v[14:17], v[152:155], v[212:215], v[14:17]
	v_mfma_f32_16x16x32_bf16 v[10:13], v[160:163], v[212:215], v[10:13]
	v_mfma_f32_16x16x32_bf16 v[54:57], v[164:167], v[180:183], v[54:57]
	v_mfma_f32_16x16x32_bf16 v[50:53], v[172:175], v[180:183], v[50:53]
	v_mfma_f32_16x16x32_bf16 v[38:41], v[164:167], v[188:191], v[38:41]
	v_mfma_f32_16x16x32_bf16 v[34:37], v[172:175], v[188:191], v[34:37]
	v_mfma_f32_16x16x32_bf16 v[22:25], v[164:167], v[196:199], v[22:25]
	v_mfma_f32_16x16x32_bf16 v[18:21], v[172:175], v[196:199], v[18:21]
	v_mfma_f32_16x16x32_bf16 v[6:9], v[164:167], v[204:207], v[6:9]
	v_mfma_f32_16x16x32_bf16 v[2:5], v[172:175], v[204:207], v[2:5]
	v_mfma_f32_16x16x32_bf16 v[54:57], v[168:171], v[184:187], v[54:57]
	v_mfma_f32_16x16x32_bf16 v[50:53], v[176:179], v[184:187], v[50:53]
	v_mfma_f32_16x16x32_bf16 v[38:41], v[168:171], v[192:195], v[38:41]
	v_mfma_f32_16x16x32_bf16 v[34:37], v[176:179], v[192:195], v[34:37]
	v_mfma_f32_16x16x32_bf16 v[22:25], v[168:171], v[200:203], v[22:25]
	v_mfma_f32_16x16x32_bf16 v[18:21], v[176:179], v[200:203], v[18:21]
	v_mfma_f32_16x16x32_bf16 v[6:9], v[168:171], v[212:215], v[6:9]
	v_mfma_f32_16x16x32_bf16 v[2:5], v[176:179], v[212:215], v[2:5]
	s_setprio 0
	s_barrier
	s_add_i32 s33, 0, 0x18000
	v_add_u32_e32 v151, s33, v149
	s_add_i32 s34, 0, 0x1c000
	ds_read_b128 v[142:145], v151
	ds_read_b128 v[152:155], v151 offset:1024
	ds_read_b128 v[156:159], v151 offset:2048
	ds_read_b128 v[160:163], v151 offset:3072
	v_add_u32_e32 v151, s34, v149
	ds_read_b128 v[164:167], v151
	ds_read_b128 v[168:171], v151 offset:1024
	ds_read_b128 v[172:175], v151 offset:2048
	ds_read_b128 v[176:179], v151 offset:3072
	s_add_u32 s12, s12, s46
	s_addc_u32 s13, s13, s47
	s_mov_b32 m0, s7
	v_lshl_add_u64 v[222:223], s[12:13], 0, v[134:135]
	ds_read_b128 v[180:183], v150 offset:32768
	ds_read_b128 v[184:187], v150 offset:33792
	ds_read_b128 v[188:191], v150 offset:34816
	ds_read_b128 v[192:195], v150 offset:35840
	ds_read_b128 v[196:199], v150 offset:36864
	ds_read_b128 v[200:203], v150 offset:37888
	ds_read_b128 v[204:207], v150 offset:38912
	ds_read_b128 v[212:215], v150 offset:39936
	global_load_lds_dwordx4 v[222:223], off
	v_lshl_add_u64 v[222:223], s[12:13], 0, v[130:131]
	s_mov_b32 m0, s8
	s_nop 0
	global_load_lds_dwordx4 v[222:223], off
	s_waitcnt vmcnt(8)
	s_waitcnt lgkmcnt(0)
	s_barrier
	s_setprio 1
	v_mfma_f32_16x16x32_bf16 v[126:129], v[142:145], v[180:183], v[126:129]
	v_mfma_f32_16x16x32_bf16 v[122:125], v[156:159], v[180:183], v[122:125]
	v_mfma_f32_16x16x32_bf16 v[110:113], v[142:145], v[188:191], v[110:113]
	v_mfma_f32_16x16x32_bf16 v[106:109], v[156:159], v[188:191], v[106:109]
	v_mfma_f32_16x16x32_bf16 v[94:97], v[142:145], v[196:199], v[94:97]
	v_mfma_f32_16x16x32_bf16 v[90:93], v[156:159], v[196:199], v[90:93]
	v_mfma_f32_16x16x32_bf16 v[78:81], v[142:145], v[204:207], v[78:81]
	v_mfma_f32_16x16x32_bf16 v[74:77], v[156:159], v[204:207], v[74:77]
	v_mfma_f32_16x16x32_bf16 v[126:129], v[152:155], v[184:187], v[126:129]
	v_mfma_f32_16x16x32_bf16 v[122:125], v[160:163], v[184:187], v[122:125]
	v_mfma_f32_16x16x32_bf16 v[110:113], v[152:155], v[192:195], v[110:113]
	v_mfma_f32_16x16x32_bf16 v[106:109], v[160:163], v[192:195], v[106:109]
	v_mfma_f32_16x16x32_bf16 v[94:97], v[152:155], v[200:203], v[94:97]
	v_mfma_f32_16x16x32_bf16 v[90:93], v[160:163], v[200:203], v[90:93]
	v_mfma_f32_16x16x32_bf16 v[78:81], v[152:155], v[212:215], v[78:81]
	v_mfma_f32_16x16x32_bf16 v[74:77], v[160:163], v[212:215], v[74:77]
	v_mfma_f32_16x16x32_bf16 v[118:121], v[164:167], v[180:183], v[118:121]
	v_mfma_f32_16x16x32_bf16 v[114:117], v[172:175], v[180:183], v[114:117]
	v_mfma_f32_16x16x32_bf16 v[102:105], v[164:167], v[188:191], v[102:105]
	v_mfma_f32_16x16x32_bf16 v[98:101], v[172:175], v[188:191], v[98:101]
	v_mfma_f32_16x16x32_bf16 v[86:89], v[164:167], v[196:199], v[86:89]
	v_mfma_f32_16x16x32_bf16 v[82:85], v[172:175], v[196:199], v[82:85]
	v_mfma_f32_16x16x32_bf16 v[70:73], v[164:167], v[204:207], v[70:73]
	v_mfma_f32_16x16x32_bf16 v[66:69], v[172:175], v[204:207], v[66:69]
	v_mfma_f32_16x16x32_bf16 v[118:121], v[168:171], v[184:187], v[118:121]
	v_mfma_f32_16x16x32_bf16 v[114:117], v[176:179], v[184:187], v[114:117]
	v_mfma_f32_16x16x32_bf16 v[102:105], v[168:171], v[192:195], v[102:105]
	v_mfma_f32_16x16x32_bf16 v[98:101], v[176:179], v[192:195], v[98:101]
	v_mfma_f32_16x16x32_bf16 v[86:89], v[168:171], v[200:203], v[86:89]
	v_mfma_f32_16x16x32_bf16 v[82:85], v[176:179], v[200:203], v[82:85]
	v_mfma_f32_16x16x32_bf16 v[70:73], v[168:171], v[212:215], v[70:73]
	v_mfma_f32_16x16x32_bf16 v[66:69], v[176:179], v[212:215], v[66:69]
	s_setprio 0
	s_barrier
	s_add_i32 s12, s33, s4
	v_lshl_add_u64 v[146:147], v[146:147], 0, s[28:29]
	s_mov_b32 m0, s12
	ds_read_b128 v[180:183], v150 offset:49152
	ds_read_b128 v[184:187], v150 offset:50176
	ds_read_b128 v[188:191], v150 offset:51200
	ds_read_b128 v[192:195], v150 offset:52224
	ds_read_b128 v[196:199], v150 offset:53248
	ds_read_b128 v[200:203], v150 offset:54272
	ds_read_b128 v[204:207], v150 offset:55296
	ds_read_b128 v[212:215], v150 offset:56320
	global_load_lds_dwordx4 v[146:147], off
	v_lshl_add_u64 v[146:147], v[208:209], 0, s[28:29]
	s_add_i32 m0, s12, 0x2000
	s_add_i32 s12, s34, s4
	global_load_lds_dwordx4 v[146:147], off
	v_lshl_add_u64 v[146:147], v[210:211], 0, s[28:29]
	s_mov_b32 m0, s12
	s_nop 0
	global_load_lds_dwordx4 v[146:147], off
	v_lshl_add_u64 v[146:147], v[216:217], 0, s[28:29]
	s_add_i32 m0, s12, 0x2000
	s_nop 0
	global_load_lds_dwordx4 v[146:147], off
	v_lshl_add_u64 v[146:147], v[218:219], 0, s[28:29]
	s_mov_b32 m0, s9
	s_nop 0
	global_load_lds_dwordx4 v[146:147], off
	v_lshl_add_u64 v[146:147], v[220:221], 0, s[28:29]
	s_mov_b32 m0, s14
	s_nop 0
	global_load_lds_dwordx4 v[146:147], off
	s_waitcnt vmcnt(8)
	s_waitcnt lgkmcnt(0)
	s_barrier
	s_setprio 1
	v_mfma_f32_16x16x32_bf16 v[62:65], v[142:145], v[180:183], v[62:65]
	v_mfma_f32_16x16x32_bf16 v[58:61], v[156:159], v[180:183], v[58:61]
	v_mfma_f32_16x16x32_bf16 v[46:49], v[142:145], v[188:191], v[46:49]
	v_mfma_f32_16x16x32_bf16 v[42:45], v[156:159], v[188:191], v[42:45]
	v_mfma_f32_16x16x32_bf16 v[30:33], v[142:145], v[196:199], v[30:33]
	v_mfma_f32_16x16x32_bf16 v[26:29], v[156:159], v[196:199], v[26:29]
	v_mfma_f32_16x16x32_bf16 v[14:17], v[142:145], v[204:207], v[14:17]
	v_mfma_f32_16x16x32_bf16 v[10:13], v[156:159], v[204:207], v[10:13]
	v_mfma_f32_16x16x32_bf16 v[62:65], v[152:155], v[184:187], v[62:65]
	v_mfma_f32_16x16x32_bf16 v[58:61], v[160:163], v[184:187], v[58:61]
	v_mfma_f32_16x16x32_bf16 v[46:49], v[152:155], v[192:195], v[46:49]
	v_mfma_f32_16x16x32_bf16 v[42:45], v[160:163], v[192:195], v[42:45]
	v_mfma_f32_16x16x32_bf16 v[30:33], v[152:155], v[200:203], v[30:33]
	v_mfma_f32_16x16x32_bf16 v[26:29], v[160:163], v[200:203], v[26:29]
	v_mfma_f32_16x16x32_bf16 v[14:17], v[152:155], v[212:215], v[14:17]
	v_mfma_f32_16x16x32_bf16 v[10:13], v[160:163], v[212:215], v[10:13]
	v_mfma_f32_16x16x32_bf16 v[54:57], v[164:167], v[180:183], v[54:57]
	v_mfma_f32_16x16x32_bf16 v[50:53], v[172:175], v[180:183], v[50:53]
	v_mfma_f32_16x16x32_bf16 v[38:41], v[164:167], v[188:191], v[38:41]
	v_mfma_f32_16x16x32_bf16 v[34:37], v[172:175], v[188:191], v[34:37]
	v_mfma_f32_16x16x32_bf16 v[22:25], v[164:167], v[196:199], v[22:25]
	v_mfma_f32_16x16x32_bf16 v[18:21], v[172:175], v[196:199], v[18:21]
	v_mfma_f32_16x16x32_bf16 v[6:9], v[164:167], v[204:207], v[6:9]
	v_mfma_f32_16x16x32_bf16 v[2:5], v[172:175], v[204:207], v[2:5]
	v_mfma_f32_16x16x32_bf16 v[54:57], v[168:171], v[184:187], v[54:57]
	v_mfma_f32_16x16x32_bf16 v[50:53], v[176:179], v[184:187], v[50:53]
	v_mfma_f32_16x16x32_bf16 v[38:41], v[168:171], v[192:195], v[38:41]
	v_mfma_f32_16x16x32_bf16 v[34:37], v[176:179], v[192:195], v[34:37]
	v_mfma_f32_16x16x32_bf16 v[22:25], v[168:171], v[200:203], v[22:25]
	v_mfma_f32_16x16x32_bf16 v[18:21], v[176:179], v[200:203], v[18:21]
	v_mfma_f32_16x16x32_bf16 v[6:9], v[168:171], v[212:215], v[6:9]
	v_mfma_f32_16x16x32_bf16 v[2:5], v[176:179], v[212:215], v[2:5]
	s_setprio 0
	s_barrier
	s_add_u32 s1, s1, 0x100
	s_addc_u32 s24, s24, 0
	s_add_u32 s10, s10, 0x100
	s_addc_u32 s11, s11, 0
	s_cmp_ge_i32 s25, s18
	s_mov_b32 s12, s25
	s_cbranch_scc0 .LBB0_1062

.LBB0_1103:
	s_add_i32 s47, s36, 2
	s_add_u32 s48, s44, 0x80
	s_addc_u32 s49, s45, 0
	s_add_i32 s52, 0, 0x10000
	s_cmp_eq_u32 s19, s36
	s_cselect_b32 s49, s39, s49
	s_cselect_b32 s48, s38, s48
	v_add_u32_e32 v145, s52, v143
	s_cselect_b32 s51, s41, s35
	s_cselect_b32 s50, s40, s34
	s_add_i32 s36, 0, 0x14000
	ds_read_b128 v[146:149], v145
	ds_read_b128 v[150:153], v145 offset:1024
	ds_read_b128 v[154:157], v145 offset:2048
	ds_read_b128 v[158:161], v145 offset:3072
	v_add_u32_e32 v145, s36, v143
	ds_read_b128 v[162:165], v145
	ds_read_b128 v[166:169], v145 offset:1024
	ds_read_b128 v[170:173], v145 offset:2048
	ds_read_b128 v[174:177], v145 offset:3072
	v_lshl_add_u64 v[210:211], s[44:45], 0, v[138:139]
	s_add_i32 m0, s5, 0xc000
	ds_read_b128 v[178:181], v144
	ds_read_b128 v[182:185], v144 offset:1024
	ds_read_b128 v[186:189], v144 offset:2048
	ds_read_b128 v[190:193], v144 offset:3072
	ds_read_b128 v[194:197], v144 offset:4096
	ds_read_b128 v[198:201], v144 offset:5120
	ds_read_b128 v[202:205], v144 offset:6144
	ds_read_b128 v[206:209], v144 offset:7168
	global_load_lds_dwordx4 v[210:211], off
	v_lshl_add_u64 v[210:211], s[44:45], 0, v[140:141]
	s_add_i32 m0, s5, 0xe000
	s_nop 0
	global_load_lds_dwordx4 v[210:211], off
	s_waitcnt vmcnt(8)
	s_waitcnt lgkmcnt(0)
	s_barrier
	s_setprio 1
	v_mfma_f32_16x16x32_bf16 v[122:125], v[146:149], v[178:181], v[122:125]
	v_mfma_f32_16x16x32_bf16 v[126:129], v[154:157], v[178:181], v[126:129]
	v_mfma_f32_16x16x32_bf16 v[110:113], v[146:149], v[186:189], v[110:113]
	v_mfma_f32_16x16x32_bf16 v[106:109], v[154:157], v[186:189], v[106:109]
	v_mfma_f32_16x16x32_bf16 v[94:97], v[146:149], v[194:197], v[94:97]
	v_mfma_f32_16x16x32_bf16 v[90:93], v[154:157], v[194:197], v[90:93]
	v_mfma_f32_16x16x32_bf16 v[78:81], v[146:149], v[202:205], v[78:81]
	v_mfma_f32_16x16x32_bf16 v[74:77], v[154:157], v[202:205], v[74:77]
	v_mfma_f32_16x16x32_bf16 v[122:125], v[150:153], v[182:185], v[122:125]
	v_mfma_f32_16x16x32_bf16 v[126:129], v[158:161], v[182:185], v[126:129]
	v_mfma_f32_16x16x32_bf16 v[110:113], v[150:153], v[190:193], v[110:113]
	v_mfma_f32_16x16x32_bf16 v[106:109], v[158:161], v[190:193], v[106:109]
	v_mfma_f32_16x16x32_bf16 v[94:97], v[150:153], v[198:201], v[94:97]
	v_mfma_f32_16x16x32_bf16 v[90:93], v[158:161], v[198:201], v[90:93]
	v_mfma_f32_16x16x32_bf16 v[78:81], v[150:153], v[206:209], v[78:81]
	v_mfma_f32_16x16x32_bf16 v[74:77], v[158:161], v[206:209], v[74:77]
	v_mfma_f32_16x16x32_bf16 v[118:121], v[162:165], v[178:181], v[118:121]
	v_mfma_f32_16x16x32_bf16 v[114:117], v[170:173], v[178:181], v[114:117]
	v_mfma_f32_16x16x32_bf16 v[102:105], v[162:165], v[186:189], v[102:105]
	v_mfma_f32_16x16x32_bf16 v[98:101], v[170:173], v[186:189], v[98:101]
	v_mfma_f32_16x16x32_bf16 v[86:89], v[162:165], v[194:197], v[86:89]
	v_mfma_f32_16x16x32_bf16 v[82:85], v[170:173], v[194:197], v[82:85]
	v_mfma_f32_16x16x32_bf16 v[70:73], v[162:165], v[202:205], v[70:73]
	v_mfma_f32_16x16x32_bf16 v[66:69], v[170:173], v[202:205], v[66:69]
	v_mfma_f32_16x16x32_bf16 v[118:121], v[166:169], v[182:185], v[118:121]
	v_mfma_f32_16x16x32_bf16 v[114:117], v[174:177], v[182:185], v[114:117]
	v_mfma_f32_16x16x32_bf16 v[102:105], v[166:169], v[190:193], v[102:105]
	v_mfma_f32_16x16x32_bf16 v[98:101], v[174:177], v[190:193], v[98:101]
	v_mfma_f32_16x16x32_bf16 v[86:89], v[166:169], v[198:201], v[86:89]
	v_mfma_f32_16x16x32_bf16 v[82:85], v[174:177], v[198:201], v[82:85]
	v_mfma_f32_16x16x32_bf16 v[70:73], v[166:169], v[206:209], v[70:73]
	v_mfma_f32_16x16x32_bf16 v[66:69], v[174:177], v[206:209], v[66:69]
	s_setprio 0
	s_barrier
	s_add_i32 s52, s52, s4
	v_lshl_add_u64 v[210:211], s[50:51], 0, v[136:137]
	s_mov_b32 m0, s52
	ds_read_b128 v[178:181], v144 offset:16384
	ds_read_b128 v[182:185], v144 offset:17408
	ds_read_b128 v[186:189], v144 offset:18432
	ds_read_b128 v[190:193], v144 offset:19456
	ds_read_b128 v[194:197], v144 offset:20480
	ds_read_b128 v[198:201], v144 offset:21504
	ds_read_b128 v[202:205], v144 offset:22528
	ds_read_b128 v[206:209], v144 offset:23552
	global_load_lds_dwordx4 v[210:211], off
	s_add_i32 m0, s52, 0x2000
	v_lshl_add_u64 v[212:213], s[50:51], 0, v[132:133]
	s_add_u32 s50, s50, s0
	s_addc_u32 s51, s51, s1
	s_add_i32 s36, s36, s4
	global_load_lds_dwordx4 v[212:213], off
	v_lshl_add_u64 v[214:215], s[50:51], 0, v[136:137]
	s_mov_b32 m0, s36
	v_lshl_add_u64 v[216:217], s[50:51], 0, v[132:133]
	global_load_lds_dwordx4 v[214:215], off
	s_add_i32 m0, s36, 0x2000
	v_lshl_add_u64 v[218:219], s[48:49], 0, v[134:135]
	global_load_lds_dwordx4 v[216:217], off
	s_mov_b32 m0, s5
	v_lshl_add_u64 v[220:221], s[48:49], 0, v[130:131]
	global_load_lds_dwordx4 v[218:219], off
	s_mov_b32 m0, s6
	s_nop 0
	global_load_lds_dwordx4 v[220:221], off
	s_waitcnt vmcnt(8)
	s_waitcnt lgkmcnt(0)
	s_barrier
	s_setprio 1
	v_mfma_f32_16x16x32_bf16 v[62:65], v[146:149], v[178:181], v[62:65]
	v_mfma_f32_16x16x32_bf16 v[58:61], v[154:157], v[178:181], v[58:61]
	v_mfma_f32_16x16x32_bf16 v[46:49], v[146:149], v[186:189], v[46:49]
	v_mfma_f32_16x16x32_bf16 v[42:45], v[154:157], v[186:189], v[42:45]
	v_mfma_f32_16x16x32_bf16 v[30:33], v[146:149], v[194:197], v[30:33]
	v_mfma_f32_16x16x32_bf16 v[26:29], v[154:157], v[194:197], v[26:29]
	v_mfma_f32_16x16x32_bf16 v[14:17], v[146:149], v[202:205], v[14:17]
	v_mfma_f32_16x16x32_bf16 v[10:13], v[154:157], v[202:205], v[10:13]
	v_mfma_f32_16x16x32_bf16 v[62:65], v[150:153], v[182:185], v[62:65]
	v_mfma_f32_16x16x32_bf16 v[58:61], v[158:161], v[182:185], v[58:61]
	v_mfma_f32_16x16x32_bf16 v[46:49], v[150:153], v[190:193], v[46:49]
	v_mfma_f32_16x16x32_bf16 v[42:45], v[158:161], v[190:193], v[42:45]
	v_mfma_f32_16x16x32_bf16 v[30:33], v[150:153], v[198:201], v[30:33]
	v_mfma_f32_16x16x32_bf16 v[26:29], v[158:161], v[198:201], v[26:29]
	v_mfma_f32_16x16x32_bf16 v[14:17], v[150:153], v[206:209], v[14:17]
	v_mfma_f32_16x16x32_bf16 v[10:13], v[158:161], v[206:209], v[10:13]
	v_mfma_f32_16x16x32_bf16 v[54:57], v[162:165], v[178:181], v[54:57]
	v_mfma_f32_16x16x32_bf16 v[50:53], v[170:173], v[178:181], v[50:53]
	v_mfma_f32_16x16x32_bf16 v[38:41], v[162:165], v[186:189], v[38:41]
	v_mfma_f32_16x16x32_bf16 v[34:37], v[170:173], v[186:189], v[34:37]
	v_mfma_f32_16x16x32_bf16 v[22:25], v[162:165], v[194:197], v[22:25]
	v_mfma_f32_16x16x32_bf16 v[18:21], v[170:173], v[194:197], v[18:21]
	v_mfma_f32_16x16x32_bf16 v[6:9], v[162:165], v[202:205], v[6:9]
	v_mfma_f32_16x16x32_bf16 v[2:5], v[170:173], v[202:205], v[2:5]
	v_mfma_f32_16x16x32_bf16 v[54:57], v[166:169], v[182:185], v[54:57]
	v_mfma_f32_16x16x32_bf16 v[50:53], v[174:177], v[182:185], v[50:53]
	v_mfma_f32_16x16x32_bf16 v[38:41], v[166:169], v[190:193], v[38:41]
	v_mfma_f32_16x16x32_bf16 v[34:37], v[174:177], v[190:193], v[34:37]
	v_mfma_f32_16x16x32_bf16 v[22:25], v[166:169], v[198:201], v[22:25]
	v_mfma_f32_16x16x32_bf16 v[18:21], v[174:177], v[198:201], v[18:21]
	v_mfma_f32_16x16x32_bf16 v[6:9], v[166:169], v[206:209], v[6:9]
	v_mfma_f32_16x16x32_bf16 v[2:5], v[174:177], v[206:209], v[2:5]
	s_setprio 0
	s_barrier
	s_add_i32 s36, 0, 0x18000
	v_add_u32_e32 v145, s36, v143
	s_add_i32 s50, 0, 0x1c000
	ds_read_b128 v[146:149], v145
	ds_read_b128 v[150:153], v145 offset:1024
	ds_read_b128 v[154:157], v145 offset:2048
	ds_read_b128 v[158:161], v145 offset:3072
	v_add_u32_e32 v145, s50, v143
	ds_read_b128 v[162:165], v145
	ds_read_b128 v[166:169], v145 offset:1024
	ds_read_b128 v[170:173], v145 offset:2048
	ds_read_b128 v[174:177], v145 offset:3072
	s_add_u32 s48, s48, s0
	s_addc_u32 s49, s49, s1
	s_mov_b32 m0, s7
	v_lshl_add_u64 v[222:223], s[48:49], 0, v[134:135]
	ds_read_b128 v[178:181], v144 offset:32768
	ds_read_b128 v[182:185], v144 offset:33792
	ds_read_b128 v[186:189], v144 offset:34816
	ds_read_b128 v[190:193], v144 offset:35840
	ds_read_b128 v[194:197], v144 offset:36864
	ds_read_b128 v[198:201], v144 offset:37888
	ds_read_b128 v[202:205], v144 offset:38912
	ds_read_b128 v[206:209], v144 offset:39936
	global_load_lds_dwordx4 v[222:223], off
	v_lshl_add_u64 v[222:223], s[48:49], 0, v[130:131]
	s_mov_b32 m0, s8
	s_nop 0
	global_load_lds_dwordx4 v[222:223], off
	s_waitcnt vmcnt(8)
	s_waitcnt lgkmcnt(0)
	s_barrier
	s_setprio 1
	v_mfma_f32_16x16x32_bf16 v[122:125], v[146:149], v[178:181], v[122:125]
	v_mfma_f32_16x16x32_bf16 v[126:129], v[154:157], v[178:181], v[126:129]
	v_mfma_f32_16x16x32_bf16 v[110:113], v[146:149], v[186:189], v[110:113]
	v_mfma_f32_16x16x32_bf16 v[106:109], v[154:157], v[186:189], v[106:109]
	v_mfma_f32_16x16x32_bf16 v[94:97], v[146:149], v[194:197], v[94:97]
	v_mfma_f32_16x16x32_bf16 v[90:93], v[154:157], v[194:197], v[90:93]
	v_mfma_f32_16x16x32_bf16 v[78:81], v[146:149], v[202:205], v[78:81]
	v_mfma_f32_16x16x32_bf16 v[74:77], v[154:157], v[202:205], v[74:77]
	v_mfma_f32_16x16x32_bf16 v[122:125], v[150:153], v[182:185], v[122:125]
	v_mfma_f32_16x16x32_bf16 v[126:129], v[158:161], v[182:185], v[126:129]
	v_mfma_f32_16x16x32_bf16 v[110:113], v[150:153], v[190:193], v[110:113]
	v_mfma_f32_16x16x32_bf16 v[106:109], v[158:161], v[190:193], v[106:109]
	v_mfma_f32_16x16x32_bf16 v[94:97], v[150:153], v[198:201], v[94:97]
	v_mfma_f32_16x16x32_bf16 v[90:93], v[158:161], v[198:201], v[90:93]
	v_mfma_f32_16x16x32_bf16 v[78:81], v[150:153], v[206:209], v[78:81]
	v_mfma_f32_16x16x32_bf16 v[74:77], v[158:161], v[206:209], v[74:77]
	v_mfma_f32_16x16x32_bf16 v[118:121], v[162:165], v[178:181], v[118:121]
	v_mfma_f32_16x16x32_bf16 v[114:117], v[170:173], v[178:181], v[114:117]
	v_mfma_f32_16x16x32_bf16 v[102:105], v[162:165], v[186:189], v[102:105]
	v_mfma_f32_16x16x32_bf16 v[98:101], v[170:173], v[186:189], v[98:101]
	v_mfma_f32_16x16x32_bf16 v[86:89], v[162:165], v[194:197], v[86:89]
	v_mfma_f32_16x16x32_bf16 v[82:85], v[170:173], v[194:197], v[82:85]
	v_mfma_f32_16x16x32_bf16 v[70:73], v[162:165], v[202:205], v[70:73]
	v_mfma_f32_16x16x32_bf16 v[66:69], v[170:173], v[202:205], v[66:69]
	v_mfma_f32_16x16x32_bf16 v[118:121], v[166:169], v[182:185], v[118:121]
	v_mfma_f32_16x16x32_bf16 v[114:117], v[174:177], v[182:185], v[114:117]
	v_mfma_f32_16x16x32_bf16 v[102:105], v[166:169], v[190:193], v[102:105]
	v_mfma_f32_16x16x32_bf16 v[98:101], v[174:177], v[190:193], v[98:101]
	v_mfma_f32_16x16x32_bf16 v[86:89], v[166:169], v[198:201], v[86:89]
	v_mfma_f32_16x16x32_bf16 v[82:85], v[174:177], v[198:201], v[82:85]
	v_mfma_f32_16x16x32_bf16 v[70:73], v[166:169], v[206:209], v[70:73]
	v_mfma_f32_16x16x32_bf16 v[66:69], v[174:177], v[206:209], v[66:69]
	s_setprio 0
	s_barrier
	s_add_i32 s36, s36, s4
	v_lshl_add_u64 v[210:211], v[210:211], 0, s[28:29]
	s_mov_b32 m0, s36
	ds_read_b128 v[178:181], v144 offset:49152
	ds_read_b128 v[182:185], v144 offset:50176
	ds_read_b128 v[186:189], v144 offset:51200
	ds_read_b128 v[190:193], v144 offset:52224
	ds_read_b128 v[194:197], v144 offset:53248
	ds_read_b128 v[198:201], v144 offset:54272
	ds_read_b128 v[202:205], v144 offset:55296
	ds_read_b128 v[206:209], v144 offset:56320
	global_load_lds_dwordx4 v[210:211], off
	v_lshl_add_u64 v[210:211], v[212:213], 0, s[28:29]
	s_add_i32 m0, s36, 0x2000
	s_add_i32 s36, s50, s4
	global_load_lds_dwordx4 v[210:211], off
	v_lshl_add_u64 v[210:211], v[214:215], 0, s[28:29]
	s_mov_b32 m0, s36
	s_nop 0
	global_load_lds_dwordx4 v[210:211], off
	v_lshl_add_u64 v[210:211], v[216:217], 0, s[28:29]
	s_add_i32 m0, s36, 0x2000
	s_nop 0
	global_load_lds_dwordx4 v[210:211], off
	v_lshl_add_u64 v[210:211], v[218:219], 0, s[28:29]
	s_mov_b32 m0, s9
	s_nop 0
	global_load_lds_dwordx4 v[210:211], off
	v_lshl_add_u64 v[210:211], v[220:221], 0, s[28:29]
	s_mov_b32 m0, s14
	s_nop 0
	global_load_lds_dwordx4 v[210:211], off
	s_waitcnt vmcnt(8)
	s_waitcnt lgkmcnt(0)
	s_barrier
	s_setprio 1
	v_mfma_f32_16x16x32_bf16 v[62:65], v[146:149], v[178:181], v[62:65]
	v_mfma_f32_16x16x32_bf16 v[58:61], v[154:157], v[178:181], v[58:61]
	v_mfma_f32_16x16x32_bf16 v[46:49], v[146:149], v[186:189], v[46:49]
	v_mfma_f32_16x16x32_bf16 v[42:45], v[154:157], v[186:189], v[42:45]
	v_mfma_f32_16x16x32_bf16 v[30:33], v[146:149], v[194:197], v[30:33]
	v_mfma_f32_16x16x32_bf16 v[26:29], v[154:157], v[194:197], v[26:29]
	v_mfma_f32_16x16x32_bf16 v[14:17], v[146:149], v[202:205], v[14:17]
	v_mfma_f32_16x16x32_bf16 v[10:13], v[154:157], v[202:205], v[10:13]
	v_mfma_f32_16x16x32_bf16 v[62:65], v[150:153], v[182:185], v[62:65]
	v_mfma_f32_16x16x32_bf16 v[58:61], v[158:161], v[182:185], v[58:61]
	v_mfma_f32_16x16x32_bf16 v[46:49], v[150:153], v[190:193], v[46:49]
	v_mfma_f32_16x16x32_bf16 v[42:45], v[158:161], v[190:193], v[42:45]
	v_mfma_f32_16x16x32_bf16 v[30:33], v[150:153], v[198:201], v[30:33]
	v_mfma_f32_16x16x32_bf16 v[26:29], v[158:161], v[198:201], v[26:29]
	v_mfma_f32_16x16x32_bf16 v[14:17], v[150:153], v[206:209], v[14:17]
	v_mfma_f32_16x16x32_bf16 v[10:13], v[158:161], v[206:209], v[10:13]
	v_mfma_f32_16x16x32_bf16 v[54:57], v[162:165], v[178:181], v[54:57]
	v_mfma_f32_16x16x32_bf16 v[50:53], v[170:173], v[178:181], v[50:53]
	v_mfma_f32_16x16x32_bf16 v[38:41], v[162:165], v[186:189], v[38:41]
	v_mfma_f32_16x16x32_bf16 v[34:37], v[170:173], v[186:189], v[34:37]
	v_mfma_f32_16x16x32_bf16 v[22:25], v[162:165], v[194:197], v[22:25]
	v_mfma_f32_16x16x32_bf16 v[18:21], v[170:173], v[194:197], v[18:21]
	v_mfma_f32_16x16x32_bf16 v[6:9], v[162:165], v[202:205], v[6:9]
	v_mfma_f32_16x16x32_bf16 v[2:5], v[170:173], v[202:205], v[2:5]
	v_mfma_f32_16x16x32_bf16 v[54:57], v[166:169], v[182:185], v[54:57]
	v_mfma_f32_16x16x32_bf16 v[50:53], v[174:177], v[182:185], v[50:53]
	v_mfma_f32_16x16x32_bf16 v[38:41], v[166:169], v[190:193], v[38:41]
	v_mfma_f32_16x16x32_bf16 v[34:37], v[174:177], v[190:193], v[34:37]
	v_mfma_f32_16x16x32_bf16 v[22:25], v[166:169], v[198:201], v[22:25]
	v_mfma_f32_16x16x32_bf16 v[18:21], v[174:177], v[198:201], v[18:21]
	v_mfma_f32_16x16x32_bf16 v[6:9], v[166:169], v[206:209], v[6:9]
	v_mfma_f32_16x16x32_bf16 v[2:5], v[174:177], v[206:209], v[2:5]
	s_setprio 0
	s_barrier
	s_add_u32 s44, s44, 0x100
	s_addc_u32 s45, s45, 0
	s_add_u32 s34, s34, 0x100
	s_addc_u32 s35, s35, 0
	s_cmp_ge_i32 s47, s15
	s_mov_b32 s36, s47
	s_cbranch_scc0 .LBB0_1103

.LBB0_1182:
	s_add_i32 s7, s6, 2
	s_add_u32 s8, s10, 0x80
	s_addc_u32 s9, s11, 0
	s_add_i32 s14, 0, 0x10000
	s_cmp_eq_u32 s85, s6
	s_cselect_b32 s13, s73, s9
	s_cselect_b32 s12, s72, s8
	s_cselect_b32 s9, s75, s5
	s_cselect_b32 s8, s74, s1
	s_add_i32 s6, 0, 0x14000
	v_add_u32_e32 v154, s14, v189
	v_add_u32_e32 v170, s6, v189
	ds_read_b128 v[130:133], v154
	ds_read_b128 v[134:137], v154 offset:1024
	ds_read_b128 v[150:153], v154 offset:2048
	ds_read_b128 v[154:157], v154 offset:3072
	ds_read_b128 v[158:161], v170
	ds_read_b128 v[162:165], v170 offset:1024
	ds_read_b128 v[166:169], v170 offset:2048
	ds_read_b128 v[170:173], v170 offset:3072
	v_lshl_add_u64 v[186:187], s[10:11], 0, v[146:147]
	s_add_i32 m0, s27, 0xc000
	ds_read_b128 v[174:177], v190
	ds_read_b128 v[178:181], v190 offset:1024
	ds_read_b128 v[182:185], v190 offset:2048
	ds_read_b128 v[192:195], v190 offset:3072
	ds_read_b128 v[196:199], v190 offset:4096
	ds_read_b128 v[200:203], v190 offset:5120
	ds_read_b128 v[204:207], v190 offset:6144
	ds_read_b128 v[212:215], v190 offset:7168
	global_load_lds_dwordx4 v[186:187], off
	v_lshl_add_u64 v[186:187], s[10:11], 0, v[148:149]
	s_add_i32 m0, s27, 0xe000
	s_nop 0
	global_load_lds_dwordx4 v[186:187], off
	s_waitcnt vmcnt(8)
	s_waitcnt lgkmcnt(0)
	s_barrier
	s_setprio 1
	v_mfma_f32_16x16x32_bf16 v[126:129], v[130:133], v[174:177], v[126:129]
	v_mfma_f32_16x16x32_bf16 v[122:125], v[150:153], v[174:177], v[122:125]
	v_mfma_f32_16x16x32_bf16 v[110:113], v[130:133], v[182:185], v[110:113]
	v_mfma_f32_16x16x32_bf16 v[106:109], v[150:153], v[182:185], v[106:109]
	v_mfma_f32_16x16x32_bf16 v[94:97], v[130:133], v[196:199], v[94:97]
	v_mfma_f32_16x16x32_bf16 v[90:93], v[150:153], v[196:199], v[90:93]
	v_mfma_f32_16x16x32_bf16 v[78:81], v[130:133], v[204:207], v[78:81]
	v_mfma_f32_16x16x32_bf16 v[74:77], v[150:153], v[204:207], v[74:77]
	v_mfma_f32_16x16x32_bf16 v[126:129], v[134:137], v[178:181], v[126:129]
	v_mfma_f32_16x16x32_bf16 v[122:125], v[154:157], v[178:181], v[122:125]
	v_mfma_f32_16x16x32_bf16 v[110:113], v[134:137], v[192:195], v[110:113]
	v_mfma_f32_16x16x32_bf16 v[106:109], v[154:157], v[192:195], v[106:109]
	v_mfma_f32_16x16x32_bf16 v[94:97], v[134:137], v[200:203], v[94:97]
	v_mfma_f32_16x16x32_bf16 v[90:93], v[154:157], v[200:203], v[90:93]
	v_mfma_f32_16x16x32_bf16 v[78:81], v[134:137], v[212:215], v[78:81]
	v_mfma_f32_16x16x32_bf16 v[74:77], v[154:157], v[212:215], v[74:77]
	v_mfma_f32_16x16x32_bf16 v[118:121], v[158:161], v[174:177], v[118:121]
	v_mfma_f32_16x16x32_bf16 v[114:117], v[166:169], v[174:177], v[114:117]
	v_mfma_f32_16x16x32_bf16 v[102:105], v[158:161], v[182:185], v[102:105]
	v_mfma_f32_16x16x32_bf16 v[98:101], v[166:169], v[182:185], v[98:101]
	v_mfma_f32_16x16x32_bf16 v[86:89], v[158:161], v[196:199], v[86:89]
	v_mfma_f32_16x16x32_bf16 v[82:85], v[166:169], v[196:199], v[82:85]
	v_mfma_f32_16x16x32_bf16 v[70:73], v[158:161], v[204:207], v[70:73]
	v_mfma_f32_16x16x32_bf16 v[66:69], v[166:169], v[204:207], v[66:69]
	v_mfma_f32_16x16x32_bf16 v[118:121], v[162:165], v[178:181], v[118:121]
	v_mfma_f32_16x16x32_bf16 v[114:117], v[170:173], v[178:181], v[114:117]
	v_mfma_f32_16x16x32_bf16 v[102:105], v[162:165], v[192:195], v[102:105]
	v_mfma_f32_16x16x32_bf16 v[98:101], v[170:173], v[192:195], v[98:101]
	v_mfma_f32_16x16x32_bf16 v[86:89], v[162:165], v[200:203], v[86:89]
	v_mfma_f32_16x16x32_bf16 v[82:85], v[170:173], v[200:203], v[82:85]
	v_mfma_f32_16x16x32_bf16 v[70:73], v[162:165], v[212:215], v[70:73]
	v_mfma_f32_16x16x32_bf16 v[66:69], v[170:173], v[212:215], v[66:69]
	s_setprio 0
	s_barrier
	s_add_i32 s14, s14, s26
	v_lshl_add_u64 v[186:187], s[8:9], 0, v[144:145]
	s_mov_b32 m0, s14
	ds_read_b128 v[174:177], v190 offset:16384
	ds_read_b128 v[178:181], v190 offset:17408
	ds_read_b128 v[182:185], v190 offset:18432
	ds_read_b128 v[192:195], v190 offset:19456
	ds_read_b128 v[196:199], v190 offset:20480
	ds_read_b128 v[200:203], v190 offset:21504
	ds_read_b128 v[204:207], v190 offset:22528
	ds_read_b128 v[212:215], v190 offset:23552
	global_load_lds_dwordx4 v[186:187], off
	s_add_i32 m0, s14, 0x2000
	v_lshl_add_u64 v[208:209], s[8:9], 0, v[140:141]
	s_add_u32 s8, s8, s56
	s_addc_u32 s9, s9, s57
	s_add_i32 s6, s6, s26
	global_load_lds_dwordx4 v[208:209], off
	v_lshl_add_u64 v[210:211], s[8:9], 0, v[144:145]
	s_mov_b32 m0, s6
	v_lshl_add_u64 v[216:217], s[8:9], 0, v[140:141]
	global_load_lds_dwordx4 v[210:211], off
	s_add_i32 m0, s6, 0x2000
	v_lshl_add_u64 v[218:219], s[12:13], 0, v[142:143]
	global_load_lds_dwordx4 v[216:217], off
	s_mov_b32 m0, s27
	v_lshl_add_u64 v[220:221], s[12:13], 0, v[138:139]
	global_load_lds_dwordx4 v[218:219], off
	s_mov_b32 m0, s38
	s_nop 0
	global_load_lds_dwordx4 v[220:221], off
	s_waitcnt vmcnt(8)
	s_waitcnt lgkmcnt(0)
	s_barrier
	s_setprio 1
	v_mfma_f32_16x16x32_bf16 v[62:65], v[130:133], v[174:177], v[62:65]
	v_mfma_f32_16x16x32_bf16 v[58:61], v[150:153], v[174:177], v[58:61]
	v_mfma_f32_16x16x32_bf16 v[46:49], v[130:133], v[182:185], v[46:49]
	v_mfma_f32_16x16x32_bf16 v[42:45], v[150:153], v[182:185], v[42:45]
	v_mfma_f32_16x16x32_bf16 v[30:33], v[130:133], v[196:199], v[30:33]
	v_mfma_f32_16x16x32_bf16 v[26:29], v[150:153], v[196:199], v[26:29]
	v_mfma_f32_16x16x32_bf16 v[14:17], v[130:133], v[204:207], v[14:17]
	v_mfma_f32_16x16x32_bf16 v[10:13], v[150:153], v[204:207], v[10:13]
	v_mfma_f32_16x16x32_bf16 v[62:65], v[134:137], v[178:181], v[62:65]
	v_mfma_f32_16x16x32_bf16 v[58:61], v[154:157], v[178:181], v[58:61]
	v_mfma_f32_16x16x32_bf16 v[46:49], v[134:137], v[192:195], v[46:49]
	v_mfma_f32_16x16x32_bf16 v[42:45], v[154:157], v[192:195], v[42:45]
	v_mfma_f32_16x16x32_bf16 v[30:33], v[134:137], v[200:203], v[30:33]
	v_mfma_f32_16x16x32_bf16 v[26:29], v[154:157], v[200:203], v[26:29]
	v_mfma_f32_16x16x32_bf16 v[14:17], v[134:137], v[212:215], v[14:17]
	v_mfma_f32_16x16x32_bf16 v[10:13], v[154:157], v[212:215], v[10:13]
	v_mfma_f32_16x16x32_bf16 v[54:57], v[158:161], v[174:177], v[54:57]
	v_mfma_f32_16x16x32_bf16 v[50:53], v[166:169], v[174:177], v[50:53]
	v_mfma_f32_16x16x32_bf16 v[38:41], v[158:161], v[182:185], v[38:41]
	v_mfma_f32_16x16x32_bf16 v[34:37], v[166:169], v[182:185], v[34:37]
	v_mfma_f32_16x16x32_bf16 v[22:25], v[158:161], v[196:199], v[22:25]
	v_mfma_f32_16x16x32_bf16 v[18:21], v[166:169], v[196:199], v[18:21]
	v_mfma_f32_16x16x32_bf16 v[6:9], v[158:161], v[204:207], v[6:9]
	v_mfma_f32_16x16x32_bf16 v[2:5], v[166:169], v[204:207], v[2:5]
	v_mfma_f32_16x16x32_bf16 v[54:57], v[162:165], v[178:181], v[54:57]
	v_mfma_f32_16x16x32_bf16 v[50:53], v[170:173], v[178:181], v[50:53]
	v_mfma_f32_16x16x32_bf16 v[38:41], v[162:165], v[192:195], v[38:41]
	v_mfma_f32_16x16x32_bf16 v[34:37], v[170:173], v[192:195], v[34:37]
	v_mfma_f32_16x16x32_bf16 v[22:25], v[162:165], v[200:203], v[22:25]
	v_mfma_f32_16x16x32_bf16 v[18:21], v[170:173], v[200:203], v[18:21]
	v_mfma_f32_16x16x32_bf16 v[6:9], v[162:165], v[212:215], v[6:9]
	v_mfma_f32_16x16x32_bf16 v[2:5], v[170:173], v[212:215], v[2:5]
	s_setprio 0
	s_barrier
	s_add_i32 s6, 0, 0x18000
	s_add_i32 s14, 0, 0x1c000
	v_add_u32_e32 v154, s6, v189
	v_add_u32_e32 v170, s14, v189
	ds_read_b128 v[130:133], v154
	ds_read_b128 v[134:137], v154 offset:1024
	ds_read_b128 v[150:153], v154 offset:2048
	ds_read_b128 v[154:157], v154 offset:3072
	ds_read_b128 v[158:161], v170
	ds_read_b128 v[162:165], v170 offset:1024
	ds_read_b128 v[166:169], v170 offset:2048
	ds_read_b128 v[170:173], v170 offset:3072
	s_add_u32 s8, s12, s56
	s_addc_u32 s9, s13, s57
	s_mov_b32 m0, s39
	v_lshl_add_u64 v[222:223], s[8:9], 0, v[142:143]
	ds_read_b128 v[174:177], v190 offset:32768
	ds_read_b128 v[178:181], v190 offset:33792
	ds_read_b128 v[182:185], v190 offset:34816
	ds_read_b128 v[192:195], v190 offset:35840
	ds_read_b128 v[196:199], v190 offset:36864
	ds_read_b128 v[200:203], v190 offset:37888
	ds_read_b128 v[204:207], v190 offset:38912
	ds_read_b128 v[212:215], v190 offset:39936
	global_load_lds_dwordx4 v[222:223], off
	v_lshl_add_u64 v[222:223], s[8:9], 0, v[138:139]
	s_mov_b32 m0, s50
	s_nop 0
	global_load_lds_dwordx4 v[222:223], off
	s_waitcnt vmcnt(8)
	s_waitcnt lgkmcnt(0)
	s_barrier
	s_setprio 1
	v_mfma_f32_16x16x32_bf16 v[126:129], v[130:133], v[174:177], v[126:129]
	v_mfma_f32_16x16x32_bf16 v[122:125], v[150:153], v[174:177], v[122:125]
	v_mfma_f32_16x16x32_bf16 v[110:113], v[130:133], v[182:185], v[110:113]
	v_mfma_f32_16x16x32_bf16 v[106:109], v[150:153], v[182:185], v[106:109]
	v_mfma_f32_16x16x32_bf16 v[94:97], v[130:133], v[196:199], v[94:97]
	v_mfma_f32_16x16x32_bf16 v[90:93], v[150:153], v[196:199], v[90:93]
	v_mfma_f32_16x16x32_bf16 v[78:81], v[130:133], v[204:207], v[78:81]
	v_mfma_f32_16x16x32_bf16 v[74:77], v[150:153], v[204:207], v[74:77]
	v_mfma_f32_16x16x32_bf16 v[126:129], v[134:137], v[178:181], v[126:129]
	v_mfma_f32_16x16x32_bf16 v[122:125], v[154:157], v[178:181], v[122:125]
	v_mfma_f32_16x16x32_bf16 v[110:113], v[134:137], v[192:195], v[110:113]
	v_mfma_f32_16x16x32_bf16 v[106:109], v[154:157], v[192:195], v[106:109]
	v_mfma_f32_16x16x32_bf16 v[94:97], v[134:137], v[200:203], v[94:97]
	v_mfma_f32_16x16x32_bf16 v[90:93], v[154:157], v[200:203], v[90:93]
	v_mfma_f32_16x16x32_bf16 v[78:81], v[134:137], v[212:215], v[78:81]
	v_mfma_f32_16x16x32_bf16 v[74:77], v[154:157], v[212:215], v[74:77]
	v_mfma_f32_16x16x32_bf16 v[118:121], v[158:161], v[174:177], v[118:121]
	v_mfma_f32_16x16x32_bf16 v[114:117], v[166:169], v[174:177], v[114:117]
	v_mfma_f32_16x16x32_bf16 v[102:105], v[158:161], v[182:185], v[102:105]
	v_mfma_f32_16x16x32_bf16 v[98:101], v[166:169], v[182:185], v[98:101]
	v_mfma_f32_16x16x32_bf16 v[86:89], v[158:161], v[196:199], v[86:89]
	v_mfma_f32_16x16x32_bf16 v[82:85], v[166:169], v[196:199], v[82:85]
	v_mfma_f32_16x16x32_bf16 v[70:73], v[158:161], v[204:207], v[70:73]
	v_mfma_f32_16x16x32_bf16 v[66:69], v[166:169], v[204:207], v[66:69]
	v_mfma_f32_16x16x32_bf16 v[118:121], v[162:165], v[178:181], v[118:121]
	v_mfma_f32_16x16x32_bf16 v[114:117], v[170:173], v[178:181], v[114:117]
	v_mfma_f32_16x16x32_bf16 v[102:105], v[162:165], v[192:195], v[102:105]
	v_mfma_f32_16x16x32_bf16 v[98:101], v[170:173], v[192:195], v[98:101]
	v_mfma_f32_16x16x32_bf16 v[86:89], v[162:165], v[200:203], v[86:89]
	v_mfma_f32_16x16x32_bf16 v[82:85], v[170:173], v[200:203], v[82:85]
	v_mfma_f32_16x16x32_bf16 v[70:73], v[162:165], v[212:215], v[70:73]
	v_mfma_f32_16x16x32_bf16 v[66:69], v[170:173], v[212:215], v[66:69]
	s_setprio 0
	s_barrier
	s_add_i32 s6, s6, s26
	v_lshl_add_u64 v[186:187], v[186:187], 0, s[28:29]
	s_mov_b32 m0, s6
	ds_read_b128 v[174:177], v190 offset:49152
	ds_read_b128 v[178:181], v190 offset:50176
	ds_read_b128 v[182:185], v190 offset:51200
	ds_read_b128 v[192:195], v190 offset:52224
	ds_read_b128 v[196:199], v190 offset:53248
	ds_read_b128 v[200:203], v190 offset:54272
	ds_read_b128 v[204:207], v190 offset:55296
	ds_read_b128 v[212:215], v190 offset:56320
	global_load_lds_dwordx4 v[186:187], off
	v_lshl_add_u64 v[186:187], v[208:209], 0, s[28:29]
	s_add_i32 m0, s6, 0x2000
	s_add_i32 s6, s14, s26
	global_load_lds_dwordx4 v[186:187], off
	v_lshl_add_u64 v[186:187], v[210:211], 0, s[28:29]
	s_mov_b32 m0, s6
	s_nop 0
	global_load_lds_dwordx4 v[186:187], off
	v_lshl_add_u64 v[186:187], v[216:217], 0, s[28:29]
	s_add_i32 m0, s6, 0x2000
	s_nop 0
	global_load_lds_dwordx4 v[186:187], off
	v_lshl_add_u64 v[186:187], v[218:219], 0, s[28:29]
	s_mov_b32 m0, s51
	s_nop 0
	global_load_lds_dwordx4 v[186:187], off
	v_lshl_add_u64 v[186:187], v[220:221], 0, s[28:29]
	s_mov_b32 m0, s80
	s_nop 0
	global_load_lds_dwordx4 v[186:187], off
	s_waitcnt vmcnt(8)
	s_waitcnt lgkmcnt(0)
	s_barrier
	s_setprio 1
	v_mfma_f32_16x16x32_bf16 v[62:65], v[130:133], v[174:177], v[62:65]
	v_mfma_f32_16x16x32_bf16 v[58:61], v[150:153], v[174:177], v[58:61]
	v_mfma_f32_16x16x32_bf16 v[46:49], v[130:133], v[182:185], v[46:49]
	v_mfma_f32_16x16x32_bf16 v[42:45], v[150:153], v[182:185], v[42:45]
	v_mfma_f32_16x16x32_bf16 v[30:33], v[130:133], v[196:199], v[30:33]
	v_mfma_f32_16x16x32_bf16 v[26:29], v[150:153], v[196:199], v[26:29]
	v_mfma_f32_16x16x32_bf16 v[14:17], v[130:133], v[204:207], v[14:17]
	v_mfma_f32_16x16x32_bf16 v[10:13], v[150:153], v[204:207], v[10:13]
	v_mfma_f32_16x16x32_bf16 v[62:65], v[134:137], v[178:181], v[62:65]
	v_mfma_f32_16x16x32_bf16 v[58:61], v[154:157], v[178:181], v[58:61]
	v_mfma_f32_16x16x32_bf16 v[46:49], v[134:137], v[192:195], v[46:49]
	v_mfma_f32_16x16x32_bf16 v[42:45], v[154:157], v[192:195], v[42:45]
	v_mfma_f32_16x16x32_bf16 v[30:33], v[134:137], v[200:203], v[30:33]
	v_mfma_f32_16x16x32_bf16 v[26:29], v[154:157], v[200:203], v[26:29]
	v_mfma_f32_16x16x32_bf16 v[14:17], v[134:137], v[212:215], v[14:17]
	v_mfma_f32_16x16x32_bf16 v[10:13], v[154:157], v[212:215], v[10:13]
	v_mfma_f32_16x16x32_bf16 v[54:57], v[158:161], v[174:177], v[54:57]
	v_mfma_f32_16x16x32_bf16 v[50:53], v[166:169], v[174:177], v[50:53]
	v_mfma_f32_16x16x32_bf16 v[38:41], v[158:161], v[182:185], v[38:41]
	v_mfma_f32_16x16x32_bf16 v[34:37], v[166:169], v[182:185], v[34:37]
	v_mfma_f32_16x16x32_bf16 v[22:25], v[158:161], v[196:199], v[22:25]
	v_mfma_f32_16x16x32_bf16 v[18:21], v[166:169], v[196:199], v[18:21]
	v_mfma_f32_16x16x32_bf16 v[6:9], v[158:161], v[204:207], v[6:9]
	v_mfma_f32_16x16x32_bf16 v[2:5], v[166:169], v[204:207], v[2:5]
	v_mfma_f32_16x16x32_bf16 v[54:57], v[162:165], v[178:181], v[54:57]
	v_mfma_f32_16x16x32_bf16 v[50:53], v[170:173], v[178:181], v[50:53]
	v_mfma_f32_16x16x32_bf16 v[38:41], v[162:165], v[192:195], v[38:41]
	v_mfma_f32_16x16x32_bf16 v[34:37], v[170:173], v[192:195], v[34:37]
	v_mfma_f32_16x16x32_bf16 v[22:25], v[162:165], v[200:203], v[22:25]
	v_mfma_f32_16x16x32_bf16 v[18:21], v[170:173], v[200:203], v[18:21]
	v_mfma_f32_16x16x32_bf16 v[6:9], v[162:165], v[212:215], v[6:9]
	v_mfma_f32_16x16x32_bf16 v[2:5], v[170:173], v[212:215], v[2:5]
	s_setprio 0
	s_barrier
	s_add_u32 s1, s1, 0x100
	s_addc_u32 s5, s5, 0
	s_add_u32 s10, s10, 0x100
	s_addc_u32 s11, s11, 0
	s_cmp_ge_i32 s7, s83
	s_mov_b32 s6, s7
	s_cbranch_scc0 .LBB0_1182
